# de-phase 4 sub-groups per half (1.5us steps of s_sleep) in P1/P6 tile loops + fold fmaxf canonicalisation v_max pairs in attention softmax
# speedup vs baseline: 1.0187x; 1.0030x over previous
.LBB0_402:
	v_writelane_b32 v252, s14, 54
	v_writelane_b32 v252, s86, 56
	s_nop 1
	v_writelane_b32 v252, s87, 57
	v_writelane_b32 v252, s84, 58
	s_nop 1
	v_writelane_b32 v252, s85, 59
	v_writelane_b32 v252, s68, 60
	s_nop 1
	v_writelane_b32 v253, s72, 0
	v_writelane_b32 v252, s69, 61
	v_writelane_b32 v253, s73, 1
	v_writelane_b32 v252, s70, 62
	v_writelane_b32 v253, s74, 2
	v_writelane_b32 v252, s71, 63
	v_writelane_b32 v253, s75, 3
	s_or_b64 exec, exec, s[0:1]
	s_add_u32 s18, s76, 0xa000000
	s_addc_u32 s19, s77, 0
	s_cmpk_lt_i32 s26, 0xe80
	s_cselect_b64 s[0:1], -1, 0
	s_add_u32 s15, s76, 0x7800000
	s_addc_u32 s88, s77, 0
	v_writelane_b32 v253, s0, 4
	s_add_u32 s89, s76, 0x8000000
	s_addc_u32 s90, s77, 0
	v_writelane_b32 v253, s1, 5
	s_bfe_u32 s0, s82, 0x20006
	s_lshr_b32 s1, s82, 8
	s_cmp_eq_u32 s1, 1
	s_cselect_b64 s[10:11], -1, 0
	s_lshl_b32 s2, s1, 6
	s_lshl_b32 s17, s1, 13
	s_or_b32 s1, s2, 16
	v_writelane_b32 v253, s1, 6
	s_lshl_b32 s65, s1, 7
	s_or_b32 s1, s2, 32
	v_writelane_b32 v253, s1, 7
	s_lshl_b32 s1, s1, 7
	v_writelane_b32 v253, s1, 8
	v_writelane_b32 v253, s2, 10
	s_or_b32 s1, s2, 48
	v_writelane_b32 v253, s1, 11
	s_lshl_b32 s1, s1, 7
	s_lshl_b32 s64, s0, 12
	v_writelane_b32 v253, s1, 12
	s_mov_b32 s2, s82
	v_writelane_b32 v253, s2, 14
	s_cmpk_lt_u32 s82, 0x100
	v_cndmask_b32_e64 v192, 0, 1, s[10:11]
	v_writelane_b32 v253, s3, 15
	s_cselect_b64 s[2:3], -1, 0
	v_writelane_b32 v253, s2, 16
	s_lshl_b32 s0, s0, 5
	s_barrier
	v_writelane_b32 v253, s3, 17
	v_writelane_b32 v253, s0, 18
	s_add_u32 s0, s76, 0x12000000
	s_addc_u32 s1, s77, 0
	v_writelane_b32 v253, s0, 19
	s_cmpk_gt_i32 s26, 0xe7f
	s_nop 0
	v_writelane_b32 v253, s1, 20
	s_mov_b32 s0, s26
	v_writelane_b32 v253, s0, 21
	s_mov_b32 s26, s80
	s_nop 0
	v_writelane_b32 v253, s1, 22
	v_writelane_b32 v253, s27, 23
	s_cbranch_scc1 .LBB0_549
	s_add_u32 s91, s76, 0x5800000
	v_readlane_b32 s0, v253, 8
	s_addc_u32 s92, s77, 0
	s_add_i32 s96, s0, 0
	v_readlane_b32 s0, v253, 12
	s_add_i32 s25, s64, 0
	s_add_i32 s97, s0, 0
	v_readlane_b32 s0, v253, 21
	s_mov_b32 s23, 0
	s_add_i32 s93, s25, 0x10000
	s_add_i32 s94, s17, 0
	s_add_i32 s95, s65, 0
	s_add_i32 s12, s25, 0x14000
	s_add_i32 s13, s25, 0x18000
	s_add_i32 s25, s25, 0x1c000
	s_add_i32 s33, s0, 0xfffff200
	s_lshl_b32 s84, s0, 8
	s_lshl_b32 s85, s80, 8
	s_mov_b64 s[44:45], 0x80
	s_mov_b64 s[46:47], 0x5800080
	s_mov_b64 s[48:49], 0x4900100
	s_mov_b64 s[50:51], 0x5800100
	s_mov_b64 s[52:53], 0x4980100
	s_mov_b64 s[54:55], 0x4900180
	s_mov_b64 s[56:57], 0x5800180
	s_mov_b64 s[58:59], 0x4980180
	s_mov_b64 s[60:61], 0x100
	s_mov_b64 s[62:63], 0xf80
	v_mov_b32_e32 v129, 0
	s_mov_b64 s[66:67], 0xa000080
	s_mov_b64 s[68:69], 0xa000100
	s_mov_b64 s[70:71], 0x80100
	s_mov_b64 s[72:73], 0x180
	s_mov_b64 s[74:75], 0xa000180
	s_mov_b64 s[8:9], 0x80180
	s_movk_i32 s86, 0x3800
	v_mov_b32_e32 v146, 1
	v_mov_b32_e32 v147, 0x1000
	v_mov_b32_e32 v148, 0x2000
	v_mov_b32_e32 v149, 0x3000
	v_readlane_b32 s87, v252, 54
	s_mov_b32 s40, s0
	v_readlane_b32 s1, v253, 22
	s_cmpk_lt_u32 s40, 0x80
	s_cbranch_scc1 .Lp1_lo
	s_mov_b32 s98, 62
	s_bfe_u32 s99, s40, 0x20003
	s_mul_i32 s99, s99, 6
	s_add_u32 s98, s98, s99
	s_branch .Lp1_go
.Lp1_lo:
	s_mov_b32 s98, 0
	s_bfe_u32 s99, s40, 0x20003
	s_mul_i32 s99, s99, 6
	s_add_u32 s98, s98, s99
.Lp1_go:
	s_cmp_eq_u32 s98, 0
	s_cbranch_scc1 .Lp1_done
.Lp1_loop:
	s_sleep 16
	s_sub_u32 s98, s98, 1
	s_cmp_lg_u32 s98, 0
	s_cbranch_scc1 .Lp1_loop

.LBB0_583:
	s_add_i32 s13, s13, 0
	v_add_u32_e32 v0, s13, v196
	s_setprio 1
	v_add_u32_e32 v201, v0, v197
	ds_read_b128 v[2:5], v201
	s_waitcnt lgkmcnt(0)
	v_mfma_f32_32x32x16_bf16 v[80:95], v[2:5], v[112:115], 0
	ds_read_b128 v[2:5], v201 offset:8704
	s_waitcnt lgkmcnt(0)
	v_mfma_f32_32x32x16_bf16 v[96:111], v[2:5], v[112:115], 0
	ds_read_b128 v[2:5], v201 offset:32
	s_waitcnt lgkmcnt(0)
	v_mfma_f32_32x32x16_bf16 v[80:95], v[2:5], v[116:119], v[80:95]
	ds_read_b128 v[2:5], v201 offset:8736
	s_waitcnt lgkmcnt(0)
	v_mfma_f32_32x32x16_bf16 v[96:111], v[2:5], v[116:119], v[96:111]
	ds_read_b128 v[2:5], v201 offset:64
	s_waitcnt lgkmcnt(0)
	v_mfma_f32_32x32x16_bf16 v[80:95], v[2:5], v[120:123], v[80:95]
	ds_read_b128 v[2:5], v201 offset:8768
	s_waitcnt lgkmcnt(0)
	v_mfma_f32_32x32x16_bf16 v[96:111], v[2:5], v[120:123], v[96:111]
	ds_read_b128 v[2:5], v201 offset:96
	s_waitcnt lgkmcnt(0)
	v_mfma_f32_32x32x16_bf16 v[80:95], v[2:5], v[124:127], v[80:95]
	ds_read_b128 v[2:5], v201 offset:8800
	s_waitcnt lgkmcnt(0)
	v_mfma_f32_32x32x16_bf16 v[96:111], v[2:5], v[124:127], v[96:111]
	ds_read_b128 v[2:5], v201 offset:128
	s_waitcnt lgkmcnt(0)
	v_mfma_f32_32x32x16_bf16 v[80:95], v[2:5], v[156:159], v[80:95]
	ds_read_b128 v[2:5], v201 offset:8832
	s_waitcnt lgkmcnt(0)
	v_mfma_f32_32x32x16_bf16 v[96:111], v[2:5], v[156:159], v[96:111]
	ds_read_b128 v[2:5], v201 offset:160
	s_waitcnt lgkmcnt(0)
	v_mfma_f32_32x32x16_bf16 v[80:95], v[2:5], v[160:163], v[80:95]
	ds_read_b128 v[2:5], v201 offset:8864
	s_waitcnt lgkmcnt(0)
	v_mfma_f32_32x32x16_bf16 v[96:111], v[2:5], v[160:163], v[96:111]
	ds_read_b128 v[2:5], v201 offset:192
	s_waitcnt lgkmcnt(0)
	v_mfma_f32_32x32x16_bf16 v[80:95], v[2:5], v[164:167], v[80:95]
	ds_read_b128 v[2:5], v201 offset:8896
	s_waitcnt lgkmcnt(0)
	v_mfma_f32_32x32x16_bf16 v[96:111], v[2:5], v[164:167], v[96:111]
	ds_read_b128 v[2:5], v201 offset:224
	s_waitcnt lgkmcnt(0)
	v_mfma_f32_32x32x16_bf16 v[80:95], v[2:5], v[172:175], v[80:95]
	ds_read_b128 v[2:5], v201 offset:8928
	s_waitcnt lgkmcnt(0)
	v_mfma_f32_32x32x16_bf16 v[96:111], v[2:5], v[172:175], v[96:111]
	s_setprio 0
	s_nop 10
	v_max_f32_e32 v0, v80, v96
	v_max_f32_e32 v2, v81, v97
	v_max3_f32 v0, v200, v0, v2
	v_max_f32_e32 v2, v82, v98
	v_max_f32_e32 v3, v83, v99
	v_max3_f32 v0, v0, v2, v3
	v_max_f32_e32 v2, v84, v100
	v_max_f32_e32 v3, v85, v101
	v_max3_f32 v0, v0, v2, v3
	v_max_f32_e32 v2, v86, v102
	v_max_f32_e32 v3, v87, v103
	v_max3_f32 v0, v0, v2, v3
	v_max_f32_e32 v2, v88, v104
	v_max_f32_e32 v3, v89, v105
	v_max3_f32 v0, v0, v2, v3
	v_max_f32_e32 v2, v90, v106
	v_max_f32_e32 v3, v91, v107
	v_max3_f32 v0, v0, v2, v3
	v_max_f32_e32 v2, v92, v108
	v_max_f32_e32 v3, v93, v109
	v_max3_f32 v0, v0, v2, v3
	v_max_f32_e32 v2, v94, v110
	v_max_f32_e32 v3, v111, v111
	v_max_f32_e32 v4, v95, v95
	v_max_f32_e32 v3, v4, v3
	v_max3_f32 v0, v0, v2, v3
	v_mov_b32_e32 v2, v0
	s_nop 1
	v_permlane32_swap_b32_e32 v0, v2
	v_max_f32_e32 v2, v2, v2
	v_max_f32_e32 v0, v0, v0
	v_max_f32_e32 v202, v0, v2
	v_add_f32_e32 v204, 0x41000000, v200
	v_cmp_gt_f32_e32 vcc, v202, v204
	s_cbranch_vccz .LBB0_585
	v_sub_f32_e32 v0, v200, v202
	v_exp_f32_e32 v0, v0
	v_add_f32_e32 v204, 0x41000000, v202
	v_mul_f32_e32 v203, v203, v0
	v_pk_mul_f32 v[78:79], v[78:79], v[0:1] op_sel_hi:[1,0]
	v_pk_mul_f32 v[76:77], v[76:77], v[0:1] op_sel_hi:[1,0]
	v_pk_mul_f32 v[74:75], v[74:75], v[0:1] op_sel_hi:[1,0]
	v_pk_mul_f32 v[72:73], v[72:73], v[0:1] op_sel_hi:[1,0]
	v_pk_mul_f32 v[70:71], v[70:71], v[0:1] op_sel_hi:[1,0]
	v_pk_mul_f32 v[68:69], v[68:69], v[0:1] op_sel_hi:[1,0]
	v_pk_mul_f32 v[66:67], v[66:67], v[0:1] op_sel_hi:[1,0]
	v_pk_mul_f32 v[64:65], v[64:65], v[0:1] op_sel_hi:[1,0]
	v_pk_mul_f32 v[62:63], v[62:63], v[0:1] op_sel_hi:[1,0]
	v_pk_mul_f32 v[60:61], v[60:61], v[0:1] op_sel_hi:[1,0]
	v_pk_mul_f32 v[58:59], v[58:59], v[0:1] op_sel_hi:[1,0]
	v_pk_mul_f32 v[56:57], v[56:57], v[0:1] op_sel_hi:[1,0]
	v_pk_mul_f32 v[54:55], v[54:55], v[0:1] op_sel_hi:[1,0]
	v_pk_mul_f32 v[52:53], v[52:53], v[0:1] op_sel_hi:[1,0]
	v_pk_mul_f32 v[50:51], v[50:51], v[0:1] op_sel_hi:[1,0]
	v_pk_mul_f32 v[48:49], v[48:49], v[0:1] op_sel_hi:[1,0]
	v_pk_mul_f32 v[46:47], v[46:47], v[0:1] op_sel_hi:[1,0]
	v_pk_mul_f32 v[44:45], v[44:45], v[0:1] op_sel_hi:[1,0]
	v_pk_mul_f32 v[42:43], v[42:43], v[0:1] op_sel_hi:[1,0]
	v_pk_mul_f32 v[40:41], v[40:41], v[0:1] op_sel_hi:[1,0]
	v_pk_mul_f32 v[38:39], v[38:39], v[0:1] op_sel_hi:[1,0]
	v_pk_mul_f32 v[36:37], v[36:37], v[0:1] op_sel_hi:[1,0]
	v_pk_mul_f32 v[34:35], v[34:35], v[0:1] op_sel_hi:[1,0]
	v_pk_mul_f32 v[32:33], v[32:33], v[0:1] op_sel_hi:[1,0]
	v_pk_mul_f32 v[30:31], v[30:31], v[0:1] op_sel_hi:[1,0]
	v_pk_mul_f32 v[28:29], v[28:29], v[0:1] op_sel_hi:[1,0]
	v_pk_mul_f32 v[26:27], v[26:27], v[0:1] op_sel_hi:[1,0]
	v_pk_mul_f32 v[24:25], v[24:25], v[0:1] op_sel_hi:[1,0]
	v_pk_mul_f32 v[22:23], v[22:23], v[0:1] op_sel_hi:[1,0]
	v_pk_mul_f32 v[20:21], v[20:21], v[0:1] op_sel_hi:[1,0]
	v_pk_mul_f32 v[18:19], v[18:19], v[0:1] op_sel_hi:[1,0]
	v_pk_mul_f32 v[16:17], v[16:17], v[0:1] op_sel_hi:[1,0]
	s_branch .LBB0_586

.LBB0_586:
	v_sub_f32_e32 v0, v80, v202
	v_exp_f32_e32 v200, v0
	v_sub_f32_e32 v0, v96, v202
	v_exp_f32_e32 v96, v0
	v_sub_f32_e32 v0, v81, v202
	v_sub_f32_e32 v2, v97, v202
	v_exp_f32_e32 v0, v0
	v_exp_f32_e32 v2, v2
	v_add_f32_e32 v3, v96, v200
	v_add_u32_e32 v194, s13, v197
	v_pk_add_f32 v[4:5], v[2:3], v[0:1]
	s_nop 0
	v_pk_add_f32 v[206:207], v[4:5], v[4:5] op_sel_hi:[0,1]
	v_sub_f32_e32 v4, v98, v202
	v_sub_f32_e32 v3, v82, v202
	v_exp_f32_e32 v97, v4
	v_sub_f32_e32 v4, v83, v202
	v_exp_f32_e32 v3, v3
	v_exp_f32_e32 v206, v4
	v_sub_f32_e32 v4, v99, v202
	v_exp_f32_e32 v4, v4
	v_add_f32_e32 v5, v97, v3
	v_cvt_pk_bf16_f32 v2, v96, v2
	v_pk_add_f32 v[6:7], v[4:5], v[206:207]
	s_nop 0
	v_pk_add_f32 v[98:99], v[6:7], v[6:7] op_sel_hi:[0,1]
	v_sub_f32_e32 v6, v100, v202
	v_sub_f32_e32 v5, v84, v202
	v_exp_f32_e32 v205, v6
	v_sub_f32_e32 v6, v85, v202
	v_exp_f32_e32 v5, v5
	v_exp_f32_e32 v98, v6
	v_sub_f32_e32 v6, v101, v202
	v_exp_f32_e32 v6, v6
	v_add_f32_e32 v7, v205, v5
	v_pk_add_f32 v[8:9], v[6:7], v[98:99]
	v_sub_f32_e32 v7, v86, v202
	v_exp_f32_e32 v99, v7
	v_sub_f32_e32 v7, v102, v202
	v_pk_add_f32 v[100:101], v[8:9], v[8:9] op_sel_hi:[0,1]
	v_exp_f32_e32 v207, v7
	v_sub_f32_e32 v7, v87, v202
	v_exp_f32_e32 v100, v7
	v_sub_f32_e32 v7, v103, v202
	v_exp_f32_e32 v10, v7
	v_add_f32_e32 v11, v207, v99
	v_sub_f32_e32 v7, v88, v202
	v_pk_add_f32 v[8:9], v[10:11], v[100:101]
	v_exp_f32_e32 v11, v7
	v_sub_f32_e32 v7, v104, v202
	v_pk_add_f32 v[82:83], v[8:9], v[8:9] op_sel_hi:[0,1]
	v_exp_f32_e32 v104, v7
	v_sub_f32_e32 v7, v89, v202
	v_exp_f32_e32 v82, v7
	v_sub_f32_e32 v7, v105, v202
	v_exp_f32_e32 v8, v7
	v_add_f32_e32 v9, v104, v11
	v_sub_f32_e32 v7, v90, v202
	v_cvt_pk_bf16_f32 v90, v5, v98
	v_pk_add_f32 v[12:13], v[8:9], v[82:83]
	v_exp_f32_e32 v9, v7
	v_sub_f32_e32 v7, v106, v202
	v_pk_add_f32 v[84:85], v[12:13], v[12:13] op_sel_hi:[0,1]
	v_exp_f32_e32 v105, v7
	v_sub_f32_e32 v7, v91, v202
	v_exp_f32_e32 v84, v7
	v_sub_f32_e32 v7, v107, v202
	v_exp_f32_e32 v12, v7
	v_add_f32_e32 v13, v105, v9
	v_sub_f32_e32 v7, v92, v202
	v_cvt_pk_bf16_f32 v91, v99, v100
	v_pk_add_f32 v[14:15], v[12:13], v[84:85]
	v_exp_f32_e32 v13, v7
	v_sub_f32_e32 v7, v108, v202
	v_pk_add_f32 v[86:87], v[14:15], v[14:15] op_sel_hi:[0,1]
	v_exp_f32_e32 v106, v7
	v_sub_f32_e32 v7, v93, v202
	v_exp_f32_e32 v86, v7
	v_sub_f32_e32 v7, v109, v202
	v_exp_f32_e32 v14, v7
	v_add_f32_e32 v15, v106, v13
	v_sub_f32_e32 v7, v94, v202
	v_cvt_pk_bf16_f32 v83, v9, v84
	v_pk_add_f32 v[80:81], v[14:15], v[86:87]
	v_exp_f32_e32 v15, v7
	v_sub_f32_e32 v7, v110, v202
	v_pk_add_f32 v[102:103], v[80:81], v[80:81] op_sel_hi:[0,1]
	v_exp_f32_e32 v107, v7
	v_sub_f32_e32 v7, v95, v202
	v_exp_f32_e32 v102, v7
	v_sub_f32_e32 v7, v111, v202
	v_exp_f32_e32 v80, v7
	v_add_f32_e32 v81, v107, v15
	v_cvt_pk_bf16_f32 v84, v13, v86
	v_cvt_pk_bf16_f32 v82, v11, v82
	v_pk_add_f32 v[88:89], v[80:81], v[102:103]
	v_cvt_pk_bf16_f32 v85, v15, v102
	v_pk_add_f32 v[88:89], v[88:89], v[88:89] op_sel:[0,1] op_sel_hi:[1,0]
	v_cvt_pk_bf16_f32 v5, v207, v10
	v_mov_b32_e32 v7, v88
	s_nop 1
	v_permlane32_swap_b32_e32 v88, v7
	v_add_f32_e32 v7, v88, v7
	v_cvt_pk_bf16_f32 v88, v200, v0
	v_add_u32_e32 v0, v194, v196
	ds_read_b128 v[92:95], v0 offset:34816
	ds_read_b128 v[98:101], v0 offset:34848
	v_cvt_pk_bf16_f32 v89, v3, v206
	v_cvt_pk_bf16_f32 v3, v97, v4
	v_cvt_pk_bf16_f32 v4, v205, v6
	s_waitcnt lgkmcnt(1)
	v_mfma_f32_32x32x16_bf16 v[64:79], v[92:95], v[88:91], v[64:79]
	ds_read_b128 v[92:95], v0 offset:43520
	v_add_f32_e32 v7, v203, v7
	s_waitcnt lgkmcnt(0)
	v_mfma_f32_32x32x16_bf16 v[48:63], v[92:95], v[88:91], v[48:63]
	ds_read_b128 v[92:95], v0 offset:52224
	s_waitcnt lgkmcnt(0)
	v_mfma_f32_32x32x16_bf16 v[32:47], v[92:95], v[88:91], v[32:47]
	ds_read_b128 v[92:95], v0 offset:60928
	s_waitcnt lgkmcnt(0)
	v_mfma_f32_32x32x16_bf16 v[16:31], v[92:95], v[88:91], v[16:31]
	ds_read_b128 v[86:89], v0 offset:43552
	s_waitcnt lgkmcnt(0)
	v_mfma_f32_32x32x16_bf16 v[48:63], v[86:89], v[82:85], v[48:63]
	ds_read_b128 v[86:89], v0 offset:52256
	s_waitcnt lgkmcnt(0)
	v_mfma_f32_32x32x16_bf16 v[32:47], v[86:89], v[82:85], v[32:47]
	ds_read_b128 v[86:89], v0 offset:60960
	v_mfma_f32_32x32x16_bf16 v[64:79], v[98:101], v[82:85], v[64:79]
	s_waitcnt lgkmcnt(0)
	v_mfma_f32_32x32x16_bf16 v[16:31], v[86:89], v[82:85], v[16:31]
	ds_read_b128 v[82:85], v0 offset:34880
	s_waitcnt lgkmcnt(0)
	v_mfma_f32_32x32x16_bf16 v[64:79], v[82:85], v[2:5], v[64:79]
	ds_read_b128 v[82:85], v0 offset:43584
	s_waitcnt lgkmcnt(0)
	v_mfma_f32_32x32x16_bf16 v[48:63], v[82:85], v[2:5], v[48:63]
	ds_read_b128 v[82:85], v0 offset:52288
	s_waitcnt lgkmcnt(0)
	v_mfma_f32_32x32x16_bf16 v[32:47], v[82:85], v[2:5], v[32:47]
	ds_read_b128 v[82:85], v0 offset:60992
	s_waitcnt lgkmcnt(0)
	v_mfma_f32_32x32x16_bf16 v[16:31], v[82:85], v[2:5], v[16:31]
	v_cvt_pk_bf16_f32 v2, v104, v8
	ds_read_b128 v[8:11], v0 offset:34912
	v_cvt_pk_bf16_f32 v3, v105, v12
	v_cvt_pk_bf16_f32 v4, v106, v14
	v_cvt_pk_bf16_f32 v5, v107, v80
	s_waitcnt lgkmcnt(0)
	s_nop 0
	v_mfma_f32_32x32x16_bf16 v[64:79], v[8:11], v[2:5], v[64:79]
	ds_read_b128 v[8:11], v0 offset:43616
	s_waitcnt lgkmcnt(0)
	v_mfma_f32_32x32x16_bf16 v[48:63], v[8:11], v[2:5], v[48:63]
	ds_read_b128 v[8:11], v0 offset:52320
	s_waitcnt lgkmcnt(0)
	v_mfma_f32_32x32x16_bf16 v[32:47], v[8:11], v[2:5], v[32:47]
	ds_read_b128 v[8:11], v0 offset:61024
	s_waitcnt lgkmcnt(0)
	v_mfma_f32_32x32x16_bf16 v[16:31], v[8:11], v[2:5], v[16:31]
	s_setprio 1
	ds_read_b128 v[2:5], v201 offset:17408
	ds_read_b128 v[8:11], v201 offset:17440
	s_waitcnt lgkmcnt(1)
	v_mfma_f32_32x32x16_bf16 v[80:95], v[2:5], v[112:115], 0
	ds_read_b128 v[2:5], v201 offset:26112
	ds_read_b128 v[12:15], v201 offset:26144
	s_waitcnt lgkmcnt(1)
	v_mfma_f32_32x32x16_bf16 v[96:111], v[2:5], v[112:115], 0
	v_mfma_f32_32x32x16_bf16 v[80:95], v[8:11], v[116:119], v[80:95]
	ds_read_b128 v[2:5], v201 offset:17472
	ds_read_b128 v[8:11], v201 offset:17504
	s_waitcnt lgkmcnt(2)
	v_mfma_f32_32x32x16_bf16 v[96:111], v[12:15], v[116:119], v[96:111]
	s_waitcnt lgkmcnt(1)
	v_mfma_f32_32x32x16_bf16 v[80:95], v[2:5], v[120:123], v[80:95]
	ds_read_b128 v[2:5], v201 offset:26176
	ds_read_b128 v[12:15], v201 offset:26208
	s_waitcnt lgkmcnt(1)
	v_mfma_f32_32x32x16_bf16 v[96:111], v[2:5], v[120:123], v[96:111]
	v_mfma_f32_32x32x16_bf16 v[80:95], v[8:11], v[124:127], v[80:95]
	ds_read_b128 v[2:5], v201 offset:17536
	ds_read_b128 v[8:11], v201 offset:17568
	s_waitcnt lgkmcnt(2)
	v_mfma_f32_32x32x16_bf16 v[96:111], v[12:15], v[124:127], v[96:111]
	s_waitcnt lgkmcnt(1)
	v_mfma_f32_32x32x16_bf16 v[80:95], v[2:5], v[156:159], v[80:95]
	ds_read_b128 v[2:5], v201 offset:26240
	ds_read_b128 v[12:15], v201 offset:26272
	s_waitcnt lgkmcnt(1)
	v_mfma_f32_32x32x16_bf16 v[96:111], v[2:5], v[156:159], v[96:111]
	v_mfma_f32_32x32x16_bf16 v[80:95], v[8:11], v[160:163], v[80:95]
	ds_read_b128 v[2:5], v201 offset:17600
	ds_read_b128 v[8:11], v201 offset:17632
	s_waitcnt lgkmcnt(2)
	v_mfma_f32_32x32x16_bf16 v[96:111], v[12:15], v[160:163], v[96:111]
	s_waitcnt lgkmcnt(1)
	v_mfma_f32_32x32x16_bf16 v[80:95], v[2:5], v[164:167], v[80:95]
	ds_read_b128 v[2:5], v201 offset:26304
	ds_read_b128 v[12:15], v201 offset:26336
	s_waitcnt lgkmcnt(1)
	v_mfma_f32_32x32x16_bf16 v[96:111], v[2:5], v[164:167], v[96:111]
	v_mfma_f32_32x32x16_bf16 v[80:95], v[8:11], v[172:175], v[80:95]
	s_waitcnt lgkmcnt(0)
	v_mfma_f32_32x32x16_bf16 v[96:111], v[12:15], v[172:175], v[96:111]
	s_setprio 0
	s_nop 10
	v_max_f32_e32 v2, v80, v96
	v_max_f32_e32 v3, v81, v97
	v_max3_f32 v2, v202, v2, v3
	v_max_f32_e32 v3, v82, v98
	v_max_f32_e32 v4, v83, v99
	v_max3_f32 v2, v2, v3, v4
	v_max_f32_e32 v3, v84, v100
	v_max_f32_e32 v4, v85, v101
	v_max3_f32 v2, v2, v3, v4
	v_max_f32_e32 v3, v86, v102
	v_max_f32_e32 v4, v87, v103
	v_max3_f32 v2, v2, v3, v4
	v_max_f32_e32 v3, v88, v104
	v_max_f32_e32 v4, v89, v105
	v_max3_f32 v2, v2, v3, v4
	v_max_f32_e32 v3, v90, v106
	v_max_f32_e32 v4, v91, v107
	v_max3_f32 v2, v2, v3, v4
	v_max_f32_e32 v3, v92, v108
	v_max_f32_e32 v4, v93, v109
	v_max3_f32 v2, v2, v3, v4
	v_max_f32_e32 v3, v94, v110
	v_max_f32_e32 v4, v95, v111
	v_max3_f32 v2, v2, v3, v4
	v_mov_b32_e32 v3, v2
	s_nop 1
	v_permlane32_swap_b32_e32 v2, v3
	v_max_f32_e32 v3, v3, v3
	v_max_f32_e32 v2, v2, v2
	v_max_f32_e32 v200, v2, v3
	v_cmp_gt_f32_e32 vcc, v200, v204
	s_cbranch_vccz .LBB0_588
	v_sub_f32_e32 v2, v202, v200
	v_exp_f32_e32 v2, v2
	s_nop 0
	v_mul_f32_e32 v7, v7, v2
	v_pk_mul_f32 v[78:79], v[78:79], v[2:3] op_sel_hi:[1,0]
	v_pk_mul_f32 v[76:77], v[76:77], v[2:3] op_sel_hi:[1,0]
	v_pk_mul_f32 v[74:75], v[74:75], v[2:3] op_sel_hi:[1,0]
	v_pk_mul_f32 v[72:73], v[72:73], v[2:3] op_sel_hi:[1,0]
	v_pk_mul_f32 v[70:71], v[70:71], v[2:3] op_sel_hi:[1,0]
	v_pk_mul_f32 v[68:69], v[68:69], v[2:3] op_sel_hi:[1,0]
	v_pk_mul_f32 v[66:67], v[66:67], v[2:3] op_sel_hi:[1,0]
	v_pk_mul_f32 v[64:65], v[64:65], v[2:3] op_sel_hi:[1,0]
	v_pk_mul_f32 v[62:63], v[62:63], v[2:3] op_sel_hi:[1,0]
	v_pk_mul_f32 v[60:61], v[60:61], v[2:3] op_sel_hi:[1,0]
	v_pk_mul_f32 v[58:59], v[58:59], v[2:3] op_sel_hi:[1,0]
	v_pk_mul_f32 v[56:57], v[56:57], v[2:3] op_sel_hi:[1,0]
	v_pk_mul_f32 v[54:55], v[54:55], v[2:3] op_sel_hi:[1,0]
	v_pk_mul_f32 v[52:53], v[52:53], v[2:3] op_sel_hi:[1,0]
	v_pk_mul_f32 v[50:51], v[50:51], v[2:3] op_sel_hi:[1,0]
	v_pk_mul_f32 v[48:49], v[48:49], v[2:3] op_sel_hi:[1,0]
	v_pk_mul_f32 v[46:47], v[46:47], v[2:3] op_sel_hi:[1,0]
	v_pk_mul_f32 v[44:45], v[44:45], v[2:3] op_sel_hi:[1,0]
	v_pk_mul_f32 v[42:43], v[42:43], v[2:3] op_sel_hi:[1,0]
	v_pk_mul_f32 v[40:41], v[40:41], v[2:3] op_sel_hi:[1,0]
	v_pk_mul_f32 v[38:39], v[38:39], v[2:3] op_sel_hi:[1,0]
	v_pk_mul_f32 v[36:37], v[36:37], v[2:3] op_sel_hi:[1,0]
	v_pk_mul_f32 v[34:35], v[34:35], v[2:3] op_sel_hi:[1,0]
	v_pk_mul_f32 v[32:33], v[32:33], v[2:3] op_sel_hi:[1,0]
	v_pk_mul_f32 v[30:31], v[30:31], v[2:3] op_sel_hi:[1,0]
	v_pk_mul_f32 v[28:29], v[28:29], v[2:3] op_sel_hi:[1,0]
	v_pk_mul_f32 v[26:27], v[26:27], v[2:3] op_sel_hi:[1,0]
	v_pk_mul_f32 v[24:25], v[24:25], v[2:3] op_sel_hi:[1,0]
	v_pk_mul_f32 v[22:23], v[22:23], v[2:3] op_sel_hi:[1,0]
	v_pk_mul_f32 v[20:21], v[20:21], v[2:3] op_sel_hi:[1,0]
	v_pk_mul_f32 v[18:19], v[18:19], v[2:3] op_sel_hi:[1,0]
	v_pk_mul_f32 v[16:17], v[16:17], v[2:3] op_sel_hi:[1,0]
	s_branch .LBB0_589

.LBB0_627:
	s_add_u32 s0, s76, 0x2e000000
	s_addc_u32 s1, s77, 0
	v_writelane_b32 v253, s0, 40
	s_add_u32 s2, s76, 0x22000000
	s_addc_u32 s3, s77, 0
	v_writelane_b32 v253, s1, 41
	s_nop 0
	v_readlane_b32 s0, v253, 4
	v_readlane_b32 s1, v253, 5
	s_andn2_b64 vcc, exec, s[0:1]
	s_barrier
	s_cbranch_vccnz .LBB0_691
	v_readlane_b32 s0, v253, 28
	s_add_i32 s57, s0, 0
	v_readlane_b32 s0, v253, 30
	s_add_i32 s58, s0, 0
	v_readlane_b32 s0, v253, 8
	s_add_i32 s63, s64, 0
	s_add_i32 s59, s0, 0
	v_readlane_b32 s0, v253, 12
	s_mov_b32 s9, 0
	s_add_i32 s56, s63, 0x10000
	s_add_i32 s60, s0, 0
	s_add_i32 s61, s63, 0x14000
	s_add_i32 s62, s63, 0x18000
	s_add_i32 s63, s63, 0x1c000
	s_add_i32 s66, s78, 0xfffffa00
	s_lshl_b32 s67, s78, 8
	s_lshl_b32 s68, s80, 8
	s_add_i32 s69, 0, 0x10000
	s_add_i32 s70, 0, 0x14000
	s_mov_b64 s[12:13], 0x80
	s_mov_b64 s[14:15], 0x12000080
	s_mov_b64 s[16:17], 0x3000100
	s_mov_b64 s[18:19], 0x12000100
	s_mov_b64 s[20:21], 0x3080100
	s_mov_b64 s[22:23], 0x3000180
	s_mov_b64 s[36:37], 0x12000180
	s_mov_b64 s[38:39], 0x3080180
	s_mov_b64 s[40:41], 0x100
	s_mov_b64 s[42:43], 0xf80
	s_movk_i32 s71, 0x1080
	s_movk_i32 s72, 0x2100
	s_mov_b64 s[44:45], 0x2400100
	s_mov_b64 s[46:47], 0x2480100
	s_mov_b64 s[48:49], 0x2400180
	s_mov_b64 s[50:51], 0x2480180
	s_movk_i32 s73, 0x1800
	v_mov_b32_e32 v129, 0
	v_mov_b32_e32 v146, 1
	s_mov_b32 s74, s78
	s_mov_b32 s75, s78
	s_cmpk_lt_u32 s75, 0x80
	s_cbranch_scc1 .Lp6_lo
	s_mov_b32 s98, 62
	s_bfe_u32 s99, s75, 0x20003
	s_mul_i32 s99, s99, 6
	s_add_u32 s98, s98, s99
	s_branch .Lp6_go
.Lp6_lo:
	s_mov_b32 s98, 0
	s_bfe_u32 s99, s75, 0x20003
	s_mul_i32 s99, s99, 6
	s_add_u32 s98, s98, s99

.LBB0_722:
	s_add_i32 s28, s51, 0
	v_add_u32_e32 v0, s28, v196
	s_setprio 1
	v_add_u32_e32 v201, v0, v197
	ds_read_b128 v[2:5], v201
	s_waitcnt lgkmcnt(0)
	v_mfma_f32_32x32x16_bf16 v[80:95], v[2:5], v[112:115], 0
	ds_read_b128 v[2:5], v201 offset:8704
	s_waitcnt lgkmcnt(0)
	v_mfma_f32_32x32x16_bf16 v[96:111], v[2:5], v[112:115], 0
	ds_read_b128 v[2:5], v201 offset:32
	s_waitcnt lgkmcnt(0)
	v_mfma_f32_32x32x16_bf16 v[80:95], v[2:5], v[116:119], v[80:95]
	ds_read_b128 v[2:5], v201 offset:8736
	s_waitcnt lgkmcnt(0)
	v_mfma_f32_32x32x16_bf16 v[96:111], v[2:5], v[116:119], v[96:111]
	ds_read_b128 v[2:5], v201 offset:64
	s_waitcnt lgkmcnt(0)
	v_mfma_f32_32x32x16_bf16 v[80:95], v[2:5], v[120:123], v[80:95]
	ds_read_b128 v[2:5], v201 offset:8768
	s_waitcnt lgkmcnt(0)
	v_mfma_f32_32x32x16_bf16 v[96:111], v[2:5], v[120:123], v[96:111]
	ds_read_b128 v[2:5], v201 offset:96
	s_waitcnt lgkmcnt(0)
	v_mfma_f32_32x32x16_bf16 v[80:95], v[2:5], v[124:127], v[80:95]
	ds_read_b128 v[2:5], v201 offset:8800
	s_waitcnt lgkmcnt(0)
	v_mfma_f32_32x32x16_bf16 v[96:111], v[2:5], v[124:127], v[96:111]
	ds_read_b128 v[2:5], v201 offset:128
	s_waitcnt lgkmcnt(0)
	v_mfma_f32_32x32x16_bf16 v[80:95], v[2:5], v[156:159], v[80:95]
	ds_read_b128 v[2:5], v201 offset:8832
	s_waitcnt lgkmcnt(0)
	v_mfma_f32_32x32x16_bf16 v[96:111], v[2:5], v[156:159], v[96:111]
	ds_read_b128 v[2:5], v201 offset:160
	s_waitcnt lgkmcnt(0)
	v_mfma_f32_32x32x16_bf16 v[80:95], v[2:5], v[160:163], v[80:95]
	ds_read_b128 v[2:5], v201 offset:8864
	s_waitcnt lgkmcnt(0)
	v_mfma_f32_32x32x16_bf16 v[96:111], v[2:5], v[160:163], v[96:111]
	ds_read_b128 v[2:5], v201 offset:192
	s_waitcnt lgkmcnt(0)
	v_mfma_f32_32x32x16_bf16 v[80:95], v[2:5], v[164:167], v[80:95]
	ds_read_b128 v[2:5], v201 offset:8896
	s_waitcnt lgkmcnt(0)
	v_mfma_f32_32x32x16_bf16 v[96:111], v[2:5], v[164:167], v[96:111]
	ds_read_b128 v[2:5], v201 offset:224
	s_waitcnt lgkmcnt(0)
	v_mfma_f32_32x32x16_bf16 v[80:95], v[2:5], v[172:175], v[80:95]
	ds_read_b128 v[2:5], v201 offset:8928
	s_waitcnt lgkmcnt(0)
	v_mfma_f32_32x32x16_bf16 v[96:111], v[2:5], v[172:175], v[96:111]
	s_setprio 0
	s_nop 10
	v_max_f32_e32 v0, v80, v96
	v_max_f32_e32 v2, v81, v97
	v_max3_f32 v0, v200, v0, v2
	v_max_f32_e32 v2, v82, v98
	v_max_f32_e32 v3, v83, v99
	v_max3_f32 v0, v0, v2, v3
	v_max_f32_e32 v2, v84, v100
	v_max_f32_e32 v3, v85, v101
	v_max3_f32 v0, v0, v2, v3
	v_max_f32_e32 v2, v86, v102
	v_max_f32_e32 v3, v87, v103
	v_max3_f32 v0, v0, v2, v3
	v_max_f32_e32 v2, v88, v104
	v_max_f32_e32 v3, v89, v105
	v_max3_f32 v0, v0, v2, v3
	v_max_f32_e32 v2, v90, v106
	v_max_f32_e32 v3, v91, v107
	v_max3_f32 v0, v0, v2, v3
	v_max_f32_e32 v2, v92, v108
	v_max_f32_e32 v3, v93, v109
	v_max3_f32 v0, v0, v2, v3
	v_max_f32_e32 v2, v94, v110
	v_max_f32_e32 v3, v111, v111
	v_max_f32_e32 v4, v95, v95
	v_max_f32_e32 v3, v4, v3
	v_max3_f32 v0, v0, v2, v3
	v_mov_b32_e32 v2, v0
	s_nop 1
	v_permlane32_swap_b32_e32 v0, v2
	v_max_f32_e32 v2, v2, v2
	v_max_f32_e32 v0, v0, v0
	v_max_f32_e32 v202, v0, v2
	v_add_f32_e32 v203, 0x41000000, v200
	v_cmp_gt_f32_e32 vcc, v202, v203
	s_cbranch_vccz .LBB0_724
	v_sub_f32_e32 v0, v200, v202
	v_exp_f32_e32 v0, v0
	v_add_f32_e32 v203, 0x41000000, v202
	v_mul_f32_e32 v204, v204, v0
	v_pk_mul_f32 v[78:79], v[78:79], v[0:1] op_sel_hi:[1,0]
	v_pk_mul_f32 v[76:77], v[76:77], v[0:1] op_sel_hi:[1,0]
	v_pk_mul_f32 v[74:75], v[74:75], v[0:1] op_sel_hi:[1,0]
	v_pk_mul_f32 v[72:73], v[72:73], v[0:1] op_sel_hi:[1,0]
	v_pk_mul_f32 v[70:71], v[70:71], v[0:1] op_sel_hi:[1,0]
	v_pk_mul_f32 v[68:69], v[68:69], v[0:1] op_sel_hi:[1,0]
	v_pk_mul_f32 v[66:67], v[66:67], v[0:1] op_sel_hi:[1,0]
	v_pk_mul_f32 v[64:65], v[64:65], v[0:1] op_sel_hi:[1,0]
	v_pk_mul_f32 v[62:63], v[62:63], v[0:1] op_sel_hi:[1,0]
	v_pk_mul_f32 v[60:61], v[60:61], v[0:1] op_sel_hi:[1,0]
	v_pk_mul_f32 v[58:59], v[58:59], v[0:1] op_sel_hi:[1,0]
	v_pk_mul_f32 v[56:57], v[56:57], v[0:1] op_sel_hi:[1,0]
	v_pk_mul_f32 v[54:55], v[54:55], v[0:1] op_sel_hi:[1,0]
	v_pk_mul_f32 v[52:53], v[52:53], v[0:1] op_sel_hi:[1,0]
	v_pk_mul_f32 v[50:51], v[50:51], v[0:1] op_sel_hi:[1,0]
	v_pk_mul_f32 v[48:49], v[48:49], v[0:1] op_sel_hi:[1,0]
	v_pk_mul_f32 v[46:47], v[46:47], v[0:1] op_sel_hi:[1,0]
	v_pk_mul_f32 v[44:45], v[44:45], v[0:1] op_sel_hi:[1,0]
	v_pk_mul_f32 v[42:43], v[42:43], v[0:1] op_sel_hi:[1,0]
	v_pk_mul_f32 v[40:41], v[40:41], v[0:1] op_sel_hi:[1,0]
	v_pk_mul_f32 v[38:39], v[38:39], v[0:1] op_sel_hi:[1,0]
	v_pk_mul_f32 v[36:37], v[36:37], v[0:1] op_sel_hi:[1,0]
	v_pk_mul_f32 v[34:35], v[34:35], v[0:1] op_sel_hi:[1,0]
	v_pk_mul_f32 v[32:33], v[32:33], v[0:1] op_sel_hi:[1,0]
	v_pk_mul_f32 v[30:31], v[30:31], v[0:1] op_sel_hi:[1,0]
	v_pk_mul_f32 v[28:29], v[28:29], v[0:1] op_sel_hi:[1,0]
	v_pk_mul_f32 v[26:27], v[26:27], v[0:1] op_sel_hi:[1,0]
	v_pk_mul_f32 v[24:25], v[24:25], v[0:1] op_sel_hi:[1,0]
	v_pk_mul_f32 v[22:23], v[22:23], v[0:1] op_sel_hi:[1,0]
	v_pk_mul_f32 v[20:21], v[20:21], v[0:1] op_sel_hi:[1,0]
	v_pk_mul_f32 v[18:19], v[18:19], v[0:1] op_sel_hi:[1,0]
	v_pk_mul_f32 v[16:17], v[16:17], v[0:1] op_sel_hi:[1,0]
	s_branch .LBB0_725

.LBB0_725:
	v_sub_f32_e32 v0, v80, v202
	v_exp_f32_e32 v200, v0
	v_sub_f32_e32 v0, v96, v202
	v_exp_f32_e32 v96, v0
	v_sub_f32_e32 v0, v81, v202
	v_sub_f32_e32 v2, v97, v202
	v_exp_f32_e32 v0, v0
	v_exp_f32_e32 v2, v2
	v_add_f32_e32 v3, v96, v200
	v_add_u32_e32 v194, s28, v197
	v_pk_add_f32 v[4:5], v[2:3], v[0:1]
	s_nop 0
	v_pk_add_f32 v[206:207], v[4:5], v[4:5] op_sel_hi:[0,1]
	v_sub_f32_e32 v4, v98, v202
	v_sub_f32_e32 v3, v82, v202
	v_exp_f32_e32 v97, v4
	v_sub_f32_e32 v4, v83, v202
	v_exp_f32_e32 v3, v3
	v_exp_f32_e32 v206, v4
	v_sub_f32_e32 v4, v99, v202
	v_exp_f32_e32 v4, v4
	v_add_f32_e32 v5, v97, v3
	v_cvt_pk_bf16_f32 v2, v96, v2
	v_pk_add_f32 v[6:7], v[4:5], v[206:207]
	s_nop 0
	v_pk_add_f32 v[98:99], v[6:7], v[6:7] op_sel_hi:[0,1]
	v_sub_f32_e32 v6, v100, v202
	v_sub_f32_e32 v5, v84, v202
	v_exp_f32_e32 v205, v6
	v_sub_f32_e32 v6, v85, v202
	v_exp_f32_e32 v5, v5
	v_exp_f32_e32 v98, v6
	v_sub_f32_e32 v6, v101, v202
	v_exp_f32_e32 v6, v6
	v_add_f32_e32 v7, v205, v5
	v_pk_add_f32 v[8:9], v[6:7], v[98:99]
	v_sub_f32_e32 v7, v86, v202
	v_exp_f32_e32 v99, v7
	v_sub_f32_e32 v7, v102, v202
	v_pk_add_f32 v[100:101], v[8:9], v[8:9] op_sel_hi:[0,1]
	v_exp_f32_e32 v207, v7
	v_sub_f32_e32 v7, v87, v202
	v_exp_f32_e32 v100, v7
	v_sub_f32_e32 v7, v103, v202
	v_exp_f32_e32 v10, v7
	v_add_f32_e32 v11, v207, v99
	v_sub_f32_e32 v7, v88, v202
	v_pk_add_f32 v[8:9], v[10:11], v[100:101]
	v_exp_f32_e32 v11, v7
	v_sub_f32_e32 v7, v104, v202
	v_pk_add_f32 v[82:83], v[8:9], v[8:9] op_sel_hi:[0,1]
	v_exp_f32_e32 v104, v7
	v_sub_f32_e32 v7, v89, v202
	v_exp_f32_e32 v82, v7
	v_sub_f32_e32 v7, v105, v202
	v_exp_f32_e32 v8, v7
	v_add_f32_e32 v9, v104, v11
	v_sub_f32_e32 v7, v90, v202
	v_cvt_pk_bf16_f32 v90, v5, v98
	v_pk_add_f32 v[12:13], v[8:9], v[82:83]
	v_exp_f32_e32 v9, v7
	v_sub_f32_e32 v7, v106, v202
	v_pk_add_f32 v[84:85], v[12:13], v[12:13] op_sel_hi:[0,1]
	v_exp_f32_e32 v105, v7
	v_sub_f32_e32 v7, v91, v202
	v_exp_f32_e32 v84, v7
	v_sub_f32_e32 v7, v107, v202
	v_exp_f32_e32 v12, v7
	v_add_f32_e32 v13, v105, v9
	v_sub_f32_e32 v7, v92, v202
	v_cvt_pk_bf16_f32 v91, v99, v100
	v_pk_add_f32 v[14:15], v[12:13], v[84:85]
	v_exp_f32_e32 v13, v7
	v_sub_f32_e32 v7, v108, v202
	v_pk_add_f32 v[86:87], v[14:15], v[14:15] op_sel_hi:[0,1]
	v_exp_f32_e32 v106, v7
	v_sub_f32_e32 v7, v93, v202
	v_exp_f32_e32 v86, v7
	v_sub_f32_e32 v7, v109, v202
	v_exp_f32_e32 v14, v7
	v_add_f32_e32 v15, v106, v13
	v_sub_f32_e32 v7, v94, v202
	v_cvt_pk_bf16_f32 v83, v9, v84
	v_pk_add_f32 v[80:81], v[14:15], v[86:87]
	v_exp_f32_e32 v15, v7
	v_sub_f32_e32 v7, v110, v202
	v_pk_add_f32 v[102:103], v[80:81], v[80:81] op_sel_hi:[0,1]
	v_exp_f32_e32 v107, v7
	v_sub_f32_e32 v7, v95, v202
	v_exp_f32_e32 v102, v7
	v_sub_f32_e32 v7, v111, v202
	v_exp_f32_e32 v80, v7
	v_add_f32_e32 v81, v107, v15
	v_cvt_pk_bf16_f32 v84, v13, v86
	v_cvt_pk_bf16_f32 v82, v11, v82
	v_pk_add_f32 v[88:89], v[80:81], v[102:103]
	v_cvt_pk_bf16_f32 v85, v15, v102
	v_pk_add_f32 v[88:89], v[88:89], v[88:89] op_sel:[0,1] op_sel_hi:[1,0]
	v_cvt_pk_bf16_f32 v5, v207, v10
	v_mov_b32_e32 v7, v88
	s_nop 1
	v_permlane32_swap_b32_e32 v88, v7
	v_add_f32_e32 v7, v88, v7
	v_cvt_pk_bf16_f32 v88, v200, v0
	v_add_u32_e32 v0, v194, v196
	ds_read_b128 v[92:95], v0 offset:34816
	ds_read_b128 v[98:101], v0 offset:34848
	v_cvt_pk_bf16_f32 v89, v3, v206
	v_cvt_pk_bf16_f32 v3, v97, v4
	v_cvt_pk_bf16_f32 v4, v205, v6
	s_waitcnt lgkmcnt(1)
	v_mfma_f32_32x32x16_bf16 v[64:79], v[92:95], v[88:91], v[64:79]
	ds_read_b128 v[92:95], v0 offset:43520
	v_add_f32_e32 v7, v204, v7
	s_waitcnt lgkmcnt(0)
	v_mfma_f32_32x32x16_bf16 v[48:63], v[92:95], v[88:91], v[48:63]
	ds_read_b128 v[92:95], v0 offset:52224
	s_waitcnt lgkmcnt(0)
	v_mfma_f32_32x32x16_bf16 v[32:47], v[92:95], v[88:91], v[32:47]
	ds_read_b128 v[92:95], v0 offset:60928
	s_waitcnt lgkmcnt(0)
	v_mfma_f32_32x32x16_bf16 v[16:31], v[92:95], v[88:91], v[16:31]
	ds_read_b128 v[86:89], v0 offset:43552
	s_waitcnt lgkmcnt(0)
	v_mfma_f32_32x32x16_bf16 v[48:63], v[86:89], v[82:85], v[48:63]
	ds_read_b128 v[86:89], v0 offset:52256
	s_waitcnt lgkmcnt(0)
	v_mfma_f32_32x32x16_bf16 v[32:47], v[86:89], v[82:85], v[32:47]
	ds_read_b128 v[86:89], v0 offset:60960
	v_mfma_f32_32x32x16_bf16 v[64:79], v[98:101], v[82:85], v[64:79]
	s_waitcnt lgkmcnt(0)
	v_mfma_f32_32x32x16_bf16 v[16:31], v[86:89], v[82:85], v[16:31]
	ds_read_b128 v[82:85], v0 offset:34880
	s_waitcnt lgkmcnt(0)
	v_mfma_f32_32x32x16_bf16 v[64:79], v[82:85], v[2:5], v[64:79]
	ds_read_b128 v[82:85], v0 offset:43584
	s_waitcnt lgkmcnt(0)
	v_mfma_f32_32x32x16_bf16 v[48:63], v[82:85], v[2:5], v[48:63]
	ds_read_b128 v[82:85], v0 offset:52288
	s_waitcnt lgkmcnt(0)
	v_mfma_f32_32x32x16_bf16 v[32:47], v[82:85], v[2:5], v[32:47]
	ds_read_b128 v[82:85], v0 offset:60992
	s_waitcnt lgkmcnt(0)
	v_mfma_f32_32x32x16_bf16 v[16:31], v[82:85], v[2:5], v[16:31]
	v_cvt_pk_bf16_f32 v2, v104, v8
	ds_read_b128 v[8:11], v0 offset:34912
	v_cvt_pk_bf16_f32 v3, v105, v12
	v_cvt_pk_bf16_f32 v4, v106, v14
	v_cvt_pk_bf16_f32 v5, v107, v80
	s_waitcnt lgkmcnt(0)
	s_nop 0
	v_mfma_f32_32x32x16_bf16 v[64:79], v[8:11], v[2:5], v[64:79]
	ds_read_b128 v[8:11], v0 offset:43616
	s_waitcnt lgkmcnt(0)
	v_mfma_f32_32x32x16_bf16 v[48:63], v[8:11], v[2:5], v[48:63]
	ds_read_b128 v[8:11], v0 offset:52320
	s_waitcnt lgkmcnt(0)
	v_mfma_f32_32x32x16_bf16 v[32:47], v[8:11], v[2:5], v[32:47]
	ds_read_b128 v[8:11], v0 offset:61024
	s_waitcnt lgkmcnt(0)
	v_mfma_f32_32x32x16_bf16 v[16:31], v[8:11], v[2:5], v[16:31]
	s_setprio 1
	ds_read_b128 v[2:5], v201 offset:17408
	s_waitcnt lgkmcnt(0)
	v_mfma_f32_32x32x16_bf16 v[80:95], v[2:5], v[112:115], 0
	ds_read_b128 v[2:5], v201 offset:26112
	s_waitcnt lgkmcnt(0)
	v_mfma_f32_32x32x16_bf16 v[96:111], v[2:5], v[112:115], 0
	ds_read_b128 v[2:5], v201 offset:17440
	s_waitcnt lgkmcnt(0)
	v_mfma_f32_32x32x16_bf16 v[80:95], v[2:5], v[116:119], v[80:95]
	ds_read_b128 v[2:5], v201 offset:26144
	s_waitcnt lgkmcnt(0)
	v_mfma_f32_32x32x16_bf16 v[96:111], v[2:5], v[116:119], v[96:111]
	ds_read_b128 v[2:5], v201 offset:17472
	s_waitcnt lgkmcnt(0)
	v_mfma_f32_32x32x16_bf16 v[80:95], v[2:5], v[120:123], v[80:95]
	ds_read_b128 v[2:5], v201 offset:26176
	s_waitcnt lgkmcnt(0)
	v_mfma_f32_32x32x16_bf16 v[96:111], v[2:5], v[120:123], v[96:111]
	ds_read_b128 v[2:5], v201 offset:17504
	s_waitcnt lgkmcnt(0)
	v_mfma_f32_32x32x16_bf16 v[80:95], v[2:5], v[124:127], v[80:95]
	ds_read_b128 v[2:5], v201 offset:26208
	s_waitcnt lgkmcnt(0)
	v_mfma_f32_32x32x16_bf16 v[96:111], v[2:5], v[124:127], v[96:111]
	ds_read_b128 v[2:5], v201 offset:17536
	s_waitcnt lgkmcnt(0)
	v_mfma_f32_32x32x16_bf16 v[80:95], v[2:5], v[156:159], v[80:95]
	ds_read_b128 v[2:5], v201 offset:26240
	s_waitcnt lgkmcnt(0)
	v_mfma_f32_32x32x16_bf16 v[96:111], v[2:5], v[156:159], v[96:111]
	ds_read_b128 v[2:5], v201 offset:17568
	s_waitcnt lgkmcnt(0)
	v_mfma_f32_32x32x16_bf16 v[80:95], v[2:5], v[160:163], v[80:95]
	ds_read_b128 v[2:5], v201 offset:26272
	s_waitcnt lgkmcnt(0)
	v_mfma_f32_32x32x16_bf16 v[96:111], v[2:5], v[160:163], v[96:111]
	ds_read_b128 v[2:5], v201 offset:17600
	s_waitcnt lgkmcnt(0)
	v_mfma_f32_32x32x16_bf16 v[80:95], v[2:5], v[164:167], v[80:95]
	ds_read_b128 v[2:5], v201 offset:26304
	s_waitcnt lgkmcnt(0)
	v_mfma_f32_32x32x16_bf16 v[96:111], v[2:5], v[164:167], v[96:111]
	ds_read_b128 v[2:5], v201 offset:17632
	s_waitcnt lgkmcnt(0)
	v_mfma_f32_32x32x16_bf16 v[80:95], v[2:5], v[172:175], v[80:95]
	ds_read_b128 v[2:5], v201 offset:26336
	s_waitcnt lgkmcnt(0)
	v_mfma_f32_32x32x16_bf16 v[96:111], v[2:5], v[172:175], v[96:111]
	s_setprio 0
	s_nop 10
	v_max_f32_e32 v2, v80, v96
	v_max_f32_e32 v3, v81, v97
	v_max3_f32 v2, v202, v2, v3
	v_max_f32_e32 v3, v82, v98
	v_max_f32_e32 v4, v83, v99
	v_max3_f32 v2, v2, v3, v4
	v_max_f32_e32 v3, v84, v100
	v_max_f32_e32 v4, v85, v101
	v_max3_f32 v2, v2, v3, v4
	v_max_f32_e32 v3, v86, v102
	v_max_f32_e32 v4, v87, v103
	v_max3_f32 v2, v2, v3, v4
	v_max_f32_e32 v3, v88, v104
	v_max_f32_e32 v4, v89, v105
	v_max3_f32 v2, v2, v3, v4
	v_max_f32_e32 v3, v90, v106
	v_max_f32_e32 v4, v91, v107
	v_max3_f32 v2, v2, v3, v4
	v_max_f32_e32 v3, v92, v108
	v_max_f32_e32 v4, v93, v109
	v_max3_f32 v2, v2, v3, v4
	v_max_f32_e32 v3, v94, v110
	v_max_f32_e32 v4, v95, v111
	v_max3_f32 v2, v2, v3, v4
	v_mov_b32_e32 v3, v2
	s_nop 1
	v_permlane32_swap_b32_e32 v2, v3
	v_max_f32_e32 v3, v3, v3
	v_max_f32_e32 v2, v2, v2
	v_max_f32_e32 v200, v2, v3
	v_cmp_gt_f32_e32 vcc, v200, v203
	s_cbranch_vccz .LBB0_727
	v_sub_f32_e32 v2, v202, v200
	v_exp_f32_e32 v2, v2
	s_nop 0
	v_mul_f32_e32 v7, v7, v2
	v_pk_mul_f32 v[78:79], v[78:79], v[2:3] op_sel_hi:[1,0]
	v_pk_mul_f32 v[76:77], v[76:77], v[2:3] op_sel_hi:[1,0]
	v_pk_mul_f32 v[74:75], v[74:75], v[2:3] op_sel_hi:[1,0]
	v_pk_mul_f32 v[72:73], v[72:73], v[2:3] op_sel_hi:[1,0]
	v_pk_mul_f32 v[70:71], v[70:71], v[2:3] op_sel_hi:[1,0]
	v_pk_mul_f32 v[68:69], v[68:69], v[2:3] op_sel_hi:[1,0]
	v_pk_mul_f32 v[66:67], v[66:67], v[2:3] op_sel_hi:[1,0]
	v_pk_mul_f32 v[64:65], v[64:65], v[2:3] op_sel_hi:[1,0]
	v_pk_mul_f32 v[62:63], v[62:63], v[2:3] op_sel_hi:[1,0]
	v_pk_mul_f32 v[60:61], v[60:61], v[2:3] op_sel_hi:[1,0]
	v_pk_mul_f32 v[58:59], v[58:59], v[2:3] op_sel_hi:[1,0]
	v_pk_mul_f32 v[56:57], v[56:57], v[2:3] op_sel_hi:[1,0]
	v_pk_mul_f32 v[54:55], v[54:55], v[2:3] op_sel_hi:[1,0]
	v_pk_mul_f32 v[52:53], v[52:53], v[2:3] op_sel_hi:[1,0]
	v_pk_mul_f32 v[50:51], v[50:51], v[2:3] op_sel_hi:[1,0]
	v_pk_mul_f32 v[48:49], v[48:49], v[2:3] op_sel_hi:[1,0]
	v_pk_mul_f32 v[46:47], v[46:47], v[2:3] op_sel_hi:[1,0]
	v_pk_mul_f32 v[44:45], v[44:45], v[2:3] op_sel_hi:[1,0]
	v_pk_mul_f32 v[42:43], v[42:43], v[2:3] op_sel_hi:[1,0]
	v_pk_mul_f32 v[40:41], v[40:41], v[2:3] op_sel_hi:[1,0]
	v_pk_mul_f32 v[38:39], v[38:39], v[2:3] op_sel_hi:[1,0]
	v_pk_mul_f32 v[36:37], v[36:37], v[2:3] op_sel_hi:[1,0]
	v_pk_mul_f32 v[34:35], v[34:35], v[2:3] op_sel_hi:[1,0]
	v_pk_mul_f32 v[32:33], v[32:33], v[2:3] op_sel_hi:[1,0]
	v_pk_mul_f32 v[30:31], v[30:31], v[2:3] op_sel_hi:[1,0]
	v_pk_mul_f32 v[28:29], v[28:29], v[2:3] op_sel_hi:[1,0]
	v_pk_mul_f32 v[26:27], v[26:27], v[2:3] op_sel_hi:[1,0]
	v_pk_mul_f32 v[24:25], v[24:25], v[2:3] op_sel_hi:[1,0]
	v_pk_mul_f32 v[22:23], v[22:23], v[2:3] op_sel_hi:[1,0]
	v_pk_mul_f32 v[20:21], v[20:21], v[2:3] op_sel_hi:[1,0]
	v_pk_mul_f32 v[18:19], v[18:19], v[2:3] op_sel_hi:[1,0]
	v_pk_mul_f32 v[16:17], v[16:17], v[2:3] op_sel_hi:[1,0]
	s_branch .LBB0_728

.LBB0_914:
	s_nop 3
	v_max_f32_e32 v0, v96, v80
	v_max_f32_e32 v4, v97, v81
	v_max3_f32 v0, v202, v0, v4
	v_max_f32_e32 v4, v98, v82
	v_max_f32_e32 v5, v99, v83
	v_max3_f32 v0, v0, v4, v5
	v_max_f32_e32 v4, v100, v84
	v_max_f32_e32 v5, v101, v85
	v_max3_f32 v0, v0, v4, v5
	v_max_f32_e32 v4, v102, v86
	v_max_f32_e32 v5, v103, v87
	v_max3_f32 v0, v0, v4, v5
	v_max_f32_e32 v4, v104, v88
	v_max_f32_e32 v5, v105, v89
	v_max3_f32 v0, v0, v4, v5
	v_max_f32_e32 v4, v106, v90
	v_max_f32_e32 v5, v107, v91
	v_max3_f32 v0, v0, v4, v5
	v_max_f32_e32 v4, v108, v92
	v_max_f32_e32 v5, v109, v93
	v_max3_f32 v0, v0, v4, v5
	v_max_f32_e32 v4, v110, v94
	v_max_f32_e32 v5, v111, v95
	v_max3_f32 v0, v0, v4, v5
	v_mov_b32_e32 v4, v0
	s_nop 1
	v_permlane32_swap_b32_e32 v0, v4
	v_max_f32_e32 v4, v4, v4
	v_max_f32_e32 v0, v0, v0
	v_max_f32_e32 v4, v0, v4
	v_add_f32_e32 v0, 0x41000000, v202
	v_cmp_gt_f32_e32 vcc, v4, v0
	s_cbranch_vccz .LBB0_916
	v_sub_f32_e32 v0, v202, v4
	v_exp_f32_e32 v0, v0
	v_mov_b32_e32 v202, v4
	v_mul_f32_e32 v198, v198, v0
	v_pk_mul_f32 v[78:79], v[78:79], v[0:1] op_sel_hi:[1,0]
	v_pk_mul_f32 v[76:77], v[76:77], v[0:1] op_sel_hi:[1,0]
	v_pk_mul_f32 v[74:75], v[74:75], v[0:1] op_sel_hi:[1,0]
	v_pk_mul_f32 v[72:73], v[72:73], v[0:1] op_sel_hi:[1,0]
	v_pk_mul_f32 v[70:71], v[70:71], v[0:1] op_sel_hi:[1,0]
	v_pk_mul_f32 v[68:69], v[68:69], v[0:1] op_sel_hi:[1,0]
	v_pk_mul_f32 v[66:67], v[66:67], v[0:1] op_sel_hi:[1,0]
	v_pk_mul_f32 v[64:65], v[64:65], v[0:1] op_sel_hi:[1,0]
	v_pk_mul_f32 v[62:63], v[62:63], v[0:1] op_sel_hi:[1,0]
	v_pk_mul_f32 v[60:61], v[60:61], v[0:1] op_sel_hi:[1,0]
	v_pk_mul_f32 v[58:59], v[58:59], v[0:1] op_sel_hi:[1,0]
	v_pk_mul_f32 v[56:57], v[56:57], v[0:1] op_sel_hi:[1,0]
	v_pk_mul_f32 v[54:55], v[54:55], v[0:1] op_sel_hi:[1,0]
	v_pk_mul_f32 v[52:53], v[52:53], v[0:1] op_sel_hi:[1,0]
	v_pk_mul_f32 v[50:51], v[50:51], v[0:1] op_sel_hi:[1,0]
	v_pk_mul_f32 v[48:49], v[48:49], v[0:1] op_sel_hi:[1,0]
	v_pk_mul_f32 v[46:47], v[46:47], v[0:1] op_sel_hi:[1,0]
	v_pk_mul_f32 v[44:45], v[44:45], v[0:1] op_sel_hi:[1,0]
	v_pk_mul_f32 v[42:43], v[42:43], v[0:1] op_sel_hi:[1,0]
	v_pk_mul_f32 v[40:41], v[40:41], v[0:1] op_sel_hi:[1,0]
	v_pk_mul_f32 v[38:39], v[38:39], v[0:1] op_sel_hi:[1,0]
	v_pk_mul_f32 v[36:37], v[36:37], v[0:1] op_sel_hi:[1,0]
	v_pk_mul_f32 v[34:35], v[34:35], v[0:1] op_sel_hi:[1,0]
	v_pk_mul_f32 v[32:33], v[32:33], v[0:1] op_sel_hi:[1,0]
	v_pk_mul_f32 v[30:31], v[30:31], v[0:1] op_sel_hi:[1,0]
	v_pk_mul_f32 v[28:29], v[28:29], v[0:1] op_sel_hi:[1,0]
	v_pk_mul_f32 v[26:27], v[26:27], v[0:1] op_sel_hi:[1,0]
	v_pk_mul_f32 v[24:25], v[24:25], v[0:1] op_sel_hi:[1,0]
	v_pk_mul_f32 v[22:23], v[22:23], v[0:1] op_sel_hi:[1,0]
	v_pk_mul_f32 v[20:21], v[20:21], v[0:1] op_sel_hi:[1,0]
	v_pk_mul_f32 v[18:19], v[18:19], v[0:1] op_sel_hi:[1,0]
	v_pk_mul_f32 v[16:17], v[16:17], v[0:1] op_sel_hi:[1,0]
	s_branch .LBB0_917

.LBB0_921:
	s_nop 3
	v_max_f32_e32 v0, v96, v80
	v_max_f32_e32 v3, v97, v81
	v_max3_f32 v0, v202, v0, v3
	v_max_f32_e32 v3, v98, v82
	v_max_f32_e32 v4, v99, v83
	v_max3_f32 v0, v0, v3, v4
	v_max_f32_e32 v3, v100, v84
	v_max_f32_e32 v4, v101, v85
	v_max3_f32 v0, v0, v3, v4
	v_max_f32_e32 v3, v102, v86
	v_max_f32_e32 v4, v103, v87
	v_max3_f32 v0, v0, v3, v4
	v_max_f32_e32 v3, v104, v88
	v_max_f32_e32 v4, v105, v89
	v_max3_f32 v0, v0, v3, v4
	v_max_f32_e32 v3, v106, v90
	v_max_f32_e32 v4, v107, v91
	v_max3_f32 v0, v0, v3, v4
	v_max_f32_e32 v3, v108, v92
	v_max_f32_e32 v4, v109, v93
	v_max3_f32 v0, v0, v3, v4
	v_max_f32_e32 v3, v110, v94
	v_max_f32_e32 v4, v95, v95
	v_max_f32_e32 v5, v111, v111
	v_max_f32_e32 v4, v5, v4
	v_max3_f32 v0, v0, v3, v4
	v_mov_b32_e32 v3, v0
	s_nop 1
	v_permlane32_swap_b32_e32 v0, v3
	v_max_f32_e32 v3, v3, v3
	v_max_f32_e32 v0, v0, v0
	v_max_f32_e32 v3, v0, v3
	v_add_f32_e32 v0, 0x41000000, v202
	v_cmp_gt_f32_e32 vcc, v3, v0
	s_cbranch_vccz .LBB0_923
	v_sub_f32_e32 v0, v202, v3
	v_exp_f32_e32 v0, v0
	v_mov_b32_e32 v202, v3
	v_mul_f32_e32 v198, v198, v0
	v_pk_mul_f32 v[78:79], v[78:79], v[0:1] op_sel_hi:[1,0]
	v_pk_mul_f32 v[76:77], v[76:77], v[0:1] op_sel_hi:[1,0]
	v_pk_mul_f32 v[74:75], v[74:75], v[0:1] op_sel_hi:[1,0]
	v_pk_mul_f32 v[72:73], v[72:73], v[0:1] op_sel_hi:[1,0]
	v_pk_mul_f32 v[70:71], v[70:71], v[0:1] op_sel_hi:[1,0]
	v_pk_mul_f32 v[68:69], v[68:69], v[0:1] op_sel_hi:[1,0]
	v_pk_mul_f32 v[66:67], v[66:67], v[0:1] op_sel_hi:[1,0]
	v_pk_mul_f32 v[64:65], v[64:65], v[0:1] op_sel_hi:[1,0]
	v_pk_mul_f32 v[62:63], v[62:63], v[0:1] op_sel_hi:[1,0]
	v_pk_mul_f32 v[60:61], v[60:61], v[0:1] op_sel_hi:[1,0]
	v_pk_mul_f32 v[58:59], v[58:59], v[0:1] op_sel_hi:[1,0]
	v_pk_mul_f32 v[56:57], v[56:57], v[0:1] op_sel_hi:[1,0]
	v_pk_mul_f32 v[54:55], v[54:55], v[0:1] op_sel_hi:[1,0]
	v_pk_mul_f32 v[52:53], v[52:53], v[0:1] op_sel_hi:[1,0]
	v_pk_mul_f32 v[50:51], v[50:51], v[0:1] op_sel_hi:[1,0]
	v_pk_mul_f32 v[48:49], v[48:49], v[0:1] op_sel_hi:[1,0]
	v_pk_mul_f32 v[46:47], v[46:47], v[0:1] op_sel_hi:[1,0]
	v_pk_mul_f32 v[44:45], v[44:45], v[0:1] op_sel_hi:[1,0]
	v_pk_mul_f32 v[42:43], v[42:43], v[0:1] op_sel_hi:[1,0]
	v_pk_mul_f32 v[40:41], v[40:41], v[0:1] op_sel_hi:[1,0]
	v_pk_mul_f32 v[38:39], v[38:39], v[0:1] op_sel_hi:[1,0]
	v_pk_mul_f32 v[36:37], v[36:37], v[0:1] op_sel_hi:[1,0]
	v_pk_mul_f32 v[34:35], v[34:35], v[0:1] op_sel_hi:[1,0]
	v_pk_mul_f32 v[32:33], v[32:33], v[0:1] op_sel_hi:[1,0]
	v_pk_mul_f32 v[30:31], v[30:31], v[0:1] op_sel_hi:[1,0]
	v_pk_mul_f32 v[28:29], v[28:29], v[0:1] op_sel_hi:[1,0]
	v_pk_mul_f32 v[26:27], v[26:27], v[0:1] op_sel_hi:[1,0]
	v_pk_mul_f32 v[24:25], v[24:25], v[0:1] op_sel_hi:[1,0]
	v_pk_mul_f32 v[22:23], v[22:23], v[0:1] op_sel_hi:[1,0]
	v_pk_mul_f32 v[20:21], v[20:21], v[0:1] op_sel_hi:[1,0]
	v_pk_mul_f32 v[18:19], v[18:19], v[0:1] op_sel_hi:[1,0]
	v_pk_mul_f32 v[16:17], v[16:17], v[0:1] op_sel_hi:[1,0]
	s_branch .LBB0_924

.LBB0_943:
	v_lshl_add_u64 v[4:5], s[76:77], 0, v[106:107]
	s_mov_b32 s33, 0x2e000000
	v_add_co_u32_e32 v0, vcc, s33, v4
	s_mov_b32 s33, 0x2e008000
	s_nop 0
	v_addc_co_u32_e32 v1, vcc, 0, v5, vcc
	global_load_dwordx4 v[0:3], v[0:1], off
	v_add_u32_e32 v28, v200, v201
	s_mov_b32 s0, 0x800000
	v_readlane_b32 s40, v254, 15
	v_readlane_b32 s41, v254, 16
	v_readlane_b32 s50, v254, 19
	v_readlane_b32 s51, v254, 20
	v_readlane_b32 s44, v254, 21
	v_readlane_b32 s45, v254, 22
	v_readlane_b32 s48, v254, 23
	v_readlane_b32 s49, v254, 24
	v_readlane_b32 s52, v254, 25
	v_readlane_b32 s53, v254, 26
	v_readlane_b32 s58, v254, 27
	v_readlane_b32 s59, v254, 28
	v_readlane_b32 s60, v254, 29
	v_readlane_b32 s61, v254, 30
	v_readlane_b32 s62, v254, 31
	v_readlane_b32 s63, v254, 32
	v_readlane_b32 s54, v254, 33
	v_readlane_b32 s55, v254, 34
	v_readlane_b32 s56, v254, 35
	v_readlane_b32 s57, v254, 36
	v_readlane_b32 s68, v254, 37
	v_readlane_b32 s69, v254, 38
	v_readlane_b32 s70, v254, 39
	v_readlane_b32 s71, v254, 40
	v_readlane_b32 s72, v254, 41
	v_readlane_b32 s73, v254, 42
	v_readlane_b32 s74, v254, 43
	v_readlane_b32 s75, v254, 44
	v_readlane_b32 s42, v254, 45
	v_readlane_b32 s43, v254, 46
	v_readlane_b32 s78, v254, 47
	v_readlane_b32 s79, v254, 48
	v_readlane_b32 s80, v254, 49
	v_readlane_b32 s81, v254, 50
	v_readlane_b32 s82, v254, 51
	v_readlane_b32 s83, v254, 52
	v_readlane_b32 s84, v254, 53
	v_readlane_b32 s85, v254, 54
	v_readlane_b32 s86, v254, 55
	v_readlane_b32 s87, v254, 56
	v_readlane_b32 s88, v254, 57
	v_readlane_b32 s89, v254, 58
	v_readlane_b32 s90, v254, 59
	v_readlane_b32 s91, v254, 60
	v_readlane_b32 s92, v254, 61
	v_readlane_b32 s93, v254, 62
	v_writelane_b32 v255, s4, 53
	v_readlane_b32 s94, v254, 63
	s_waitcnt vmcnt(0)
	ds_write_b128 v191, v[0:3]
	v_add_co_u32_e32 v0, vcc, s33, v4
	s_mov_b32 s33, 0x2e010000
	s_nop 0
	v_addc_co_u32_e32 v1, vcc, 0, v5, vcc
	global_load_dwordx4 v[0:3], v[0:1], off offset:1024
	v_writelane_b32 v255, s5, 54
	s_waitcnt vmcnt(0)
	ds_write_b128 v192, v[0:3]
	v_add_co_u32_e32 v0, vcc, s33, v4
	s_mov_b32 s33, 0x2e018000
	s_nop 0
	v_addc_co_u32_e32 v1, vcc, 0, v5, vcc
	global_load_dwordx4 v[0:3], v[0:1], off offset:2048
	v_readlane_b32 s95, v255, 0
	v_readlane_b32 s96, v255, 1
	v_readlane_b32 s97, v255, 2
	v_readlane_b32 s4, v255, 3
	v_readlane_b32 s5, v255, 4
	v_readlane_b32 s6, v255, 5
	v_readlane_b32 s7, v255, 6
	v_readlane_b32 s2, v255, 7
	v_readlane_b32 s3, v255, 8
	v_readlane_b32 s8, v255, 9
	v_readlane_b32 s9, v255, 10
	v_readlane_b32 s10, v255, 11
	v_readlane_b32 s11, v255, 12
	v_readlane_b32 s12, v255, 13
	v_readlane_b32 s13, v255, 14
	v_readlane_b32 s14, v255, 15
	v_readlane_b32 s15, v255, 16
	v_readlane_b32 s16, v255, 17
	v_readlane_b32 s17, v255, 18
	v_readlane_b32 s18, v255, 19
	v_readlane_b32 s19, v255, 20
	v_readlane_b32 s20, v255, 21
	v_readlane_b32 s21, v255, 22
	v_readlane_b32 s22, v255, 23
	v_readlane_b32 s23, v255, 24
	v_readlane_b32 s24, v255, 25
	v_readlane_b32 s25, v255, 26
	v_readlane_b32 s26, v255, 27
	v_readlane_b32 s27, v255, 28
	v_readlane_b32 s28, v255, 29
	v_readlane_b32 s29, v255, 30
	v_readlane_b32 s30, v255, 31
	v_readlane_b32 s31, v255, 32
	v_readlane_b32 s34, v255, 33
	v_readlane_b32 s35, v255, 34
	v_readlane_b32 s36, v255, 35
	v_readlane_b32 s37, v255, 36
	v_readlane_b32 s38, v255, 37
	v_readlane_b32 s39, v255, 38
	v_readlane_b32 s66, v255, 39
	v_readlane_b32 s67, v255, 40
	v_readlane_b32 s64, v255, 43
	v_readlane_b32 s65, v255, 44
	v_readlane_b32 s46, v255, 45
	v_readlane_b32 s47, v255, 46
	s_waitcnt vmcnt(0)
	ds_write_b128 v193, v[0:3]
	v_add_co_u32_e32 v0, vcc, s33, v4
	s_mov_b32 s33, 0x12004000
	s_nop 0
	v_addc_co_u32_e32 v1, vcc, 0, v5, vcc
	global_load_dwordx4 v[0:3], v[0:1], off offset:3072
	s_waitcnt vmcnt(0)
	ds_write_b128 v195, v[0:3]
	v_lshl_add_u64 v[0:1], s[76:77], 0, v[108:109]
	global_load_dwordx4 v[0:3], v[0:1], off
	s_waitcnt vmcnt(0)
	ds_write_b128 v196, v[0:3]
	v_lshl_add_u64 v[0:1], s[76:77], 0, v[110:111]
	global_load_dwordx4 v[0:3], v[0:1], off
	s_waitcnt vmcnt(0)
	ds_write_b128 v197, v[0:3]
	v_lshl_add_u64 v[0:1], s[76:77], 0, v[112:113]
	global_load_dwordx4 v[0:3], v[0:1], off
	s_waitcnt vmcnt(0)
	ds_write_b128 v198, v[0:3]
	v_lshl_add_u64 v[0:1], s[76:77], 0, v[114:115]
	global_load_dwordx4 v[0:3], v[0:1], off
	v_readlane_b32 s76, v255, 41
	v_readlane_b32 s77, v255, 42
	s_waitcnt vmcnt(0)
	ds_write_b128 v199, v[0:3]
	ds_read_b128 v[0:3], v28
	ds_read_b128 v[4:7], v28 offset:32
	ds_read_b128 v[8:11], v28 offset:64
	ds_read_b128 v[12:15], v28 offset:96
	ds_read_b128 v[16:19], v28 offset:128
	ds_read_b128 v[20:23], v28 offset:160
	ds_read_b128 v[24:27], v28 offset:192
	ds_read_b128 v[28:31], v28 offset:224
	s_waitcnt lgkmcnt(7)
	v_lshlrev_b32_e32 v92, 16, v0
	v_and_b32_e32 v93, 0xffff0000, v0
	v_lshlrev_b32_e32 v152, 16, v1
	v_and_b32_e32 v153, 0xffff0000, v1
	v_lshlrev_b32_e32 v94, 16, v2
	v_and_b32_e32 v95, 0xffff0000, v2
	v_lshlrev_b32_e32 v150, 16, v3
	v_and_b32_e32 v151, 0xffff0000, v3
	s_waitcnt lgkmcnt(6)
	v_lshlrev_b32_e32 v88, 16, v4
	v_and_b32_e32 v89, 0xffff0000, v4
	v_lshlrev_b32_e32 v148, 16, v5
	v_and_b32_e32 v149, 0xffff0000, v5
	v_lshlrev_b32_e32 v90, 16, v6
	v_and_b32_e32 v91, 0xffff0000, v6
	v_lshlrev_b32_e32 v146, 16, v7
	v_and_b32_e32 v147, 0xffff0000, v7
	s_waitcnt lgkmcnt(5)
	v_lshlrev_b32_e32 v84, 16, v8
	v_and_b32_e32 v85, 0xffff0000, v8
	v_lshlrev_b32_e32 v144, 16, v9
	v_and_b32_e32 v145, 0xffff0000, v9
	v_lshlrev_b32_e32 v86, 16, v10
	v_and_b32_e32 v87, 0xffff0000, v10
	v_lshlrev_b32_e32 v142, 16, v11
	v_and_b32_e32 v143, 0xffff0000, v11
	s_waitcnt lgkmcnt(4)
	v_lshlrev_b32_e32 v80, 16, v12
	v_and_b32_e32 v81, 0xffff0000, v12
	v_lshlrev_b32_e32 v140, 16, v13
	v_and_b32_e32 v141, 0xffff0000, v13
	v_lshlrev_b32_e32 v82, 16, v14
	v_and_b32_e32 v83, 0xffff0000, v14
	v_lshlrev_b32_e32 v138, 16, v15
	v_and_b32_e32 v139, 0xffff0000, v15
	s_waitcnt lgkmcnt(3)
	v_lshlrev_b32_e32 v76, 16, v16
	v_and_b32_e32 v77, 0xffff0000, v16
	v_lshlrev_b32_e32 v136, 16, v17
	v_and_b32_e32 v137, 0xffff0000, v17
	v_lshlrev_b32_e32 v78, 16, v18
	v_and_b32_e32 v79, 0xffff0000, v18
	v_lshlrev_b32_e32 v134, 16, v19
	v_and_b32_e32 v135, 0xffff0000, v19
	s_waitcnt lgkmcnt(2)
	v_lshlrev_b32_e32 v72, 16, v20
	v_and_b32_e32 v73, 0xffff0000, v20
	v_lshlrev_b32_e32 v132, 16, v21
	v_and_b32_e32 v133, 0xffff0000, v21
	v_lshlrev_b32_e32 v74, 16, v22
	v_and_b32_e32 v75, 0xffff0000, v22
	v_lshlrev_b32_e32 v130, 16, v23
	v_and_b32_e32 v131, 0xffff0000, v23
	s_waitcnt lgkmcnt(1)
	v_lshlrev_b32_e32 v68, 16, v24
	v_and_b32_e32 v69, 0xffff0000, v24
	v_lshlrev_b32_e32 v128, 16, v25
	v_and_b32_e32 v129, 0xffff0000, v25
	v_lshlrev_b32_e32 v70, 16, v26
	v_and_b32_e32 v71, 0xffff0000, v26
	v_lshlrev_b32_e32 v126, 16, v27
	v_and_b32_e32 v127, 0xffff0000, v27
	s_waitcnt lgkmcnt(0)
	v_lshlrev_b32_e32 v64, 16, v28
	v_and_b32_e32 v65, 0xffff0000, v28
	v_lshlrev_b32_e32 v124, 16, v29
	v_and_b32_e32 v125, 0xffff0000, v29
	v_lshlrev_b32_e32 v66, 16, v30
	v_and_b32_e32 v67, 0xffff0000, v30
	v_lshlrev_b32_e32 v122, 16, v31
	v_and_b32_e32 v123, 0xffff0000, v31
	global_load_dwordx4 v[0:3], v[102:103], off offset:464
	global_load_dwordx4 v[4:7], v[102:103], off offset:448
	global_load_dwordx4 v[8:11], v[102:103], off offset:400
	global_load_dwordx4 v[12:15], v[102:103], off offset:384
	global_load_dwordx4 v[16:19], v[102:103], off offset:336
	global_load_dwordx4 v[20:23], v[102:103], off offset:320
	global_load_dwordx4 v[24:27], v[102:103], off offset:272
	global_load_dwordx4 v[28:31], v[102:103], off offset:256
	global_load_dwordx4 v[32:35], v[102:103], off offset:208
	global_load_dwordx4 v[36:39], v[102:103], off offset:192
	global_load_dwordx4 v[40:43], v[102:103], off offset:144
	global_load_dwordx4 v[44:47], v[102:103], off offset:128
	global_load_dwordx4 v[48:51], v[102:103], off offset:80
	global_load_dwordx4 v[52:55], v[102:103], off offset:64
	global_load_dwordx4 v[56:59], v[102:103], off offset:16
	global_load_dwordx4 v[60:63], v[102:103], off
	v_mul_f32_e32 v194, v93, v93
	v_pk_fma_f32 v[234:235], v[92:93], v[92:93], v[194:195] op_sel_hi:[1,1,0]
	v_mul_f32_e32 v194, v153, v153
	v_pk_fma_f32 v[234:235], v[152:153], v[152:153], v[234:235]
	s_nop 0
	v_pk_add_f32 v[234:235], v[194:195], v[234:235] op_sel_hi:[0,1]
	v_pk_fma_f32 v[234:235], v[94:95], v[94:95], v[234:235]
	v_mul_f32_e32 v194, v95, v95
	v_pk_add_f32 v[234:235], v[194:195], v[234:235] op_sel_hi:[0,1]
	v_pk_fma_f32 v[234:235], v[150:151], v[150:151], v[234:235]
	v_mul_f32_e32 v194, v151, v151
	v_pk_add_f32 v[234:235], v[194:195], v[234:235] op_sel_hi:[0,1]
	v_pk_fma_f32 v[234:235], v[88:89], v[88:89], v[234:235]
	v_mul_f32_e32 v194, v89, v89
	v_pk_add_f32 v[234:235], v[194:195], v[234:235] op_sel_hi:[0,1]
	v_pk_fma_f32 v[234:235], v[148:149], v[148:149], v[234:235]
	v_mul_f32_e32 v194, v149, v149
	v_pk_add_f32 v[234:235], v[194:195], v[234:235] op_sel_hi:[0,1]
	v_pk_fma_f32 v[234:235], v[90:91], v[90:91], v[234:235]
	v_mul_f32_e32 v194, v91, v91
	v_pk_add_f32 v[234:235], v[194:195], v[234:235] op_sel_hi:[0,1]
	v_pk_fma_f32 v[234:235], v[146:147], v[146:147], v[234:235]
	v_mul_f32_e32 v194, v147, v147
	v_pk_add_f32 v[234:235], v[194:195], v[234:235] op_sel_hi:[0,1]
	v_pk_fma_f32 v[234:235], v[84:85], v[84:85], v[234:235]
	v_mul_f32_e32 v194, v85, v85
	v_pk_add_f32 v[234:235], v[194:195], v[234:235] op_sel_hi:[0,1]
	v_pk_fma_f32 v[234:235], v[144:145], v[144:145], v[234:235]
	v_mul_f32_e32 v194, v145, v145
	v_pk_add_f32 v[234:235], v[194:195], v[234:235] op_sel_hi:[0,1]
	v_pk_fma_f32 v[234:235], v[86:87], v[86:87], v[234:235]
	v_mul_f32_e32 v194, v87, v87
	v_pk_add_f32 v[234:235], v[194:195], v[234:235] op_sel_hi:[0,1]
	v_pk_fma_f32 v[234:235], v[142:143], v[142:143], v[234:235]
	v_mul_f32_e32 v194, v143, v143
	v_pk_add_f32 v[234:235], v[194:195], v[234:235] op_sel_hi:[0,1]
	v_pk_fma_f32 v[234:235], v[80:81], v[80:81], v[234:235]
	v_mul_f32_e32 v194, v81, v81
	v_pk_add_f32 v[234:235], v[194:195], v[234:235] op_sel_hi:[0,1]
	v_pk_fma_f32 v[234:235], v[140:141], v[140:141], v[234:235]
	v_mul_f32_e32 v194, v141, v141
	v_pk_add_f32 v[234:235], v[194:195], v[234:235] op_sel_hi:[0,1]
	v_pk_fma_f32 v[234:235], v[82:83], v[82:83], v[234:235]
	v_mul_f32_e32 v194, v83, v83
	v_pk_add_f32 v[234:235], v[194:195], v[234:235] op_sel_hi:[0,1]
	v_pk_fma_f32 v[234:235], v[138:139], v[138:139], v[234:235]
	v_mul_f32_e32 v194, v139, v139
	v_pk_add_f32 v[234:235], v[194:195], v[234:235] op_sel_hi:[0,1]
	v_pk_fma_f32 v[234:235], v[76:77], v[76:77], v[234:235]
	v_mul_f32_e32 v194, v77, v77
	v_pk_add_f32 v[234:235], v[194:195], v[234:235] op_sel_hi:[0,1]
	v_pk_fma_f32 v[234:235], v[136:137], v[136:137], v[234:235]
	v_mul_f32_e32 v194, v137, v137
	v_pk_add_f32 v[234:235], v[194:195], v[234:235] op_sel_hi:[0,1]
	v_pk_fma_f32 v[234:235], v[78:79], v[78:79], v[234:235]
	v_mul_f32_e32 v194, v79, v79
	v_pk_add_f32 v[234:235], v[194:195], v[234:235] op_sel_hi:[0,1]
	v_pk_fma_f32 v[234:235], v[134:135], v[134:135], v[234:235]
	v_mul_f32_e32 v194, v135, v135
	v_pk_add_f32 v[234:235], v[194:195], v[234:235] op_sel_hi:[0,1]
	v_pk_fma_f32 v[234:235], v[72:73], v[72:73], v[234:235]
	v_mul_f32_e32 v194, v73, v73
	v_pk_add_f32 v[234:235], v[194:195], v[234:235] op_sel_hi:[0,1]
	v_pk_fma_f32 v[234:235], v[132:133], v[132:133], v[234:235]
	v_mul_f32_e32 v194, v133, v133
	v_pk_add_f32 v[234:235], v[194:195], v[234:235] op_sel_hi:[0,1]
	v_pk_fma_f32 v[234:235], v[74:75], v[74:75], v[234:235]
	v_mul_f32_e32 v194, v75, v75
	v_pk_add_f32 v[234:235], v[194:195], v[234:235] op_sel_hi:[0,1]
	v_pk_fma_f32 v[234:235], v[130:131], v[130:131], v[234:235]
	v_mul_f32_e32 v194, v131, v131
	v_pk_add_f32 v[234:235], v[194:195], v[234:235] op_sel_hi:[0,1]
	v_pk_fma_f32 v[234:235], v[68:69], v[68:69], v[234:235]
	v_mul_f32_e32 v194, v69, v69
	v_pk_add_f32 v[234:235], v[194:195], v[234:235] op_sel_hi:[0,1]
	v_pk_fma_f32 v[234:235], v[128:129], v[128:129], v[234:235]
	v_mul_f32_e32 v194, v129, v129
	v_pk_add_f32 v[234:235], v[194:195], v[234:235] op_sel_hi:[0,1]
	v_pk_fma_f32 v[234:235], v[70:71], v[70:71], v[234:235]
	v_mul_f32_e32 v194, v71, v71
	v_pk_add_f32 v[234:235], v[194:195], v[234:235] op_sel_hi:[0,1]
	v_pk_fma_f32 v[234:235], v[126:127], v[126:127], v[234:235]
	v_mul_f32_e32 v194, v127, v127
	v_pk_add_f32 v[234:235], v[194:195], v[234:235] op_sel_hi:[0,1]
	v_pk_fma_f32 v[234:235], v[64:65], v[64:65], v[234:235]
	v_mul_f32_e32 v194, v65, v65
	v_pk_add_f32 v[234:235], v[194:195], v[234:235] op_sel_hi:[0,1]
	v_pk_fma_f32 v[234:235], v[124:125], v[124:125], v[234:235]
	v_mul_f32_e32 v194, v125, v125
	v_pk_add_f32 v[234:235], v[194:195], v[234:235] op_sel_hi:[0,1]
	v_pk_fma_f32 v[234:235], v[66:67], v[66:67], v[234:235]
	v_mul_f32_e32 v194, v67, v67
	v_pk_add_f32 v[234:235], v[194:195], v[234:235] op_sel_hi:[0,1]
	v_pk_fma_f32 v[234:235], v[122:123], v[122:123], v[234:235]
	v_mul_f32_e32 v194, v123, v123
	v_pk_add_f32 v[234:235], v[194:195], v[234:235] op_sel_hi:[0,1]
	v_mov_b32_e32 v194, v234
	s_nop 1
	v_permlane32_swap_b32_e32 v234, v194
	v_add_f32_e32 v194, v234, v194
	v_fmamk_f32 v194, v194, 0x3c000000, v162
	v_cmp_gt_f32_e32 vcc, s0, v194
	v_mul_f32_e32 v233, 0x4b800000, v194
	v_readlane_b32 s0, v252, 38
	v_cndmask_b32_e32 v194, v194, v233, vcc
	v_rsq_f32_e32 v194, v194
	v_readlane_b32 s1, v252, 39
	v_mul_f32_e32 v233, 0x45800000, v194
	v_cndmask_b32_e32 v194, v194, v233, vcc
	v_mul_f32_e32 v194, 0x3e0293ee, v194
	v_pk_mul_f32 v[92:93], v[194:195], v[92:93] op_sel_hi:[0,1]
	s_waitcnt vmcnt(0)
	v_pk_mul_f32 v[60:61], v[60:61], v[92:93]
	v_readlane_b32 vcc_lo, v254, 17
	v_cvt_pk_bf16_f32 v92, v60, v61
	v_pk_mul_f32 v[60:61], v[194:195], v[152:153] op_sel_hi:[0,1]
	v_pk_mul_f32 v[60:61], v[62:63], v[60:61]
	v_readlane_b32 vcc_hi, v254, 18
	v_cvt_pk_bf16_f32 v93, v60, v61
	v_pk_mul_f32 v[60:61], v[194:195], v[94:95] op_sel_hi:[0,1]
	v_pk_mul_f32 v[56:57], v[56:57], v[60:61]
	s_nop 0
	v_cvt_pk_bf16_f32 v94, v56, v57
	v_pk_mul_f32 v[56:57], v[194:195], v[150:151] op_sel_hi:[0,1]
	v_pk_mul_f32 v[56:57], v[58:59], v[56:57]
	s_nop 0
	v_cvt_pk_bf16_f32 v95, v56, v57
	v_pk_mul_f32 v[56:57], v[194:195], v[88:89] op_sel_hi:[0,1]
	v_pk_mul_f32 v[52:53], v[52:53], v[56:57]
	s_nop 0
	v_cvt_pk_bf16_f32 v88, v52, v53
	v_pk_mul_f32 v[52:53], v[194:195], v[148:149] op_sel_hi:[0,1]
	v_pk_mul_f32 v[52:53], v[54:55], v[52:53]
	s_nop 0
	v_cvt_pk_bf16_f32 v89, v52, v53
	v_pk_mul_f32 v[52:53], v[194:195], v[90:91] op_sel_hi:[0,1]
	v_pk_mul_f32 v[48:49], v[52:53], v[48:49]
	s_nop 0
	v_cvt_pk_bf16_f32 v90, v48, v49
	v_pk_mul_f32 v[48:49], v[194:195], v[146:147] op_sel_hi:[0,1]
	v_pk_mul_f32 v[48:49], v[48:49], v[50:51]
	s_nop 0
	v_cvt_pk_bf16_f32 v91, v48, v49
	v_pk_mul_f32 v[48:49], v[194:195], v[84:85] op_sel_hi:[0,1]
	v_pk_mul_f32 v[44:45], v[48:49], v[44:45]
	s_nop 0
	v_cvt_pk_bf16_f32 v84, v44, v45
	v_pk_mul_f32 v[44:45], v[194:195], v[144:145] op_sel_hi:[0,1]
	v_pk_mul_f32 v[44:45], v[44:45], v[46:47]
	s_nop 0
	v_cvt_pk_bf16_f32 v85, v44, v45
	v_pk_mul_f32 v[44:45], v[194:195], v[86:87] op_sel_hi:[0,1]
	v_pk_mul_f32 v[40:41], v[44:45], v[40:41]
	s_nop 0
	v_cvt_pk_bf16_f32 v86, v40, v41
	v_pk_mul_f32 v[40:41], v[194:195], v[142:143] op_sel_hi:[0,1]
	v_pk_mul_f32 v[40:41], v[40:41], v[42:43]
	s_nop 0
	v_cvt_pk_bf16_f32 v87, v40, v41
	v_pk_mul_f32 v[40:41], v[194:195], v[80:81] op_sel_hi:[0,1]
	v_pk_mul_f32 v[36:37], v[40:41], v[36:37]
	s_nop 0
	v_cvt_pk_bf16_f32 v80, v36, v37
	v_pk_mul_f32 v[36:37], v[194:195], v[140:141] op_sel_hi:[0,1]
	v_pk_mul_f32 v[36:37], v[36:37], v[38:39]
	s_nop 0
	v_cvt_pk_bf16_f32 v81, v36, v37
	v_pk_mul_f32 v[36:37], v[194:195], v[82:83] op_sel_hi:[0,1]
	v_pk_mul_f32 v[32:33], v[36:37], v[32:33]
	s_nop 0
	v_cvt_pk_bf16_f32 v82, v32, v33
	v_pk_mul_f32 v[32:33], v[194:195], v[138:139] op_sel_hi:[0,1]
	v_pk_mul_f32 v[32:33], v[32:33], v[34:35]
	s_nop 0
	v_cvt_pk_bf16_f32 v83, v32, v33
	v_pk_mul_f32 v[32:33], v[194:195], v[76:77] op_sel_hi:[0,1]
	v_pk_mul_f32 v[28:29], v[32:33], v[28:29]
	s_nop 0
	v_cvt_pk_bf16_f32 v76, v28, v29
	v_pk_mul_f32 v[28:29], v[194:195], v[136:137] op_sel_hi:[0,1]
	v_pk_mul_f32 v[28:29], v[28:29], v[30:31]
	s_nop 0
	v_cvt_pk_bf16_f32 v77, v28, v29
	v_pk_mul_f32 v[28:29], v[194:195], v[78:79] op_sel_hi:[0,1]
	v_pk_mul_f32 v[24:25], v[28:29], v[24:25]
	s_nop 0
	v_cvt_pk_bf16_f32 v78, v24, v25
	v_pk_mul_f32 v[24:25], v[194:195], v[134:135] op_sel_hi:[0,1]
	v_pk_mul_f32 v[24:25], v[24:25], v[26:27]
	s_nop 0
	v_cvt_pk_bf16_f32 v79, v24, v25
	v_pk_mul_f32 v[24:25], v[194:195], v[72:73] op_sel_hi:[0,1]
	v_pk_mul_f32 v[20:21], v[24:25], v[20:21]
	s_nop 0
	v_cvt_pk_bf16_f32 v72, v20, v21
	v_pk_mul_f32 v[20:21], v[194:195], v[132:133] op_sel_hi:[0,1]
	v_pk_mul_f32 v[20:21], v[20:21], v[22:23]
	s_nop 0
	v_cvt_pk_bf16_f32 v73, v20, v21
	v_pk_mul_f32 v[20:21], v[194:195], v[74:75] op_sel_hi:[0,1]
	v_pk_mul_f32 v[16:17], v[20:21], v[16:17]
	s_nop 0
	v_cvt_pk_bf16_f32 v74, v16, v17
	v_pk_mul_f32 v[16:17], v[194:195], v[130:131] op_sel_hi:[0,1]
	v_pk_mul_f32 v[16:17], v[16:17], v[18:19]
	s_nop 0
	v_cvt_pk_bf16_f32 v75, v16, v17
	v_pk_mul_f32 v[16:17], v[194:195], v[68:69] op_sel_hi:[0,1]
	v_pk_mul_f32 v[12:13], v[16:17], v[12:13]
	s_nop 0
	v_cvt_pk_bf16_f32 v68, v12, v13
	v_pk_mul_f32 v[12:13], v[194:195], v[128:129] op_sel_hi:[0,1]
	v_pk_mul_f32 v[12:13], v[12:13], v[14:15]
	s_nop 0
	v_cvt_pk_bf16_f32 v69, v12, v13
	v_pk_mul_f32 v[12:13], v[194:195], v[70:71] op_sel_hi:[0,1]
	v_pk_mul_f32 v[8:9], v[12:13], v[8:9]
	s_nop 0
	v_cvt_pk_bf16_f32 v70, v8, v9
	v_pk_mul_f32 v[8:9], v[194:195], v[126:127] op_sel_hi:[0,1]
	v_pk_mul_f32 v[8:9], v[8:9], v[10:11]
	s_nop 0
	v_cvt_pk_bf16_f32 v71, v8, v9
	v_pk_mul_f32 v[8:9], v[194:195], v[64:65] op_sel_hi:[0,1]
	v_pk_mul_f32 v[4:5], v[8:9], v[4:5]
	s_nop 0
	v_cvt_pk_bf16_f32 v64, v4, v5
	v_pk_mul_f32 v[4:5], v[194:195], v[124:125] op_sel_hi:[0,1]
	v_pk_mul_f32 v[4:5], v[4:5], v[6:7]
	s_nop 0
	v_cvt_pk_bf16_f32 v65, v4, v5
	v_pk_mul_f32 v[4:5], v[194:195], v[66:67] op_sel_hi:[0,1]
	v_pk_mul_f32 v[0:1], v[4:5], v[0:1]
	s_nop 0
	v_cvt_pk_bf16_f32 v66, v0, v1
	v_pk_mul_f32 v[0:1], v[194:195], v[122:123] op_sel_hi:[0,1]
	v_pk_mul_f32 v[0:1], v[0:1], v[2:3]
	s_nop 0
	v_cvt_pk_bf16_f32 v67, v0, v1
	ds_read_b128 v[0:3], v202
	ds_read_b128 v[122:125], v202 offset:32
	s_waitcnt lgkmcnt(1)
	v_mfma_f32_32x32x16_bf16 v[48:63], v[0:3], v[92:95], 0
	ds_read_b128 v[0:3], v202 offset:8704
	s_waitcnt lgkmcnt(0)
	v_mfma_f32_32x32x16_bf16 v[32:47], v[0:3], v[92:95], 0
	ds_read_b128 v[0:3], v202 offset:17408
	s_waitcnt lgkmcnt(0)
	v_mfma_f32_32x32x16_bf16 v[16:31], v[0:3], v[92:95], 0
	ds_read_b128 v[0:3], v202 offset:26112
	s_waitcnt lgkmcnt(0)
	v_mfma_f32_32x32x16_bf16 v[0:15], v[0:3], v[92:95], 0
	ds_read_b128 v[92:95], v202 offset:8736
	s_waitcnt lgkmcnt(0)
	v_mfma_f32_32x32x16_bf16 v[32:47], v[92:95], v[88:91], v[32:47]
	ds_read_b128 v[92:95], v202 offset:17440
	s_waitcnt lgkmcnt(0)
	v_mfma_f32_32x32x16_bf16 v[16:31], v[92:95], v[88:91], v[16:31]
	ds_read_b128 v[92:95], v202 offset:26144
	v_mfma_f32_32x32x16_bf16 v[48:63], v[122:125], v[88:91], v[48:63]
	s_waitcnt lgkmcnt(0)
	v_mfma_f32_32x32x16_bf16 v[0:15], v[92:95], v[88:91], v[0:15]
	ds_read_b128 v[88:91], v202 offset:64
	s_waitcnt lgkmcnt(0)
	v_mfma_f32_32x32x16_bf16 v[48:63], v[88:91], v[84:87], v[48:63]
	ds_read_b128 v[88:91], v202 offset:8768
	s_waitcnt lgkmcnt(0)
	v_mfma_f32_32x32x16_bf16 v[32:47], v[88:91], v[84:87], v[32:47]
	ds_read_b128 v[88:91], v202 offset:17472
	s_waitcnt lgkmcnt(0)
	v_mfma_f32_32x32x16_bf16 v[16:31], v[88:91], v[84:87], v[16:31]
	ds_read_b128 v[88:91], v202 offset:26176
	s_waitcnt lgkmcnt(0)
	v_mfma_f32_32x32x16_bf16 v[0:15], v[88:91], v[84:87], v[0:15]
	ds_read_b128 v[84:87], v202 offset:96
	s_waitcnt lgkmcnt(0)
	v_mfma_f32_32x32x16_bf16 v[48:63], v[84:87], v[80:83], v[48:63]
	ds_read_b128 v[84:87], v202 offset:8800
	s_waitcnt lgkmcnt(0)
	v_mfma_f32_32x32x16_bf16 v[32:47], v[84:87], v[80:83], v[32:47]
	ds_read_b128 v[84:87], v202 offset:17504
	s_waitcnt lgkmcnt(0)
	v_mfma_f32_32x32x16_bf16 v[16:31], v[84:87], v[80:83], v[16:31]
	ds_read_b128 v[84:87], v202 offset:26208
	s_waitcnt lgkmcnt(0)
	v_mfma_f32_32x32x16_bf16 v[0:15], v[84:87], v[80:83], v[0:15]
	ds_read_b128 v[80:83], v202 offset:128
	s_waitcnt lgkmcnt(0)
	v_mfma_f32_32x32x16_bf16 v[48:63], v[80:83], v[76:79], v[48:63]
	ds_read_b128 v[80:83], v202 offset:8832
	s_waitcnt lgkmcnt(0)
	v_mfma_f32_32x32x16_bf16 v[32:47], v[80:83], v[76:79], v[32:47]
	ds_read_b128 v[80:83], v202 offset:17536
	s_waitcnt lgkmcnt(0)
	v_mfma_f32_32x32x16_bf16 v[16:31], v[80:83], v[76:79], v[16:31]
	ds_read_b128 v[80:83], v202 offset:26240
	s_waitcnt lgkmcnt(0)
	v_mfma_f32_32x32x16_bf16 v[0:15], v[80:83], v[76:79], v[0:15]
	ds_read_b128 v[76:79], v202 offset:160
	s_waitcnt lgkmcnt(0)
	v_mfma_f32_32x32x16_bf16 v[48:63], v[76:79], v[72:75], v[48:63]
	ds_read_b128 v[76:79], v202 offset:8864
	s_waitcnt lgkmcnt(0)
	v_mfma_f32_32x32x16_bf16 v[32:47], v[76:79], v[72:75], v[32:47]
	ds_read_b128 v[76:79], v202 offset:17568
	s_waitcnt lgkmcnt(0)
	v_mfma_f32_32x32x16_bf16 v[16:31], v[76:79], v[72:75], v[16:31]
	ds_read_b128 v[76:79], v202 offset:26272
	s_waitcnt lgkmcnt(0)
	v_mfma_f32_32x32x16_bf16 v[0:15], v[76:79], v[72:75], v[0:15]
	ds_read_b128 v[72:75], v202 offset:192
	s_waitcnt lgkmcnt(0)
	v_mfma_f32_32x32x16_bf16 v[48:63], v[72:75], v[68:71], v[48:63]
	ds_read_b128 v[72:75], v202 offset:8896
	s_waitcnt lgkmcnt(0)
	v_mfma_f32_32x32x16_bf16 v[32:47], v[72:75], v[68:71], v[32:47]
	ds_read_b128 v[72:75], v202 offset:17600
	s_waitcnt lgkmcnt(0)
	v_mfma_f32_32x32x16_bf16 v[16:31], v[72:75], v[68:71], v[16:31]
	ds_read_b128 v[72:75], v202 offset:26304
	s_waitcnt lgkmcnt(0)
	v_mfma_f32_32x32x16_bf16 v[0:15], v[72:75], v[68:71], v[0:15]
	ds_read_b128 v[68:71], v202 offset:224
	s_waitcnt lgkmcnt(0)
	v_mfma_f32_32x32x16_bf16 v[48:63], v[68:71], v[64:67], v[48:63]
	ds_read_b128 v[68:71], v202 offset:8928
	s_waitcnt lgkmcnt(0)
	v_mfma_f32_32x32x16_bf16 v[32:47], v[68:71], v[64:67], v[32:47]
	ds_read_b128 v[68:71], v202 offset:17632
	s_waitcnt lgkmcnt(0)
	v_mfma_f32_32x32x16_bf16 v[16:31], v[68:71], v[64:67], v[16:31]
	ds_read_b128 v[68:71], v202 offset:26336
	s_waitcnt lgkmcnt(0)
	v_mfma_f32_32x32x16_bf16 v[0:15], v[68:71], v[64:67], v[0:15]
	s_nop 2
	v_max_f32_e32 v64, v48, v48
	v_max_f32_e32 v64, 0xf149f2ca, v64
	v_cndmask_b32_e64 v64, v64, v163, s[40:41]
	v_max_f32_e32 v65, v49, v49
	v_max_f32_e32 v65, v64, v65
	v_cndmask_b32_e32 v64, v65, v64, vcc
	v_max_f32_e32 v65, v50, v50
	v_max_f32_e32 v65, v64, v65
	v_cndmask_b32_e64 v64, v65, v64, s[50:51]
	v_max_f32_e32 v65, v51, v51
	v_max_f32_e32 v65, v64, v65
	v_cndmask_b32_e64 v64, v65, v64, s[44:45]
	v_max_f32_e32 v65, v52, v52
	v_max_f32_e32 v65, v64, v65
	v_cndmask_b32_e64 v64, v65, v64, s[48:49]
	v_max_f32_e32 v65, v53, v64
	v_cndmask_b32_e64 v64, v65, v64, s[52:53]
	v_max_f32_e32 v65, v54, v64
	v_cndmask_b32_e64 v64, v65, v64, s[58:59]
	v_max_f32_e32 v65, v55, v64
	v_cndmask_b32_e64 v64, v65, v64, s[60:61]
	v_max_f32_e32 v65, v56, v64
	v_cndmask_b32_e64 v64, v65, v64, s[62:63]
	v_max_f32_e32 v65, v57, v64
	v_cndmask_b32_e64 v64, v65, v64, s[54:55]
	v_max_f32_e32 v65, v58, v64
	v_cndmask_b32_e64 v64, v65, v64, s[56:57]
	v_max_f32_e32 v65, v59, v64
	v_cndmask_b32_e64 v64, v65, v64, s[68:69]
	v_max_f32_e32 v65, v60, v64
	v_cndmask_b32_e64 v64, v65, v64, s[70:71]
	v_max_f32_e32 v65, v61, v64
	v_cndmask_b32_e64 v64, v65, v64, s[72:73]
	v_max_f32_e32 v65, v62, v64
	v_cndmask_b32_e64 v64, v65, v64, s[74:75]
	v_max_f32_e32 v65, v63, v64
	v_cndmask_b32_e64 v64, v65, v64, s[42:43]
	v_max_f32_e32 v65, v32, v64
	v_cndmask_b32_e64 v64, v65, v64, s[78:79]
	v_max_f32_e32 v65, v33, v64
	v_cndmask_b32_e64 v64, v65, v64, s[80:81]
	v_max_f32_e32 v65, v34, v64
	v_cndmask_b32_e64 v64, v65, v64, s[82:83]
	v_max_f32_e32 v65, v35, v64
	v_cndmask_b32_e64 v64, v65, v64, s[84:85]
	v_max_f32_e32 v65, v36, v64
	v_cndmask_b32_e64 v64, v65, v64, s[86:87]
	v_max_f32_e32 v65, v37, v64
	v_cndmask_b32_e64 v64, v65, v64, s[88:89]
	v_max_f32_e32 v65, v38, v64
	v_cndmask_b32_e64 v64, v65, v64, s[90:91]
	v_max_f32_e32 v65, v39, v64
	v_cndmask_b32_e64 v64, v65, v64, s[92:93]
	v_max_f32_e32 v65, v40, v64
	v_cndmask_b32_e64 v64, v65, v64, s[94:95]
	v_max_f32_e32 v65, v41, v64
	v_cndmask_b32_e64 v64, v65, v64, s[96:97]
	v_max_f32_e32 v65, v42, v64
	v_cndmask_b32_e64 v64, v65, v64, s[0:1]
	v_max_f32_e32 v65, v43, v64
	v_cndmask_b32_e64 v64, v65, v64, s[4:5]
	v_max_f32_e32 v65, v44, v64
	v_cndmask_b32_e64 v64, v65, v64, s[6:7]
	v_max_f32_e32 v65, v45, v64
	v_cndmask_b32_e64 v64, v65, v64, s[2:3]
	v_max_f32_e32 v65, v46, v64
	v_cndmask_b32_e64 v64, v65, v64, s[8:9]
	v_max_f32_e32 v65, v47, v64
	v_cndmask_b32_e64 v64, v65, v64, s[10:11]
	v_max_f32_e32 v65, v16, v64
	v_cndmask_b32_e64 v64, v65, v64, s[12:13]
	v_max_f32_e32 v65, v17, v64
	v_cndmask_b32_e64 v64, v65, v64, s[14:15]
	v_max_f32_e32 v65, v18, v64
	v_cndmask_b32_e64 v64, v65, v64, s[16:17]
	v_max_f32_e32 v65, v19, v64
	v_cndmask_b32_e64 v64, v65, v64, s[18:19]
	v_max_f32_e32 v65, v20, v64
	v_cndmask_b32_e64 v64, v65, v64, s[20:21]
	v_max_f32_e32 v65, v21, v64
	v_cndmask_b32_e64 v64, v65, v64, s[22:23]
	v_max_f32_e32 v65, v22, v64
	v_cndmask_b32_e64 v64, v65, v64, s[24:25]
	v_max_f32_e32 v65, v23, v64
	v_cndmask_b32_e64 v64, v65, v64, s[26:27]
	v_max_f32_e32 v65, v24, v64
	v_cndmask_b32_e64 v64, v65, v64, s[28:29]
	v_max_f32_e32 v65, v25, v64
	v_cndmask_b32_e64 v64, v65, v64, s[30:31]
	v_max_f32_e32 v65, v26, v64
	v_cndmask_b32_e64 v64, v65, v64, s[34:35]
	v_max_f32_e32 v65, v27, v64
	v_cndmask_b32_e64 v64, v65, v64, s[36:37]
	v_max_f32_e32 v65, v28, v64
	v_cndmask_b32_e64 v64, v65, v64, s[38:39]
	v_max_f32_e32 v65, v29, v64
	v_cndmask_b32_e64 v64, v65, v64, s[66:67]
	v_max_f32_e32 v65, v30, v64
	v_cndmask_b32_e64 v64, v65, v64, s[76:77]
	v_max_f32_e32 v65, v31, v64
	v_cndmask_b32_e64 v64, v65, v64, s[64:65]
	v_max_f32_e32 v65, v0, v64
	v_cndmask_b32_e64 v64, v65, v64, s[46:47]
	v_max_f32_e32 v65, v64, v64
	v_max_f32_e32 v66, v1, v1
	v_readlane_b32 s0, v253, 8
	v_max_f32_e32 v65, v65, v66
	v_readlane_b32 s1, v253, 9
	v_max_f32_e32 v66, v2, v2
	s_nop 0
	v_cndmask_b32_e64 v64, v65, v64, s[0:1]
	v_max_f32_e32 v65, v64, v64
	v_readlane_b32 s0, v253, 12
	v_max_f32_e32 v65, v65, v66
	v_readlane_b32 s1, v253, 13
	v_max_f32_e32 v66, v3, v3
	s_nop 0
	v_cndmask_b32_e64 v64, v65, v64, s[0:1]
	v_max_f32_e32 v65, v64, v64
	v_readlane_b32 s0, v253, 30
	v_max_f32_e32 v65, v65, v66
	v_readlane_b32 s1, v253, 31
	v_max_f32_e32 v66, v4, v4
	s_nop 0
	v_cndmask_b32_e64 v64, v65, v64, s[0:1]
	v_max_f32_e32 v65, v64, v64
	v_readlane_b32 s0, v253, 28
	v_max_f32_e32 v65, v65, v66
	v_readlane_b32 s1, v253, 29
	v_max_f32_e32 v66, v5, v5
	s_nop 0
	v_cndmask_b32_e64 v64, v65, v64, s[0:1]
	v_max_f32_e32 v65, v64, v64
	v_readlane_b32 s0, v252, 54
	v_max_f32_e32 v65, v65, v66
	v_readlane_b32 s1, v252, 55
	v_max_f32_e32 v66, v6, v6
	s_nop 0
	v_cndmask_b32_e64 v64, v65, v64, s[0:1]
	v_max_f32_e32 v65, v64, v64
	v_readlane_b32 s0, v253, 14
	v_max_f32_e32 v65, v65, v66
	v_readlane_b32 s1, v253, 15
	v_max_f32_e32 v66, v7, v7
	s_nop 0
	v_cndmask_b32_e64 v64, v65, v64, s[0:1]
	v_max_f32_e32 v65, v64, v64
	v_readlane_b32 s0, v252, 58
	v_max_f32_e32 v65, v65, v66
	v_readlane_b32 s1, v252, 59
	v_max_f32_e32 v66, v8, v8
	s_nop 0
	v_cndmask_b32_e64 v64, v65, v64, s[0:1]
	v_max_f32_e32 v65, v64, v64
	v_readlane_b32 s0, v252, 56
	v_max_f32_e32 v65, v65, v66
	v_readlane_b32 s1, v252, 57
	v_max_f32_e32 v66, v9, v9
	s_nop 0
	v_cndmask_b32_e64 v64, v65, v64, s[0:1]
	v_max_f32_e32 v65, v64, v64
	v_readlane_b32 s0, v252, 16
	v_max_f32_e32 v65, v65, v66
	v_readlane_b32 s1, v252, 17
	v_max_f32_e32 v66, v10, v10
	s_nop 0
	v_cndmask_b32_e64 v64, v65, v64, s[0:1]
	v_max_f32_e32 v65, v64, v64
	v_readlane_b32 s0, v253, 24
	v_max_f32_e32 v65, v65, v66
	v_readlane_b32 s1, v253, 25
	v_max_f32_e32 v66, v11, v11
	s_nop 0
	v_cndmask_b32_e64 v64, v65, v64, s[0:1]
	v_max_f32_e32 v65, v64, v64
	v_readlane_b32 s0, v253, 4
	v_max_f32_e32 v65, v65, v66
	v_readlane_b32 s1, v253, 5
	v_max_f32_e32 v66, v12, v12
	s_nop 0
	v_cndmask_b32_e64 v64, v65, v64, s[0:1]
	v_max_f32_e32 v65, v64, v64
	v_readlane_b32 s0, v252, 18
	v_max_f32_e32 v65, v65, v66
	v_readlane_b32 s1, v252, 19
	v_max_f32_e32 v66, v13, v13
	s_nop 0
	v_cndmask_b32_e64 v64, v65, v64, s[0:1]
	v_max_f32_e32 v65, v64, v64
	v_readlane_b32 s0, v255, 47
	v_max_f32_e32 v65, v65, v66
	v_readlane_b32 s1, v255, 48
	v_max_f32_e32 v66, v14, v14
	s_nop 0
	v_cndmask_b32_e64 v64, v65, v64, s[0:1]
	v_max_f32_e32 v65, v64, v64
	v_readlane_b32 s0, v255, 49
	v_max_f32_e32 v65, v65, v66
	v_readlane_b32 s1, v255, 50
	v_max_f32_e32 v66, v15, v15
	s_nop 0
	v_cndmask_b32_e64 v64, v65, v64, s[0:1]
	v_max_f32_e32 v65, v64, v64
	v_readlane_b32 s0, v255, 51
	v_max_f32_e32 v65, v65, v66
	v_readlane_b32 s1, v255, 52
	s_nop 1
	v_cndmask_b32_e64 v64, v65, v64, s[0:1]
	v_mov_b32_e32 v65, v64
	s_nop 1
	v_permlane32_swap_b32_e32 v64, v65
	v_max_f32_e32 v65, v65, v65
	v_max_f32_e32 v64, v64, v64
	v_max_f32_e32 v64, v64, v65
	v_sub_f32_e32 v48, v48, v64
	v_exp_f32_e32 v48, v48
	v_sub_f32_e32 v49, v49, v64
	v_exp_f32_e32 v49, v49
	v_sub_f32_e32 v50, v50, v64
	v_exp_f32_e32 v50, v50
	v_sub_f32_e32 v51, v51, v64
	v_exp_f32_e32 v51, v51
	v_sub_f32_e32 v52, v52, v64
	v_cndmask_b32_e64 v48, v48, 0, s[40:41]
	v_exp_f32_e32 v52, v52
	v_sub_f32_e32 v53, v53, v64
	v_add_f32_e32 v65, 0, v48
	v_cndmask_b32_e64 v49, v49, 0, vcc
	v_exp_f32_e32 v53, v53
	v_sub_f32_e32 v54, v54, v64
	v_add_f32_e32 v65, v49, v65
	v_cndmask_b32_e64 v50, v50, 0, s[50:51]
	v_exp_f32_e32 v54, v54
	v_sub_f32_e32 v55, v55, v64
	v_add_f32_e32 v65, v50, v65
	v_cndmask_b32_e64 v51, v51, 0, s[44:45]
	v_exp_f32_e32 v55, v55
	v_sub_f32_e32 v56, v56, v64
	v_add_f32_e32 v65, v51, v65
	v_cndmask_b32_e64 v52, v52, 0, s[48:49]
	v_exp_f32_e32 v56, v56
	v_sub_f32_e32 v57, v57, v64
	v_add_f32_e32 v65, v52, v65
	v_cndmask_b32_e64 v53, v53, 0, s[52:53]
	v_exp_f32_e32 v57, v57
	v_sub_f32_e32 v58, v58, v64
	v_add_f32_e32 v65, v53, v65
	v_cndmask_b32_e64 v54, v54, 0, s[58:59]
	v_exp_f32_e32 v58, v58
	v_sub_f32_e32 v59, v59, v64
	v_add_f32_e32 v65, v54, v65
	v_cndmask_b32_e64 v55, v55, 0, s[60:61]
	v_exp_f32_e32 v59, v59
	v_sub_f32_e32 v60, v60, v64
	v_add_f32_e32 v65, v55, v65
	v_cndmask_b32_e64 v56, v56, 0, s[62:63]
	v_exp_f32_e32 v60, v60
	v_sub_f32_e32 v61, v61, v64
	v_add_f32_e32 v65, v56, v65
	v_cndmask_b32_e64 v57, v57, 0, s[54:55]
	v_exp_f32_e32 v61, v61
	v_sub_f32_e32 v62, v62, v64
	v_add_f32_e32 v65, v57, v65
	v_cndmask_b32_e64 v58, v58, 0, s[56:57]
	v_exp_f32_e32 v62, v62
	v_sub_f32_e32 v63, v63, v64
	v_add_f32_e32 v65, v58, v65
	v_cndmask_b32_e64 v59, v59, 0, s[68:69]
	v_exp_f32_e32 v63, v63
	v_sub_f32_e32 v32, v32, v64
	v_add_f32_e32 v65, v59, v65
	v_cndmask_b32_e64 v60, v60, 0, s[70:71]
	v_exp_f32_e32 v32, v32
	v_sub_f32_e32 v33, v33, v64
	v_add_f32_e32 v65, v60, v65
	v_cndmask_b32_e64 v61, v61, 0, s[72:73]
	v_exp_f32_e32 v33, v33
	v_sub_f32_e32 v34, v34, v64
	v_add_f32_e32 v65, v61, v65
	v_cndmask_b32_e64 v62, v62, 0, s[74:75]
	v_exp_f32_e32 v34, v34
	v_sub_f32_e32 v35, v35, v64
	v_add_f32_e32 v65, v62, v65
	v_cndmask_b32_e64 v63, v63, 0, s[42:43]
	v_exp_f32_e32 v35, v35
	v_sub_f32_e32 v36, v36, v64
	v_add_f32_e32 v65, v63, v65
	v_cndmask_b32_e64 v32, v32, 0, s[78:79]
	v_exp_f32_e32 v36, v36
	v_sub_f32_e32 v37, v37, v64
	v_add_f32_e32 v65, v32, v65
	v_cndmask_b32_e64 v33, v33, 0, s[80:81]
	v_exp_f32_e32 v37, v37
	v_sub_f32_e32 v38, v38, v64
	v_add_f32_e32 v65, v33, v65
	v_cndmask_b32_e64 v34, v34, 0, s[82:83]
	v_exp_f32_e32 v38, v38
	v_sub_f32_e32 v39, v39, v64
	v_add_f32_e32 v65, v34, v65
	v_cndmask_b32_e64 v35, v35, 0, s[84:85]
	v_exp_f32_e32 v39, v39
	v_sub_f32_e32 v40, v40, v64
	v_add_f32_e32 v65, v35, v65
	v_cndmask_b32_e64 v36, v36, 0, s[86:87]
	v_exp_f32_e32 v40, v40
	v_sub_f32_e32 v41, v41, v64
	v_add_f32_e32 v65, v36, v65
	v_cndmask_b32_e64 v37, v37, 0, s[88:89]
	v_exp_f32_e32 v41, v41
	v_sub_f32_e32 v42, v42, v64
	v_add_f32_e32 v65, v37, v65
	v_cndmask_b32_e64 v38, v38, 0, s[90:91]
	v_exp_f32_e32 v42, v42
	v_sub_f32_e32 v43, v43, v64
	v_add_f32_e32 v65, v38, v65
	v_cndmask_b32_e64 v39, v39, 0, s[92:93]
	v_exp_f32_e32 v43, v43
	v_sub_f32_e32 v44, v44, v64
	v_add_f32_e32 v65, v39, v65
	v_cndmask_b32_e64 v40, v40, 0, s[94:95]
	v_readlane_b32 s0, v252, 38
	v_exp_f32_e32 v44, v44
	v_sub_f32_e32 v45, v45, v64
	v_add_f32_e32 v65, v40, v65
	v_cndmask_b32_e64 v41, v41, 0, s[96:97]
	v_readlane_b32 s1, v252, 39
	v_exp_f32_e32 v45, v45
	v_sub_f32_e32 v46, v46, v64
	v_add_f32_e32 v65, v41, v65
	v_cndmask_b32_e64 v42, v42, 0, s[0:1]
	v_exp_f32_e32 v46, v46
	v_sub_f32_e32 v47, v47, v64
	v_add_f32_e32 v65, v42, v65
	v_cndmask_b32_e64 v43, v43, 0, s[4:5]
	v_exp_f32_e32 v47, v47
	v_sub_f32_e32 v16, v16, v64
	v_add_f32_e32 v65, v43, v65
	v_cndmask_b32_e64 v44, v44, 0, s[6:7]
	v_exp_f32_e32 v16, v16
	v_sub_f32_e32 v17, v17, v64
	v_add_f32_e32 v65, v44, v65
	v_cndmask_b32_e64 v45, v45, 0, s[2:3]
	v_exp_f32_e32 v17, v17
	v_sub_f32_e32 v18, v18, v64
	v_add_f32_e32 v65, v45, v65
	v_cndmask_b32_e64 v46, v46, 0, s[8:9]
	v_exp_f32_e32 v18, v18
	v_sub_f32_e32 v19, v19, v64
	v_sub_f32_e32 v1, v1, v64
	v_add_f32_e32 v65, v46, v65
	v_cndmask_b32_e64 v47, v47, 0, s[10:11]
	v_exp_f32_e32 v19, v19
	v_sub_f32_e32 v20, v20, v64
	v_exp_f32_e32 v1, v1
	v_add_f32_e32 v65, v47, v65
	v_cndmask_b32_e64 v16, v16, 0, s[12:13]
	v_exp_f32_e32 v20, v20
	v_sub_f32_e32 v21, v21, v64
	v_sub_f32_e32 v2, v2, v64
	v_add_f32_e32 v65, v16, v65
	v_cndmask_b32_e64 v17, v17, 0, s[14:15]
	v_exp_f32_e32 v21, v21
	v_sub_f32_e32 v22, v22, v64
	v_readlane_b32 s0, v253, 8
	v_exp_f32_e32 v2, v2
	v_add_f32_e32 v65, v17, v65
	v_cndmask_b32_e64 v18, v18, 0, s[16:17]
	v_exp_f32_e32 v22, v22
	v_sub_f32_e32 v23, v23, v64
	v_readlane_b32 s1, v253, 9
	v_sub_f32_e32 v3, v3, v64
	v_add_f32_e32 v65, v18, v65
	v_cndmask_b32_e64 v19, v19, 0, s[18:19]
	v_exp_f32_e32 v23, v23
	v_sub_f32_e32 v24, v24, v64
	v_cndmask_b32_e64 v1, v1, 0, s[0:1]
	v_readlane_b32 s0, v253, 12
	v_exp_f32_e32 v3, v3
	v_add_f32_e32 v65, v19, v65
	v_cndmask_b32_e64 v20, v20, 0, s[20:21]
	v_exp_f32_e32 v24, v24
	v_sub_f32_e32 v25, v25, v64
	v_readlane_b32 s1, v253, 13
	v_sub_f32_e32 v4, v4, v64
	v_add_f32_e32 v65, v20, v65
	v_cndmask_b32_e64 v21, v21, 0, s[22:23]
	v_exp_f32_e32 v25, v25
	v_sub_f32_e32 v26, v26, v64
	v_cndmask_b32_e64 v2, v2, 0, s[0:1]
	v_readlane_b32 s0, v253, 30
	v_exp_f32_e32 v4, v4
	v_add_f32_e32 v65, v21, v65
	v_cndmask_b32_e64 v22, v22, 0, s[24:25]
	v_exp_f32_e32 v26, v26
	v_sub_f32_e32 v27, v27, v64
	v_readlane_b32 s1, v253, 31
	v_sub_f32_e32 v5, v5, v64
	v_add_f32_e32 v65, v22, v65
	v_cndmask_b32_e64 v23, v23, 0, s[26:27]
	v_exp_f32_e32 v27, v27
	v_sub_f32_e32 v28, v28, v64
	v_cndmask_b32_e64 v3, v3, 0, s[0:1]
	v_readlane_b32 s0, v253, 28
	v_exp_f32_e32 v5, v5
	v_add_f32_e32 v65, v23, v65
	v_cndmask_b32_e64 v24, v24, 0, s[28:29]
	v_exp_f32_e32 v28, v28
	v_sub_f32_e32 v29, v29, v64
	v_readlane_b32 s1, v253, 29
	v_sub_f32_e32 v6, v6, v64
	v_add_f32_e32 v65, v24, v65
	v_cndmask_b32_e64 v25, v25, 0, s[30:31]
	v_exp_f32_e32 v29, v29
	v_sub_f32_e32 v30, v30, v64
	v_cndmask_b32_e64 v66, v4, 0, s[0:1]
	v_readlane_b32 s0, v252, 54
	v_exp_f32_e32 v6, v6
	v_add_f32_e32 v65, v25, v65
	v_cndmask_b32_e64 v26, v26, 0, s[34:35]
	v_exp_f32_e32 v30, v30
	v_sub_f32_e32 v31, v31, v64
	v_readlane_b32 s1, v252, 55
	v_sub_f32_e32 v7, v7, v64
	v_add_f32_e32 v65, v26, v65
	v_cndmask_b32_e64 v27, v27, 0, s[36:37]
	v_exp_f32_e32 v31, v31
	v_sub_f32_e32 v0, v0, v64
	v_cndmask_b32_e64 v5, v5, 0, s[0:1]
	v_readlane_b32 s0, v253, 14
	v_exp_f32_e32 v7, v7
	v_add_f32_e32 v65, v27, v65
	v_cndmask_b32_e64 v28, v28, 0, s[38:39]
	v_exp_f32_e32 v0, v0
	v_readlane_b32 s1, v253, 15
	v_sub_f32_e32 v8, v8, v64
	v_add_f32_e32 v65, v28, v65
	v_cndmask_b32_e64 v29, v29, 0, s[66:67]
	v_cndmask_b32_e64 v6, v6, 0, s[0:1]
	v_readlane_b32 s0, v252, 58
	v_exp_f32_e32 v8, v8
	v_add_f32_e32 v65, v29, v65
	v_cndmask_b32_e64 v30, v30, 0, s[76:77]
	v_readlane_b32 s1, v252, 59
	v_sub_f32_e32 v9, v9, v64
	v_add_f32_e32 v65, v30, v65
	v_cndmask_b32_e64 v31, v31, 0, s[64:65]
	v_cndmask_b32_e64 v7, v7, 0, s[0:1]
	v_readlane_b32 s0, v252, 56
	v_exp_f32_e32 v9, v9
	v_add_f32_e32 v65, v31, v65
	v_cndmask_b32_e64 v0, v0, 0, s[46:47]
	v_readlane_b32 s1, v252, 57
	v_sub_f32_e32 v10, v10, v64
	v_add_f32_e32 v65, v0, v65
	v_cndmask_b32_e64 v8, v8, 0, s[0:1]
	v_readlane_b32 s0, v252, 16
	v_exp_f32_e32 v10, v10
	v_add_f32_e32 v65, v1, v65
	v_readlane_b32 s1, v252, 17
	v_sub_f32_e32 v11, v11, v64
	v_add_f32_e32 v65, v2, v65
	v_cndmask_b32_e64 v9, v9, 0, s[0:1]
	v_readlane_b32 s0, v253, 24
	v_exp_f32_e32 v11, v11
	v_add_f32_e32 v65, v3, v65
	v_readlane_b32 s1, v253, 25
	v_sub_f32_e32 v12, v12, v64
	v_add_f32_e32 v4, v66, v65
	v_cndmask_b32_e64 v10, v10, 0, s[0:1]
	v_readlane_b32 s0, v253, 4
	v_exp_f32_e32 v12, v12
	v_add_f32_e32 v4, v5, v4
	v_readlane_b32 s1, v253, 5
	v_sub_f32_e32 v13, v13, v64
	v_add_f32_e32 v4, v6, v4
	v_cndmask_b32_e64 v11, v11, 0, s[0:1]
	v_readlane_b32 s0, v252, 18
	v_exp_f32_e32 v13, v13
	v_add_f32_e32 v4, v7, v4
	v_readlane_b32 s1, v252, 19
	v_sub_f32_e32 v14, v14, v64
	v_add_f32_e32 v4, v8, v4
	v_cndmask_b32_e64 v12, v12, 0, s[0:1]
	v_readlane_b32 s0, v255, 47
	v_exp_f32_e32 v14, v14
	v_add_f32_e32 v4, v9, v4
	v_readlane_b32 s1, v255, 48
	v_sub_f32_e32 v15, v15, v64
	v_add_f32_e32 v4, v10, v4
	v_cndmask_b32_e64 v13, v13, 0, s[0:1]
	v_readlane_b32 s0, v255, 49
	v_exp_f32_e32 v15, v15
	v_add_f32_e32 v4, v11, v4
	v_readlane_b32 s1, v255, 50
	v_add_f32_e32 v4, v12, v4
	v_add_f32_e32 v4, v13, v4
	v_cndmask_b32_e64 v14, v14, 0, s[0:1]
	v_readlane_b32 s0, v255, 51
	v_readlane_b32 s1, v255, 52
	v_add_f32_e32 v4, v14, v4
	v_readlane_b32 s76, v254, 6
	v_cndmask_b32_e64 v15, v15, 0, s[0:1]
	v_add_f32_e32 v4, v15, v4
	v_mov_b32_e32 v64, v4
	s_nop 1
	v_permlane32_swap_b32_e32 v4, v64
	v_add_f32_e32 v4, v4, v64
	v_div_scale_f32 v64, vcc, v4, v4, 1.0
	v_rcp_f32_e32 v65, v64
	v_cmp_lt_f32_e64 s[40:41], 0, v4
	v_readlane_b32 s4, v255, 53
	v_readlane_b32 s77, v254, 7
	v_fma_f32 v67, -v64, v65, 1.0
	v_fmac_f32_e32 v65, v67, v65
	v_div_scale_f32 v67, vcc, 1.0, v4, 1.0
	v_mul_f32_e32 v68, v67, v65
	v_fma_f32 v69, -v64, v68, v67
	v_fmac_f32_e32 v68, v69, v65
	v_fma_f32 v64, -v64, v68, v67
	v_div_fmas_f32 v64, v64, v65, v68
	v_div_fixup_f32 v4, v64, v4, 1.0
	v_cndmask_b32_e64 v64, 0, v4, s[40:41]
	v_mul_f32_e32 v53, v64, v53
	v_mul_f32_e32 v129, v64, v1
	v_fma_f32 v1, v64, v52, v53
	v_fmac_f32_e32 v1, v64, v54
	v_mul_f32_e32 v57, v64, v57
	v_fmac_f32_e32 v1, v64, v55
	v_add_f32_e32 v232, v232, v1
	v_fma_f32 v1, v64, v56, v57
	v_fmac_f32_e32 v1, v64, v58
	v_mul_f32_e32 v61, v64, v61
	v_fmac_f32_e32 v1, v64, v59
	v_add_f32_e32 v231, v231, v1
	v_fma_f32 v1, v64, v60, v61
	v_fmac_f32_e32 v1, v64, v62
	v_mul_f32_e32 v33, v64, v33
	v_fmac_f32_e32 v1, v64, v63
	v_add_f32_e32 v229, v229, v1
	v_fma_f32 v1, v64, v32, v33
	v_fmac_f32_e32 v1, v64, v34
	v_mul_f32_e32 v37, v64, v37
	v_fmac_f32_e32 v1, v64, v35
	v_add_f32_e32 v227, v227, v1
	v_fma_f32 v1, v64, v36, v37
	v_fmac_f32_e32 v1, v64, v38
	v_mul_f32_e32 v41, v64, v41
	v_fmac_f32_e32 v1, v64, v39
	v_add_f32_e32 v225, v225, v1
	v_fma_f32 v1, v64, v40, v41
	v_fmac_f32_e32 v1, v64, v42
	v_mul_f32_e32 v45, v64, v45
	v_fmac_f32_e32 v1, v64, v43
	v_add_f32_e32 v223, v223, v1
	v_fma_f32 v1, v64, v44, v45
	v_fmac_f32_e32 v1, v64, v46
	v_mul_f32_e32 v17, v64, v17
	v_fmac_f32_e32 v1, v64, v47
	v_add_f32_e32 v222, v222, v1
	v_fma_f32 v1, v64, v16, v17
	v_fmac_f32_e32 v1, v64, v18
	v_mul_f32_e32 v21, v64, v21
	v_fmac_f32_e32 v1, v64, v19
	v_add_f32_e32 v219, v219, v1
	v_fma_f32 v1, v64, v20, v21
	v_fmac_f32_e32 v1, v64, v22
	v_mul_f32_e32 v25, v64, v25
	v_fmac_f32_e32 v1, v64, v23
	v_add_f32_e32 v217, v217, v1
	v_fma_f32 v1, v64, v24, v25
	v_mul_f32_e32 v128, v64, v0
	v_fmac_f32_e32 v1, v64, v26
	v_fma_f32 v0, v64, v0, v129
	v_mul_f32_e32 v49, v64, v49
	v_mul_f32_e32 v29, v64, v29
	v_fmac_f32_e32 v1, v64, v27
	v_fmac_f32_e32 v0, v64, v2
	v_mul_f32_e32 v133, v64, v5
	v_fma_f32 v5, v64, v48, v49
	v_add_f32_e32 v215, v215, v1
	v_fma_f32 v1, v64, v28, v29
	v_fmac_f32_e32 v0, v64, v3
	v_fmac_f32_e32 v5, v64, v50
	v_fmac_f32_e32 v1, v64, v30
	v_add_f32_e32 v211, v211, v0
	v_fma_f32 v0, v64, v66, v133
	v_mul_f32_e32 v67, v64, v50
	v_mul_f32_e32 v68, v64, v51
	v_mul_f32_e32 v76, v64, v62
	v_mul_f32_e32 v77, v64, v63
	v_mul_f32_e32 v91, v64, v18
	v_mul_f32_e32 v92, v64, v19
	v_mul_f32_e32 v140, v64, v14
	v_mul_f32_e32 v4, v64, v15
	v_fmac_f32_e32 v5, v64, v51
	v_fmac_f32_e32 v1, v64, v31
	v_fmac_f32_e32 v0, v64, v6
	v_mul_f32_e32 v134, v64, v6
	v_mul_f32_e32 v135, v64, v7
	v_add_f32_e32 v213, v213, v1
	v_fmac_f32_e32 v0, v64, v7
	v_fmac_f32_e32 v203, v64, v7
	v_pk_add_f32 v[118:119], v[118:119], v[4:5]
	v_cvt_pk_bf16_f32 v1, v67, v68
	v_cvt_pk_bf16_f32 v67, v76, v77
	v_cvt_pk_bf16_f32 v77, v91, v92
	v_cvt_pk_bf16_f32 v91, v140, v4
	ds_read_b128 v[4:7], v202 offset:34816
	v_mul_f32_e32 v9, v64, v9
	v_add_f32_e32 v209, v209, v0
	v_fma_f32 v0, v64, v8, v9
	v_fmac_f32_e32 v0, v64, v10
	v_mul_f32_e32 v13, v64, v13
	v_fmac_f32_e32 v0, v64, v11
	v_add_f32_e32 v207, v207, v0
	v_fma_f32 v0, v64, v12, v13
	v_fmac_f32_e32 v0, v64, v14
	v_mul_f32_e32 v65, v64, v48
	v_mul_f32_e32 v69, v64, v52
	v_mul_f32_e32 v70, v64, v54
	v_mul_f32_e32 v71, v64, v55
	v_mul_f32_e32 v78, v64, v32
	v_mul_f32_e32 v79, v64, v34
	v_mul_f32_e32 v80, v64, v35
	v_mul_f32_e32 v93, v64, v20
	v_mul_f32_e32 v94, v64, v22
	v_mul_f32_e32 v95, v64, v23
	v_fmac_f32_e32 v0, v64, v15
	v_mul_f32_e32 v72, v64, v56
	v_mul_f32_e32 v75, v64, v60
	v_mul_f32_e32 v130, v64, v2
	v_mul_f32_e32 v131, v64, v3
	v_fmac_f32_e32 v204, v64, v3
	v_add_f32_e32 v205, v205, v0
	v_cvt_pk_bf16_f32 v0, v65, v49
	v_cvt_pk_bf16_f32 v2, v69, v53
	v_cvt_pk_bf16_f32 v3, v70, v71
	v_cvt_pk_bf16_f32 v68, v78, v33
	v_cvt_pk_bf16_f32 v69, v79, v80
	v_cvt_pk_bf16_f32 v78, v93, v21
	v_cvt_pk_bf16_f32 v79, v94, v95
	ds_read_b128 v[92:95], v202 offset:34848
	v_mul_f32_e32 v73, v64, v58
	v_mul_f32_e32 v74, v64, v59
	v_mul_f32_e32 v81, v64, v36
	v_mul_f32_e32 v82, v64, v38
	v_mul_f32_e32 v83, v64, v39
	v_mul_f32_e32 v84, v64, v40
	v_mul_f32_e32 v85, v64, v42
	v_mul_f32_e32 v86, v64, v43
	v_mul_f32_e32 v87, v64, v44
	v_mul_f32_e32 v88, v64, v46
	v_mul_f32_e32 v89, v64, v47
	v_mul_f32_e32 v90, v64, v16
	v_mul_f32_e32 v122, v64, v24
	v_mul_f32_e32 v123, v64, v26
	v_mul_f32_e32 v124, v64, v27
	v_mul_f32_e32 v125, v64, v28
	v_mul_f32_e32 v126, v64, v30
	v_mul_f32_e32 v127, v64, v31
	v_mul_f32_e32 v132, v64, v66
	v_mul_f32_e32 v136, v64, v8
	v_mul_f32_e32 v137, v64, v10
	v_mul_f32_e32 v138, v64, v11
	v_mul_f32_e32 v139, v64, v12
	v_fmac_f32_e32 v230, v64, v51
	v_fmac_f32_e32 v226, v64, v55
	v_fmac_f32_e32 v224, v64, v59
	v_fmac_f32_e32 v221, v64, v63
	v_fmac_f32_e32 v220, v64, v35
	v_fmac_f32_e32 v218, v64, v39
	v_fmac_f32_e32 v216, v64, v43
	v_fmac_f32_e32 v214, v64, v47
	v_fmac_f32_e32 v212, v64, v19
	v_fmac_f32_e32 v210, v64, v23
	v_fmac_f32_e32 v208, v64, v27
	v_fmac_f32_e32 v206, v64, v31
	v_fmac_f32_e32 v96, v64, v11
	v_cvt_pk_bf16_f32 v64, v72, v57
	v_cvt_pk_bf16_f32 v66, v75, v61
	s_waitcnt lgkmcnt(1)
	v_mfma_f32_32x32x16_bf16 v[48:63], v[4:7], v[0:3], 0
	ds_read_b128 v[4:7], v202 offset:43520
	v_cvt_pk_bf16_f32 v65, v73, v74
	v_cvt_pk_bf16_f32 v70, v81, v37
	v_cvt_pk_bf16_f32 v72, v84, v41
	v_cvt_pk_bf16_f32 v74, v87, v45
	v_cvt_pk_bf16_f32 v71, v82, v83
	v_cvt_pk_bf16_f32 v76, v90, v17
	s_waitcnt lgkmcnt(1)
	v_mfma_f32_32x32x16_bf16 v[48:63], v[92:95], v[64:67], v[48:63]
	ds_read_b128 v[92:95], v202 offset:43552
	v_cvt_pk_bf16_f32 v80, v122, v25
	v_cvt_pk_bf16_f32 v82, v125, v29
	v_cvt_pk_bf16_f32 v75, v88, v89
	v_cvt_pk_bf16_f32 v88, v136, v9
	v_cvt_pk_bf16_f32 v90, v139, v13
	v_cvt_pk_bf16_f32 v73, v85, v86
	s_waitcnt lgkmcnt(1)
	v_mfma_f32_32x32x16_bf16 v[32:47], v[4:7], v[0:3], 0
	ds_read_b128 v[4:7], v202 offset:52224
	v_cvt_pk_bf16_f32 v81, v123, v124
	v_cvt_pk_bf16_f32 v83, v126, v127
	v_cvt_pk_bf16_f32 v84, v128, v129
	v_cvt_pk_bf16_f32 v85, v130, v131
	v_cvt_pk_bf16_f32 v86, v132, v133
	v_cvt_pk_bf16_f32 v87, v134, v135
	s_waitcnt lgkmcnt(1)
	v_mfma_f32_32x32x16_bf16 v[32:47], v[92:95], v[64:67], v[32:47]
	ds_read_b128 v[92:95], v202 offset:52256
	v_cvt_pk_bf16_f32 v89, v137, v138
	v_readlane_b32 s2, v254, 9
	v_readlane_b32 s5, v255, 54
	s_add_u32 s40, s2, s4
	v_readlane_b32 s2, v254, 10
	s_addc_u32 s41, s2, s5
	s_waitcnt lgkmcnt(1)
	v_mfma_f32_32x32x16_bf16 v[16:31], v[4:7], v[0:3], 0
	ds_read_b128 v[4:7], v202 offset:60928
	s_add_u32 s4, s4, 12
	s_mov_b64 s[6:7], 0x100
	s_addc_u32 s5, s5, 0
	v_lshl_add_u64 v[106:107], v[106:107], 0, s[6:7]
	v_lshl_add_u64 v[108:109], v[108:109], 0, s[6:7]
	v_lshl_add_u64 v[110:111], v[110:111], 0, s[6:7]
	s_waitcnt lgkmcnt(1)
	v_mfma_f32_32x32x16_bf16 v[16:31], v[92:95], v[64:67], v[16:31]
	ds_read_b128 v[92:95], v202 offset:60960
	v_lshl_add_u64 v[112:113], v[112:113], 0, s[6:7]
	v_lshl_add_u64 v[114:115], v[114:115], 0, s[6:7]
	s_cmp_eq_u32 s4, 36
	s_waitcnt lgkmcnt(1)
	v_mfma_f32_32x32x16_bf16 v[0:15], v[4:7], v[0:3], 0
	s_waitcnt lgkmcnt(0)
	v_mfma_f32_32x32x16_bf16 v[0:15], v[92:95], v[64:67], v[0:15]
	ds_read_b128 v[64:67], v202 offset:34880
	s_waitcnt lgkmcnt(0)
	v_mfma_f32_32x32x16_bf16 v[48:63], v[64:67], v[68:71], v[48:63]
	ds_read_b128 v[64:67], v202 offset:43584
	s_waitcnt lgkmcnt(0)
	v_mfma_f32_32x32x16_bf16 v[32:47], v[64:67], v[68:71], v[32:47]
	ds_read_b128 v[64:67], v202 offset:52288
	s_waitcnt lgkmcnt(0)
	v_mfma_f32_32x32x16_bf16 v[16:31], v[64:67], v[68:71], v[16:31]
	ds_read_b128 v[64:67], v202 offset:60992
	s_waitcnt lgkmcnt(0)
	v_mfma_f32_32x32x16_bf16 v[0:15], v[64:67], v[68:71], v[0:15]
	ds_read_b128 v[64:67], v202 offset:34912
	s_waitcnt lgkmcnt(0)
	v_mfma_f32_32x32x16_bf16 v[48:63], v[64:67], v[72:75], v[48:63]
	ds_read_b128 v[64:67], v202 offset:43616
	s_waitcnt lgkmcnt(0)
	v_mfma_f32_32x32x16_bf16 v[32:47], v[64:67], v[72:75], v[32:47]
	ds_read_b128 v[64:67], v202 offset:52320
	s_waitcnt lgkmcnt(0)
	v_mfma_f32_32x32x16_bf16 v[16:31], v[64:67], v[72:75], v[16:31]
	ds_read_b128 v[64:67], v202 offset:61024
	s_waitcnt lgkmcnt(0)
	v_mfma_f32_32x32x16_bf16 v[0:15], v[64:67], v[72:75], v[0:15]
	ds_read_b128 v[64:67], v202 offset:34944
	s_waitcnt lgkmcnt(0)
	v_mfma_f32_32x32x16_bf16 v[48:63], v[64:67], v[76:79], v[48:63]
	ds_read_b128 v[64:67], v202 offset:43648
	s_waitcnt lgkmcnt(0)
	v_mfma_f32_32x32x16_bf16 v[32:47], v[64:67], v[76:79], v[32:47]
	ds_read_b128 v[64:67], v202 offset:52352
	s_waitcnt lgkmcnt(0)
	v_mfma_f32_32x32x16_bf16 v[16:31], v[64:67], v[76:79], v[16:31]
	ds_read_b128 v[64:67], v202 offset:61056
	s_waitcnt lgkmcnt(0)
	v_mfma_f32_32x32x16_bf16 v[0:15], v[64:67], v[76:79], v[0:15]
	ds_read_b128 v[64:67], v202 offset:34976
	s_waitcnt lgkmcnt(0)
	v_mfma_f32_32x32x16_bf16 v[48:63], v[64:67], v[80:83], v[48:63]
	ds_read_b128 v[64:67], v202 offset:43680
	s_waitcnt lgkmcnt(0)
	v_mfma_f32_32x32x16_bf16 v[32:47], v[64:67], v[80:83], v[32:47]
	ds_read_b128 v[64:67], v202 offset:52384
	s_waitcnt lgkmcnt(0)
	v_mfma_f32_32x32x16_bf16 v[16:31], v[64:67], v[80:83], v[16:31]
	ds_read_b128 v[64:67], v202 offset:61088
	s_waitcnt lgkmcnt(0)
	v_mfma_f32_32x32x16_bf16 v[0:15], v[64:67], v[80:83], v[0:15]
	ds_read_b128 v[64:67], v202 offset:35008
	s_waitcnt lgkmcnt(0)
	v_mfma_f32_32x32x16_bf16 v[48:63], v[64:67], v[84:87], v[48:63]
	ds_read_b128 v[64:67], v202 offset:43712
	s_waitcnt lgkmcnt(0)
	v_mfma_f32_32x32x16_bf16 v[32:47], v[64:67], v[84:87], v[32:47]
	ds_read_b128 v[64:67], v202 offset:52416
	s_waitcnt lgkmcnt(0)
	v_mfma_f32_32x32x16_bf16 v[16:31], v[64:67], v[84:87], v[16:31]
	ds_read_b128 v[64:67], v202 offset:61120
	s_waitcnt lgkmcnt(0)
	v_mfma_f32_32x32x16_bf16 v[0:15], v[64:67], v[84:87], v[0:15]
	ds_read_b128 v[64:67], v202 offset:35040
	s_waitcnt lgkmcnt(0)
	v_mfma_f32_32x32x16_bf16 v[48:63], v[64:67], v[88:91], v[48:63]
	ds_read_b128 v[64:67], v202 offset:43744
	s_waitcnt lgkmcnt(0)
	v_mfma_f32_32x32x16_bf16 v[32:47], v[64:67], v[88:91], v[32:47]
	ds_read_b128 v[64:67], v202 offset:52448
	s_waitcnt lgkmcnt(0)
	v_mfma_f32_32x32x16_bf16 v[16:31], v[64:67], v[88:91], v[16:31]
	ds_read_b128 v[64:67], v202 offset:61152
	s_waitcnt lgkmcnt(0)
	v_mfma_f32_32x32x16_bf16 v[0:15], v[64:67], v[88:91], v[0:15]
	v_lshl_add_u64 v[64:65], s[76:77], 0, v[104:105]
	global_load_ushort v64, v[64:65], off
	v_lshl_add_u64 v[104:105], v[104:105], 0, 6
	global_load_dword v65, v97, s[40:41]
	s_waitcnt vmcnt(1)
	v_lshlrev_b32_e32 v64, 16, v64
	s_waitcnt vmcnt(0)
	v_add_f32_e32 v64, v65, v64
	v_mul_f32_e32 v64, 0xbfb8aa3b, v64
	v_exp_f32_e32 v64, v64
	s_nop 0
	v_add_f32_e32 v64, 1.0, v64
	v_div_scale_f32 v65, s[40:41], v64, v64, 1.0
	v_rcp_f32_e32 v66, v65
	s_mov_b32 s40, 0x12014000
	v_fma_f32 v67, -v65, v66, 1.0
	v_fmac_f32_e32 v66, v67, v66
	v_div_scale_f32 v67, vcc, 1.0, v64, 1.0
	v_mul_f32_e32 v68, v67, v66
	v_fma_f32 v69, -v65, v68, v67
	v_fmac_f32_e32 v68, v69, v66
	v_fma_f32 v65, -v65, v68, v67
	v_div_fmas_f32 v65, v65, v66, v68
	v_div_fixup_f32 v64, v65, v64, 1.0
	v_pk_mul_f32 v[48:49], v[48:49], v[64:65] op_sel_hi:[1,0]
	v_pk_mul_f32 v[50:51], v[50:51], v[64:65] op_sel_hi:[1,0]
	v_pk_mul_f32 v[32:33], v[32:33], v[64:65] op_sel_hi:[1,0]
	v_pk_mul_f32 v[34:35], v[34:35], v[64:65] op_sel_hi:[1,0]
	v_pk_mul_f32 v[16:17], v[16:17], v[64:65] op_sel_hi:[1,0]
	v_pk_mul_f32 v[18:19], v[18:19], v[64:65] op_sel_hi:[1,0]
	v_pk_mul_f32 v[0:1], v[0:1], v[64:65] op_sel_hi:[1,0]
	v_pk_mul_f32 v[2:3], v[2:3], v[64:65] op_sel_hi:[1,0]
	v_cvt_pk_bf16_f32 v48, v48, v49
	v_cvt_pk_bf16_f32 v49, v50, v51
	v_pk_mul_f32 v[50:51], v[52:53], v[64:65] op_sel_hi:[1,0]
	v_pk_mul_f32 v[52:53], v[54:55], v[64:65] op_sel_hi:[1,0]
	v_cvt_pk_bf16_f32 v32, v32, v33
	v_cvt_pk_bf16_f32 v33, v34, v35
	v_pk_mul_f32 v[34:35], v[36:37], v[64:65] op_sel_hi:[1,0]
	v_pk_mul_f32 v[36:37], v[38:39], v[64:65] op_sel_hi:[1,0]
	v_cvt_pk_bf16_f32 v16, v16, v17
	v_cvt_pk_bf16_f32 v17, v18, v19
	v_pk_mul_f32 v[18:19], v[20:21], v[64:65] op_sel_hi:[1,0]
	v_pk_mul_f32 v[20:21], v[22:23], v[64:65] op_sel_hi:[1,0]
	v_cvt_pk_bf16_f32 v0, v0, v1
	v_cvt_pk_bf16_f32 v1, v2, v3
	v_pk_mul_f32 v[2:3], v[4:5], v[64:65] op_sel_hi:[1,0]
	v_pk_mul_f32 v[4:5], v[6:7], v[64:65] op_sel_hi:[1,0]
	v_cvt_pk_bf16_f32 v50, v50, v51
	v_cvt_pk_bf16_f32 v51, v52, v53
	v_cvt_pk_bf16_f32 v34, v34, v35
	v_cvt_pk_bf16_f32 v35, v36, v37
	v_cvt_pk_bf16_f32 v18, v18, v19
	v_cvt_pk_bf16_f32 v19, v20, v21
	v_cvt_pk_bf16_f32 v2, v2, v3
	v_cvt_pk_bf16_f32 v3, v4, v5
	ds_write2_b64 v228, v[48:49], v[50:51] offset1:2
	v_pk_mul_f32 v[48:49], v[56:57], v[64:65] op_sel_hi:[1,0]
	v_pk_mul_f32 v[50:51], v[58:59], v[64:65] op_sel_hi:[1,0]
	ds_write2_b64 v228, v[32:33], v[34:35] offset0:8 offset1:10
	v_pk_mul_f32 v[32:33], v[40:41], v[64:65] op_sel_hi:[1,0]
	v_pk_mul_f32 v[34:35], v[42:43], v[64:65] op_sel_hi:[1,0]
	ds_write2_b64 v228, v[16:17], v[18:19] offset0:16 offset1:18
	v_pk_mul_f32 v[16:17], v[24:25], v[64:65] op_sel_hi:[1,0]
	v_pk_mul_f32 v[18:19], v[26:27], v[64:65] op_sel_hi:[1,0]
	ds_write2_b64 v228, v[0:1], v[2:3] offset0:24 offset1:26
	v_pk_mul_f32 v[0:1], v[8:9], v[64:65] op_sel_hi:[1,0]
	v_pk_mul_f32 v[2:3], v[10:11], v[64:65] op_sel_hi:[1,0]
	v_cvt_pk_bf16_f32 v48, v48, v49
	v_cvt_pk_bf16_f32 v49, v50, v51
	v_pk_mul_f32 v[50:51], v[60:61], v[64:65] op_sel_hi:[1,0]
	v_pk_mul_f32 v[52:53], v[62:63], v[64:65] op_sel_hi:[1,0]
	v_cvt_pk_bf16_f32 v32, v32, v33
	v_cvt_pk_bf16_f32 v33, v34, v35
	v_pk_mul_f32 v[34:35], v[44:45], v[64:65] op_sel_hi:[1,0]
	v_pk_mul_f32 v[36:37], v[46:47], v[64:65] op_sel_hi:[1,0]
	v_cvt_pk_bf16_f32 v16, v16, v17
	v_cvt_pk_bf16_f32 v17, v18, v19
	v_pk_mul_f32 v[18:19], v[28:29], v[64:65] op_sel_hi:[1,0]
	v_pk_mul_f32 v[20:21], v[30:31], v[64:65] op_sel_hi:[1,0]
	v_cvt_pk_bf16_f32 v0, v0, v1
	v_cvt_pk_bf16_f32 v1, v2, v3
	v_pk_mul_f32 v[2:3], v[12:13], v[64:65] op_sel_hi:[1,0]
	v_pk_mul_f32 v[4:5], v[14:15], v[64:65] op_sel_hi:[1,0]
	v_cvt_pk_bf16_f32 v50, v50, v51
	v_cvt_pk_bf16_f32 v51, v52, v53
	v_cvt_pk_bf16_f32 v34, v34, v35
	v_cvt_pk_bf16_f32 v35, v36, v37
	v_cvt_pk_bf16_f32 v18, v18, v19
	v_cvt_pk_bf16_f32 v19, v20, v21
	v_cvt_pk_bf16_f32 v2, v2, v3
	v_cvt_pk_bf16_f32 v3, v4, v5
	ds_write2_b64 v228, v[48:49], v[50:51] offset0:4 offset1:6
	ds_write2_b64 v228, v[32:33], v[34:35] offset0:12 offset1:14
	ds_write2_b64 v228, v[16:17], v[18:19] offset0:20 offset1:22
	ds_write2_b64 v228, v[0:1], v[2:3] offset0:28 offset1:30
	ds_read_b128 v[0:3], v191
	v_lshl_add_u64 v[4:5], s[76:77], 0, v[116:117]
	v_lshl_add_u64 v[116:117], v[116:117], 0, s[6:7]
	s_waitcnt lgkmcnt(0)
	global_store_dwordx4 v[4:5], v[0:3], off
	ds_read_b128 v[2:5], v192
	s_nop 0
	v_lshl_add_u64 v[0:1], s[76:77], 0, v[120:121]
	v_add_co_u32_e32 v6, vcc, s33, v0
	s_mov_b32 s33, 0x12008000
	s_nop 0
	v_addc_co_u32_e32 v7, vcc, 0, v1, vcc
	s_waitcnt lgkmcnt(0)
	global_store_dwordx4 v[6:7], v[2:5], off
	ds_read_b128 v[2:5], v193
	v_add_co_u32_e32 v6, vcc, s33, v0
	s_mov_b32 s33, 0x1200c000
	s_nop 0
	v_addc_co_u32_e32 v7, vcc, 0, v1, vcc
	s_waitcnt lgkmcnt(0)
	global_store_dwordx4 v[6:7], v[2:5], off
	ds_read_b128 v[2:5], v195
	v_add_co_u32_e32 v6, vcc, s33, v0
	s_mov_b32 s33, 0x12010000
	s_nop 0
	v_addc_co_u32_e32 v7, vcc, 0, v1, vcc
	s_waitcnt lgkmcnt(0)
	global_store_dwordx4 v[6:7], v[2:5], off
	ds_read_b128 v[2:5], v196
	v_add_co_u32_e32 v6, vcc, s33, v0
	s_mov_b32 s33, 0x12018000
	s_nop 0
	v_addc_co_u32_e32 v7, vcc, 0, v1, vcc
	s_waitcnt lgkmcnt(0)
	global_store_dwordx4 v[6:7], v[2:5], off
	ds_read_b128 v[2:5], v197
	v_add_co_u32_e32 v6, vcc, s40, v0
	v_lshl_add_u64 v[120:121], v[120:121], 0, s[6:7]
	s_nop 0
	v_addc_co_u32_e32 v7, vcc, 0, v1, vcc
	s_waitcnt lgkmcnt(0)
	global_store_dwordx4 v[6:7], v[2:5], off
	ds_read_b128 v[2:5], v198
	v_add_co_u32_e32 v6, vcc, s33, v0
	s_mov_b32 s33, 0x1201c000
	s_nop 0
	v_addc_co_u32_e32 v7, vcc, 0, v1, vcc
	s_waitcnt lgkmcnt(0)
	global_store_dwordx4 v[6:7], v[2:5], off
	s_nop 1
	v_add_co_u32_e32 v4, vcc, s33, v0
	s_nop 1
	v_addc_co_u32_e32 v5, vcc, 0, v1, vcc
	ds_read_b128 v[0:3], v199
	s_waitcnt lgkmcnt(0)
	global_store_dwordx4 v[4:5], v[0:3], off
	s_cbranch_scc0 .LBB0_943
	v_mov_b32_e32 v16, v118
	v_mov_b32_e32 v0, v230
	s_nop 0
	v_permlane32_swap_b32_e32 v118, v16
	v_readlane_b32 s65, v254, 5
	v_permlane32_swap_b32_e32 v230, v0
	v_cmp_gt_u32_e32 vcc, 32, v190
	v_mov_b32_e32 v2, v226
	v_or_b32_e32 v16, s65, v101
	s_movk_i32 s0, 0x84
	v_cndmask_b32_e32 v1, v230, v0, vcc
	v_permlane32_swap_b32_e32 v226, v2
	v_mov_b32_e32 v3, v224
	v_mov_b32_e32 v4, v221
	v_mov_b32_e32 v5, v220
	v_mov_b32_e32 v6, v218
	v_mov_b32_e32 v7, v216
	v_mov_b32_e32 v8, v214
	v_mov_b32_e32 v9, v212
	v_mov_b32_e32 v10, v210
	v_mov_b32_e32 v11, v208
	v_mov_b32_e32 v12, v206
	v_mov_b32_e32 v13, v204
	v_mov_b32_e32 v14, v203
	v_mov_b32_e32 v15, v96
	v_mul_lo_u32 v16, v16, s0
	v_cndmask_b32_e64 v1, v1, 0, vcc
	v_cndmask_b32_e32 v0, v226, v0, vcc
	v_permlane32_swap_b32_e32 v224, v3
	v_permlane32_swap_b32_e32 v221, v4
	v_permlane32_swap_b32_e32 v220, v5
	v_permlane32_swap_b32_e32 v218, v6
	v_permlane32_swap_b32_e32 v216, v7
	v_permlane32_swap_b32_e32 v214, v8
	v_permlane32_swap_b32_e32 v212, v9
	v_permlane32_swap_b32_e32 v210, v10
	v_permlane32_swap_b32_e32 v208, v11
	v_permlane32_swap_b32_e32 v206, v12
	v_permlane32_swap_b32_e32 v204, v13
	v_permlane32_swap_b32_e32 v203, v14
	v_permlane32_swap_b32_e32 v96, v15
	v_add_u32_e32 v24, 0, v16
	v_add_f32_e32 v1, v119, v1
	v_add_f32_e32 v0, v232, v0
	v_cndmask_b32_e32 v2, v224, v2, vcc
	v_cndmask_b32_e32 v3, v221, v3, vcc
	v_cndmask_b32_e32 v4, v220, v4, vcc
	v_cndmask_b32_e32 v5, v218, v5, vcc
	v_cndmask_b32_e32 v6, v216, v6, vcc
	v_cndmask_b32_e32 v7, v214, v7, vcc
	v_cndmask_b32_e32 v8, v212, v8, vcc
	v_cndmask_b32_e32 v9, v210, v9, vcc
	v_cndmask_b32_e32 v10, v208, v10, vcc
	v_cndmask_b32_e32 v11, v206, v11, vcc
	v_cndmask_b32_e32 v12, v204, v12, vcc
	v_cndmask_b32_e32 v13, v203, v13, vcc
	v_cndmask_b32_e32 v14, v96, v14, vcc
	v_cndmask_b32_e32 v15, v118, v15, vcc
	v_lshl_add_u32 v16, v189, 2, v24
	v_add_f32_e32 v2, v231, v2
	v_add_f32_e32 v3, v229, v3
	v_add_f32_e32 v4, v227, v4
	v_add_f32_e32 v5, v225, v5
	v_add_f32_e32 v6, v223, v6
	v_add_f32_e32 v7, v222, v7
	v_add_f32_e32 v8, v219, v8
	v_add_f32_e32 v9, v217, v9
	v_add_f32_e32 v10, v215, v10
	v_add_f32_e32 v11, v213, v11
	v_add_f32_e32 v12, v211, v12
	v_add_f32_e32 v13, v209, v13
	v_add_f32_e32 v14, v207, v14
	v_add_f32_e32 v15, v205, v15
	s_barrier
	ds_write2_b32 v16, v1, v0 offset1:2
	ds_write2_b32 v16, v2, v3 offset0:4 offset1:6
	ds_write2_b32 v16, v4, v5 offset0:8 offset1:10
	ds_write2_b32 v16, v6, v7 offset0:12 offset1:14
	ds_write2_b32 v16, v8, v9 offset0:16 offset1:18
	ds_write2_b32 v16, v10, v11 offset0:20 offset1:22
	ds_write2_b32 v16, v12, v13 offset0:24 offset1:26
	ds_write2_b32 v16, v14, v15 offset0:28 offset1:30
	s_waitcnt lgkmcnt(0)
	s_barrier
	s_and_saveexec_b64 s[68:69], vcc
	s_cbranch_execz .LBB0_941
	v_readlane_b32 s63, v254, 14
	s_lshr_b32 s33, s63, 6
	s_add_i32 s0, s33, -1
	s_cmp_lt_u32 s63, 64
	s_cselect_b64 s[10:11], -1, 0
	s_cmp_gt_u32 s0, 1
	ds_read2_b32 v[0:1], v24 offset0:1 offset1:2
	ds_read2_b32 v[4:5], v24 offset0:3 offset1:4
	ds_read2_b32 v[6:7], v24 offset0:5 offset1:6
	ds_read2_b32 v[8:9], v24 offset0:7 offset1:8
	s_cselect_b64 vcc, -1, 0
	s_and_b32 s62, s63, 0x7fffff80
	s_cmpk_lt_u32 s63, 0x80
	s_waitcnt lgkmcnt(3)
	v_cndmask_b32_e64 v0, v0, v163, s[10:11]
	s_cselect_b64 s[6:7], -1, 0
	s_cmpk_lg_i32 s62, 0x80
	v_cndmask_b32_e32 v2, v164, v0, vcc
	s_cselect_b64 vcc, -1, 0
	s_add_i32 s0, s33, -3
	s_cmpk_lt_u32 s63, 0xc0
	v_cndmask_b32_e64 v0, v1, v163, s[6:7]
	s_cselect_b64 s[4:5], -1, 0
	s_cmp_gt_u32 s0, 1
	v_cndmask_b32_e32 v3, v164, v0, vcc
	s_cselect_b64 vcc, -1, 0
	s_cmpk_lt_u32 s63, 0x100
	s_waitcnt lgkmcnt(2)
	v_cndmask_b32_e64 v0, v4, v163, s[4:5]
	s_cselect_b64 s[2:3], -1, 0
	s_cmpk_lg_i32 s62, 0x100
	v_cndmask_b32_e32 v4, v164, v0, vcc
	s_cselect_b64 vcc, -1, 0
	s_add_i32 s8, s33, -5
	s_cmpk_lt_u32 s63, 0x140
	v_cndmask_b32_e64 v0, v5, v163, s[2:3]
	s_cselect_b64 s[0:1], -1, 0
	s_cmp_gt_u32 s8, 1
	v_cndmask_b32_e32 v5, v164, v0, vcc
	s_waitcnt lgkmcnt(1)
	v_cndmask_b32_e64 v0, v6, v163, s[0:1]
	s_cselect_b64 vcc, -1, 0
	s_cmpk_lt_u32 s63, 0x180
	v_cndmask_b32_e32 v6, v164, v0, vcc
	s_cselect_b64 vcc, -1, 0
	s_cmpk_lg_i32 s62, 0x180
	v_cndmask_b32_e32 v0, v7, v163, vcc
	s_cselect_b64 s[8:9], -1, 0
	v_cndmask_b32_e64 v1, v164, v0, s[8:9]
	s_add_i32 s8, s33, -7
	s_cmpk_lt_u32 s63, 0x1c0
	s_cselect_b64 s[12:13], -1, 0
	s_cmp_gt_u32 s8, 1
	s_cselect_b64 s[8:9], -1, 0
	s_cmpk_lt_u32 s63, 0x200
	s_waitcnt lgkmcnt(0)
	v_cndmask_b32_e64 v0, v8, v163, s[12:13]
	s_cselect_b64 s[14:15], -1, 0
	s_cmpk_lg_i32 s62, 0x200
	v_cndmask_b32_e64 v8, v164, v0, s[8:9]
	v_cndmask_b32_e64 v0, v9, v163, s[14:15]
	s_cselect_b64 s[8:9], -1, 0
	v_cndmask_b32_e64 v0, v164, v0, s[8:9]
	s_add_i32 s8, s33, -9
	s_cmpk_lt_u32 s63, 0x240
	ds_read2_b32 v[10:11], v24 offset0:9 offset1:10
	ds_read2_b32 v[14:15], v24 offset0:11 offset1:12
	ds_read2_b32 v[16:17], v24 offset0:13 offset1:14
	ds_read2_b32 v[18:19], v24 offset0:15 offset1:16
	s_cselect_b64 s[16:17], -1, 0
	s_cmp_gt_u32 s8, 1
	s_cselect_b64 s[8:9], -1, 0
	s_cmpk_lt_u32 s63, 0x280
	s_waitcnt lgkmcnt(3)
	v_cndmask_b32_e64 v7, v10, v163, s[16:17]
	s_cselect_b64 s[18:19], -1, 0
	s_cmpk_lg_i32 s62, 0x280
	v_cndmask_b32_e64 v12, v164, v7, s[8:9]
	v_cndmask_b32_e64 v7, v11, v163, s[18:19]
	s_cselect_b64 s[8:9], -1, 0
	v_cndmask_b32_e64 v7, v164, v7, s[8:9]
	s_add_i32 s8, s33, -11
	s_cmpk_lt_u32 s63, 0x2c0
	s_cselect_b64 s[20:21], -1, 0
	s_cmp_gt_u32 s8, 1
	s_cselect_b64 s[8:9], -1, 0
	s_cmpk_lt_u32 s63, 0x300
	s_waitcnt lgkmcnt(2)
	v_cndmask_b32_e64 v9, v14, v163, s[20:21]
	s_cselect_b64 s[22:23], -1, 0
	s_cmpk_lg_i32 s62, 0x300
	v_cndmask_b32_e64 v13, v164, v9, s[8:9]
	v_cndmask_b32_e64 v9, v15, v163, s[22:23]
	s_cselect_b64 s[8:9], -1, 0
	v_cndmask_b32_e64 v9, v164, v9, s[8:9]
	s_add_i32 s8, s33, -13
	s_cmpk_lt_u32 s63, 0x340
	s_cselect_b64 s[24:25], -1, 0
	s_cmp_gt_u32 s8, 1
	s_cselect_b64 s[8:9], -1, 0
	s_cmpk_lt_u32 s63, 0x380
	s_waitcnt lgkmcnt(1)
	v_cndmask_b32_e64 v10, v16, v163, s[24:25]
	s_cselect_b64 s[26:27], -1, 0
	s_cmpk_lg_i32 s62, 0x380
	v_cndmask_b32_e64 v14, v164, v10, s[8:9]
	v_cndmask_b32_e64 v10, v17, v163, s[26:27]
	s_cselect_b64 s[8:9], -1, 0
	v_cndmask_b32_e64 v10, v164, v10, s[8:9]
	s_add_i32 s8, s33, -15
	s_cmpk_lt_u32 s63, 0x3c0
	s_cselect_b64 s[28:29], -1, 0
	s_cmp_gt_u32 s8, 1
	s_cselect_b64 s[8:9], -1, 0
	s_cmpk_lt_u32 s63, 0x400
	s_waitcnt lgkmcnt(0)
	v_cndmask_b32_e64 v11, v18, v163, s[28:29]
	s_cselect_b64 s[30:31], -1, 0
	s_cmpk_lg_i32 s62, 0x400
	v_cndmask_b32_e64 v15, v164, v11, s[8:9]
	v_cndmask_b32_e64 v11, v19, v163, s[30:31]
	s_cselect_b64 s[8:9], -1, 0
	v_cndmask_b32_e64 v11, v164, v11, s[8:9]
	s_sub_i32 s8, s33, 17
	s_cmpk_lt_u32 s63, 0x440
	ds_read2_b32 v[16:17], v24 offset0:17 offset1:18
	ds_read2_b32 v[18:19], v24 offset0:19 offset1:20
	ds_read2_b32 v[22:23], v24 offset0:21 offset1:22
	ds_read2_b32 v[26:27], v24 offset0:23 offset1:24
	s_cselect_b64 s[34:35], -1, 0
	s_cmp_gt_u32 s8, 1
	s_cselect_b64 s[8:9], -1, 0
	s_cmpk_lt_u32 s63, 0x480
	s_waitcnt lgkmcnt(3)
	v_cndmask_b32_e64 v16, v16, v163, s[34:35]
	s_cselect_b64 s[36:37], -1, 0
	s_cmpk_lg_i32 s62, 0x480
	v_cndmask_b32_e64 v20, v164, v16, s[8:9]
	v_cndmask_b32_e64 v16, v17, v163, s[36:37]
	s_cselect_b64 s[8:9], -1, 0
	v_cndmask_b32_e64 v16, v164, v16, s[8:9]
	s_sub_i32 s8, s33, 19
	s_cmpk_lt_u32 s63, 0x4c0
	s_cselect_b64 s[38:39], -1, 0
	s_cmp_gt_u32 s8, 1
	s_cselect_b64 s[8:9], -1, 0
	s_cmpk_lt_u32 s63, 0x500
	s_waitcnt lgkmcnt(2)
	v_cndmask_b32_e64 v17, v18, v163, s[38:39]
	s_cselect_b64 s[40:41], -1, 0
	s_cmpk_lg_i32 s62, 0x500
	v_cndmask_b32_e64 v21, v164, v17, s[8:9]
	v_cndmask_b32_e64 v17, v19, v163, s[40:41]
	s_cselect_b64 s[8:9], -1, 0
	v_cndmask_b32_e64 v17, v164, v17, s[8:9]
	s_sub_i32 s8, s33, 21
	s_cmpk_lt_u32 s63, 0x540
	s_cselect_b64 s[42:43], -1, 0
	s_cmp_gt_u32 s8, 1
	s_cselect_b64 s[8:9], -1, 0
	s_cmpk_lt_u32 s63, 0x580
	s_waitcnt lgkmcnt(1)
	v_cndmask_b32_e64 v18, v22, v163, s[42:43]
	s_cselect_b64 s[44:45], -1, 0
	s_cmpk_lg_i32 s62, 0x580
	v_cndmask_b32_e64 v22, v164, v18, s[8:9]
	v_cndmask_b32_e64 v18, v23, v163, s[44:45]
	s_cselect_b64 s[8:9], -1, 0
	v_cndmask_b32_e64 v18, v164, v18, s[8:9]
	s_sub_i32 s8, s33, 23
	s_cmpk_lt_u32 s63, 0x5c0
	s_cselect_b64 s[46:47], -1, 0
	s_cmp_gt_u32 s8, 1
	s_cselect_b64 s[8:9], -1, 0
	s_cmpk_lt_u32 s63, 0x600
	s_waitcnt lgkmcnt(0)
	v_cndmask_b32_e64 v19, v26, v163, s[46:47]
	s_cselect_b64 s[48:49], -1, 0
	s_cmpk_lg_i32 s62, 0x600
	v_cndmask_b32_e64 v23, v164, v19, s[8:9]
	v_cndmask_b32_e64 v19, v27, v163, s[48:49]
	s_cselect_b64 s[8:9], -1, 0
	v_cndmask_b32_e64 v19, v164, v19, s[8:9]
	s_sub_i32 s8, s33, 25
	s_cmpk_lt_u32 s63, 0x640
	ds_read2_b32 v[26:27], v24 offset0:25 offset1:26
	ds_read2_b32 v[28:29], v24 offset0:27 offset1:28
	ds_read2_b32 v[34:35], v24 offset0:29 offset1:30
	ds_read_b32 v31, v24 offset:124
	s_cselect_b64 s[50:51], -1, 0
	s_cmp_gt_u32 s8, 1
	s_cselect_b64 s[8:9], -1, 0
	s_cmpk_lt_u32 s63, 0x680
	s_waitcnt lgkmcnt(3)
	v_cndmask_b32_e64 v24, v26, v163, s[50:51]
	s_cselect_b64 s[52:53], -1, 0
	s_cmpk_lg_i32 s62, 0x680
	v_cndmask_b32_e64 v30, v164, v24, s[8:9]
	v_cndmask_b32_e64 v24, v27, v163, s[52:53]
	s_cselect_b64 s[8:9], -1, 0
	v_cndmask_b32_e64 v24, v164, v24, s[8:9]
	s_sub_i32 s8, s33, 27
	s_cmpk_lt_u32 s63, 0x6c0
	s_cselect_b64 s[54:55], -1, 0
	s_cmp_gt_u32 s8, 1
	s_cselect_b64 s[8:9], -1, 0
	s_cmpk_lt_u32 s63, 0x700
	s_waitcnt lgkmcnt(2)
	v_cndmask_b32_e64 v25, v28, v163, s[54:55]
	s_cselect_b64 s[56:57], -1, 0
	s_cmpk_lg_i32 s62, 0x700
	v_cndmask_b32_e64 v33, v164, v25, s[8:9]
	v_cndmask_b32_e64 v25, v29, v163, s[56:57]
	s_cselect_b64 s[8:9], -1, 0
	v_cndmask_b32_e64 v25, v164, v25, s[8:9]
	s_sub_i32 s8, s33, 29
	s_cmpk_lt_u32 s63, 0x740
	s_cselect_b64 s[58:59], -1, 0
	s_cmp_gt_u32 s8, 1
	s_cselect_b64 s[8:9], -1, 0
	s_cmpk_lt_u32 s63, 0x780
	s_waitcnt lgkmcnt(1)
	v_cndmask_b32_e64 v26, v34, v163, s[58:59]
	s_cselect_b64 s[60:61], -1, 0
	s_cmpk_lg_i32 s62, 0x780
	v_cndmask_b32_e64 v36, v164, v26, s[8:9]
	s_cselect_b64 s[8:9], -1, 0
	s_sub_i32 s33, s33, 31
	v_cndmask_b32_e64 v26, v35, v163, s[60:61]
	s_cmpk_lt_u32 s63, 0x7c0
	v_cndmask_b32_e64 v26, v164, v26, s[8:9]
	s_cselect_b64 s[8:9], -1, 0
	s_cmp_gt_u32 s33, 1
	s_waitcnt lgkmcnt(0)
	v_cndmask_b32_e64 v27, v31, v163, s[8:9]
	s_cselect_b64 s[62:63], -1, 0
	v_cndmask_b32_e64 v27, v164, v27, s[62:63]
	v_cmp_ge_f32_e64 s[62:63], v36, v27
	s_mov_b32 s33, 0x461c4000
	v_mov_b32_e32 v101, v97
	v_cndmask_b32_e64 v28, 0, 1, s[62:63]
	v_cmp_ge_f32_e64 s[62:63], v33, v27
	s_nop 1
	v_cndmask_b32_e64 v29, 0, 1, s[62:63]
	v_cmp_ge_f32_e64 s[62:63], v30, v27
	s_nop 1
	v_cndmask_b32_e64 v31, 0, 1, s[62:63]
	v_cmp_ge_f32_e64 s[62:63], v23, v27
	s_nop 1
	v_cndmask_b32_e64 v32, 0, 1, s[62:63]
	v_cmp_ge_f32_e64 s[62:63], v22, v27
	s_nop 1
	v_cndmask_b32_e64 v34, 0, 1, s[62:63]
	v_cmp_ge_f32_e64 s[62:63], v21, v27
	s_nop 1
	v_cndmask_b32_e64 v35, 0, 1, s[62:63]
	v_cmp_ge_f32_e64 s[62:63], v20, v27
	s_nop 1
	v_cndmask_b32_e64 v37, 0, 1, s[62:63]
	v_cmp_ge_f32_e64 s[62:63], v15, v27
	s_nop 1
	v_cndmask_b32_e64 v38, 0, 1, s[62:63]
	v_cmp_ge_f32_e64 s[62:63], v14, v27
	s_nop 1
	v_cndmask_b32_e64 v39, 0, 1, s[62:63]
	v_cmp_ge_f32_e64 s[62:63], v13, v27
	s_nop 1
	v_cndmask_b32_e64 v40, 0, 1, s[62:63]
	v_cmp_ge_f32_e64 s[62:63], v12, v27
	s_nop 1
	v_cndmask_b32_e64 v41, 0, 1, s[62:63]
	v_cmp_ge_f32_e64 s[62:63], s33, v27
	s_nop 1
	v_cndmask_b32_e64 v42, 0, 1, s[62:63]
	v_cmp_ge_f32_e64 s[62:63], v2, v27
	s_nop 1
	v_cndmask_b32_e64 v43, 0, 1, s[62:63]
	v_cmp_ge_f32_e64 s[62:63], v3, v27
	s_nop 1
	v_addc_co_u32_e64 v42, s[62:63], v42, v43, s[62:63]
	v_cmp_ge_f32_e64 s[62:63], v4, v27
	s_nop 1
	v_cndmask_b32_e64 v43, 0, 1, s[62:63]
	v_cmp_ge_f32_e64 s[62:63], v5, v27
	s_nop 1
	v_addc_co_u32_e64 v42, s[62:63], v42, v43, s[62:63]
	v_cmp_ge_f32_e64 s[62:63], v6, v27
	s_nop 1
	v_cndmask_b32_e64 v43, 0, 1, s[62:63]
	v_cmp_ge_f32_e64 s[62:63], v1, v27
	s_nop 1
	v_addc_co_u32_e64 v42, s[62:63], v42, v43, s[62:63]
	v_cmp_ge_f32_e64 s[62:63], v8, v27
	s_nop 1
	v_cndmask_b32_e64 v43, 0, 1, s[62:63]
	v_cmp_ge_f32_e64 s[62:63], s33, v26
	s_nop 1
	v_cndmask_b32_e64 v44, 0, 1, s[62:63]
	v_cmp_ge_f32_e64 s[62:63], v2, v26
	s_nop 1
	v_cndmask_b32_e64 v45, 0, 1, s[62:63]
	v_cmp_ge_f32_e64 s[62:63], v3, v26
	s_nop 1
	v_addc_co_u32_e64 v44, s[62:63], v44, v45, s[62:63]
	v_cmp_ge_f32_e64 s[62:63], v4, v26
	s_nop 1
	v_cndmask_b32_e64 v45, 0, 1, s[62:63]
	v_cmp_ge_f32_e64 s[62:63], v5, v26
	s_nop 1
	v_addc_co_u32_e64 v44, s[62:63], v44, v45, s[62:63]
	v_cmp_ge_f32_e64 s[62:63], v6, v26
	s_nop 1
	v_cndmask_b32_e64 v45, 0, 1, s[62:63]
	v_cmp_ge_f32_e64 s[62:63], v1, v26
	s_nop 1
	v_addc_co_u32_e64 v44, s[62:63], v44, v45, s[62:63]
	v_cmp_ge_f32_e64 s[62:63], v8, v26
	s_nop 1
	v_cndmask_b32_e64 v45, 0, 1, s[62:63]
	v_cmp_gt_f32_e64 s[62:63], v27, v26
	s_nop 1
	v_addc_co_u32_e64 v44, s[62:63], v44, v45, s[62:63]
	v_cmp_ge_f32_e64 s[62:63], v0, v26
	s_nop 1
	v_cndmask_b32_e64 v45, 0, 1, s[62:63]
	v_cmp_ge_f32_e64 s[62:63], v12, v26
	s_nop 1
	v_addc_co_u32_e64 v44, s[62:63], v44, v45, s[62:63]
	v_cmp_ge_f32_e64 s[62:63], v7, v26
	s_nop 1
	v_cndmask_b32_e64 v45, 0, 1, s[62:63]
	v_cmp_ge_f32_e64 s[62:63], v13, v26
	s_nop 1
	v_addc_co_u32_e64 v44, s[62:63], v44, v45, s[62:63]
	v_cmp_ge_f32_e64 s[62:63], v9, v26
	s_nop 1
	v_cndmask_b32_e64 v45, 0, 1, s[62:63]
	v_cmp_ge_f32_e64 s[62:63], v14, v26
	s_nop 1
	v_addc_co_u32_e64 v44, s[62:63], v44, v45, s[62:63]
	v_cmp_ge_f32_e64 s[62:63], v10, v26
	s_nop 1
	v_cndmask_b32_e64 v45, 0, 1, s[62:63]
	v_cmp_ge_f32_e64 s[62:63], v15, v26
	s_nop 1
	v_addc_co_u32_e64 v44, s[62:63], v44, v45, s[62:63]
	v_cmp_ge_f32_e64 s[62:63], v11, v26
	s_nop 1
	v_cndmask_b32_e64 v45, 0, 1, s[62:63]
	v_cmp_ge_f32_e64 s[62:63], v20, v26
	s_nop 1
	v_addc_co_u32_e64 v44, s[62:63], v44, v45, s[62:63]
	v_cmp_ge_f32_e64 s[62:63], v16, v26
	s_nop 1
	v_cndmask_b32_e64 v45, 0, 1, s[62:63]
	v_cmp_ge_f32_e64 s[62:63], v21, v26
	s_nop 1
	v_addc_co_u32_e64 v44, s[62:63], v44, v45, s[62:63]
	v_cmp_ge_f32_e64 s[62:63], v17, v26
	s_nop 1
	v_cndmask_b32_e64 v45, 0, 1, s[62:63]
	v_cmp_ge_f32_e64 s[62:63], v22, v26
	s_nop 1
	v_addc_co_u32_e64 v44, s[62:63], v44, v45, s[62:63]
	v_cmp_ge_f32_e64 s[62:63], v18, v26
	s_nop 1
	v_cndmask_b32_e64 v45, 0, 1, s[62:63]
	v_cmp_ge_f32_e64 s[62:63], v23, v26
	s_nop 1
	v_addc_co_u32_e64 v44, s[62:63], v44, v45, s[62:63]
	v_cmp_ge_f32_e64 s[62:63], v19, v26
	s_nop 1
	v_cndmask_b32_e64 v45, 0, 1, s[62:63]
	v_cmp_ge_f32_e64 s[62:63], v30, v26
	s_nop 1
	v_addc_co_u32_e64 v44, s[62:63], v44, v45, s[62:63]
	v_cmp_ge_f32_e64 s[62:63], v24, v26
	s_nop 1
	v_cndmask_b32_e64 v45, 0, 1, s[62:63]
	v_cmp_ge_f32_e64 s[62:63], v33, v26
	s_nop 1
	v_addc_co_u32_e64 v44, s[62:63], v44, v45, s[62:63]
	v_cmp_ge_f32_e64 s[62:63], v25, v26
	s_nop 1
	v_cndmask_b32_e64 v45, 0, 1, s[62:63]
	v_cmp_ge_f32_e64 s[62:63], v36, v26
	s_nop 1
	v_addc_co_u32_e64 v44, s[62:63], v44, v45, s[62:63]
	v_cmp_lt_u32_e64 s[62:63], 15, v44
	s_or_b64 s[60:61], s[62:63], s[60:61]
	v_cndmask_b32_e64 v44, 2.0, 0, s[60:61]
	v_cmp_ge_f32_e64 s[60:61], s33, v36
	s_nop 1
	v_cndmask_b32_e64 v45, 0, 1, s[60:61]
	v_cmp_ge_f32_e64 s[60:61], v2, v36
	s_nop 1
	v_cndmask_b32_e64 v46, 0, 1, s[60:61]
	v_cmp_ge_f32_e64 s[60:61], v3, v36
	s_nop 1
	v_addc_co_u32_e64 v45, s[60:61], v45, v46, s[60:61]
	v_cmp_ge_f32_e64 s[60:61], v4, v36
	s_nop 1
	v_cndmask_b32_e64 v46, 0, 1, s[60:61]
	v_cmp_ge_f32_e64 s[60:61], v5, v36
	s_nop 1
	v_addc_co_u32_e64 v45, s[60:61], v45, v46, s[60:61]
	v_cmp_ge_f32_e64 s[60:61], v6, v36
	s_nop 1
	v_cndmask_b32_e64 v46, 0, 1, s[60:61]
	v_cmp_ge_f32_e64 s[60:61], v1, v36
	s_nop 1
	v_addc_co_u32_e64 v45, s[60:61], v45, v46, s[60:61]
	v_cmp_ge_f32_e64 s[60:61], v8, v36
	s_nop 1
	v_cndmask_b32_e64 v46, 0, 1, s[60:61]
	v_cmp_gt_f32_e64 s[60:61], v27, v36
	s_nop 1
	v_addc_co_u32_e64 v45, s[60:61], v45, v46, s[60:61]
	v_cmp_ge_f32_e64 s[60:61], v0, v36
	s_nop 1
	v_cndmask_b32_e64 v46, 0, 1, s[60:61]
	v_cmp_ge_f32_e64 s[60:61], v12, v36
	s_nop 1
	v_addc_co_u32_e64 v45, s[60:61], v45, v46, s[60:61]
	v_cmp_ge_f32_e64 s[60:61], v7, v36
	s_nop 1
	v_cndmask_b32_e64 v46, 0, 1, s[60:61]
	v_cmp_ge_f32_e64 s[60:61], v13, v36
	s_nop 1
	v_addc_co_u32_e64 v45, s[60:61], v45, v46, s[60:61]
	v_cmp_ge_f32_e64 s[60:61], v9, v36
	s_nop 1
	v_cndmask_b32_e64 v46, 0, 1, s[60:61]
	v_cmp_ge_f32_e64 s[60:61], v14, v36
	s_nop 1
	v_addc_co_u32_e64 v45, s[60:61], v45, v46, s[60:61]
	v_cmp_ge_f32_e64 s[60:61], v10, v36
	s_nop 1
	v_cndmask_b32_e64 v46, 0, 1, s[60:61]
	v_cmp_ge_f32_e64 s[60:61], v15, v36
	s_nop 1
	v_addc_co_u32_e64 v45, s[60:61], v45, v46, s[60:61]
	v_cmp_ge_f32_e64 s[60:61], v11, v36
	s_nop 1
	v_cndmask_b32_e64 v46, 0, 1, s[60:61]
	v_cmp_ge_f32_e64 s[60:61], v20, v36
	s_nop 1
	v_addc_co_u32_e64 v45, s[60:61], v45, v46, s[60:61]
	v_cmp_ge_f32_e64 s[60:61], v16, v36
	s_nop 1
	v_cndmask_b32_e64 v46, 0, 1, s[60:61]
	v_cmp_ge_f32_e64 s[60:61], v21, v36
	s_nop 1
	v_addc_co_u32_e64 v45, s[60:61], v45, v46, s[60:61]
	v_cmp_ge_f32_e64 s[60:61], v17, v36
	s_nop 1
	v_cndmask_b32_e64 v46, 0, 1, s[60:61]
	v_cmp_ge_f32_e64 s[60:61], v22, v36
	s_nop 1
	v_addc_co_u32_e64 v45, s[60:61], v45, v46, s[60:61]
	v_cmp_ge_f32_e64 s[60:61], v18, v36
	s_nop 1
	v_cndmask_b32_e64 v46, 0, 1, s[60:61]
	v_cmp_ge_f32_e64 s[60:61], v23, v36
	s_nop 1
	v_addc_co_u32_e64 v45, s[60:61], v45, v46, s[60:61]
	v_cmp_ge_f32_e64 s[60:61], v19, v36
	s_nop 1
	v_cndmask_b32_e64 v46, 0, 1, s[60:61]
	v_cmp_ge_f32_e64 s[60:61], v30, v36
	s_nop 1
	v_addc_co_u32_e64 v45, s[60:61], v45, v46, s[60:61]
	v_cmp_ge_f32_e64 s[60:61], v24, v36
	s_nop 1
	v_cndmask_b32_e64 v46, 0, 1, s[60:61]
	v_cmp_ge_f32_e64 s[60:61], v33, v36
	s_nop 1
	v_addc_co_u32_e64 v45, s[60:61], v45, v46, s[60:61]
	v_cmp_ge_f32_e64 s[60:61], v25, v36
	s_nop 1
	v_cndmask_b32_e64 v46, 0, 1, s[60:61]
	v_cmp_gt_f32_e64 s[60:61], v26, v36
	s_nop 1
	v_addc_co_u32_e64 v45, s[60:61], v45, v46, s[60:61]
	v_cmp_lt_u32_e64 s[60:61], 15, v45
	s_or_b64 s[58:59], s[60:61], s[58:59]
	v_cndmask_b32_e64 v45, v165, 0, s[58:59]
	v_cmp_ge_f32_e64 s[58:59], s33, v25
	s_nop 1
	v_cndmask_b32_e64 v46, 0, 1, s[58:59]
	v_cmp_ge_f32_e64 s[58:59], v2, v25
	s_nop 1
	v_cndmask_b32_e64 v47, 0, 1, s[58:59]
	v_cmp_ge_f32_e64 s[58:59], v3, v25
	s_nop 1
	v_addc_co_u32_e64 v46, s[58:59], v46, v47, s[58:59]
	v_cmp_ge_f32_e64 s[58:59], v4, v25
	s_nop 1
	v_cndmask_b32_e64 v47, 0, 1, s[58:59]
	v_cmp_ge_f32_e64 s[58:59], v5, v25
	s_nop 1
	v_addc_co_u32_e64 v46, s[58:59], v46, v47, s[58:59]
	v_cmp_ge_f32_e64 s[58:59], v6, v25
	s_nop 1
	v_cndmask_b32_e64 v47, 0, 1, s[58:59]
	v_cmp_ge_f32_e64 s[58:59], v1, v25
	s_nop 1
	v_addc_co_u32_e64 v46, s[58:59], v46, v47, s[58:59]
	v_cmp_ge_f32_e64 s[58:59], v8, v25
	s_nop 1
	v_cndmask_b32_e64 v47, 0, 1, s[58:59]
	v_cmp_gt_f32_e64 s[58:59], v27, v25
	s_nop 1
	v_addc_co_u32_e64 v46, s[58:59], v46, v47, s[58:59]
	v_cmp_ge_f32_e64 s[58:59], v0, v25
	s_nop 1
	v_cndmask_b32_e64 v47, 0, 1, s[58:59]
	v_cmp_ge_f32_e64 s[58:59], v12, v25
	s_nop 1
	v_addc_co_u32_e64 v46, s[58:59], v46, v47, s[58:59]
	v_cmp_ge_f32_e64 s[58:59], v7, v25
	s_nop 1
	v_cndmask_b32_e64 v47, 0, 1, s[58:59]
	v_cmp_ge_f32_e64 s[58:59], v13, v25
	s_nop 1
	v_addc_co_u32_e64 v46, s[58:59], v46, v47, s[58:59]
	v_cmp_ge_f32_e64 s[58:59], v9, v25
	s_nop 1
	v_cndmask_b32_e64 v47, 0, 1, s[58:59]
	v_cmp_ge_f32_e64 s[58:59], v14, v25
	s_nop 1
	v_addc_co_u32_e64 v46, s[58:59], v46, v47, s[58:59]
	v_cmp_ge_f32_e64 s[58:59], v10, v25
	s_nop 1
	v_cndmask_b32_e64 v47, 0, 1, s[58:59]
	v_cmp_ge_f32_e64 s[58:59], v15, v25
	s_nop 1
	v_addc_co_u32_e64 v46, s[58:59], v46, v47, s[58:59]
	v_cmp_ge_f32_e64 s[58:59], v11, v25
	s_nop 1
	v_cndmask_b32_e64 v47, 0, 1, s[58:59]
	v_cmp_ge_f32_e64 s[58:59], v20, v25
	s_nop 1
	v_addc_co_u32_e64 v46, s[58:59], v46, v47, s[58:59]
	v_cmp_ge_f32_e64 s[58:59], v16, v25
	s_nop 1
	v_cndmask_b32_e64 v47, 0, 1, s[58:59]
	v_cmp_ge_f32_e64 s[58:59], v21, v25
	s_nop 1
	v_addc_co_u32_e64 v46, s[58:59], v46, v47, s[58:59]
	v_cmp_ge_f32_e64 s[58:59], v17, v25
	s_nop 1
	v_cndmask_b32_e64 v47, 0, 1, s[58:59]
	v_cmp_ge_f32_e64 s[58:59], v22, v25
	s_nop 1
	v_addc_co_u32_e64 v46, s[58:59], v46, v47, s[58:59]
	v_cmp_ge_f32_e64 s[58:59], v18, v25
	s_nop 1
	v_cndmask_b32_e64 v47, 0, 1, s[58:59]
	v_cmp_ge_f32_e64 s[58:59], v23, v25
	s_nop 1
	v_addc_co_u32_e64 v46, s[58:59], v46, v47, s[58:59]
	v_cmp_ge_f32_e64 s[58:59], v19, v25
	s_nop 1
	v_cndmask_b32_e64 v47, 0, 1, s[58:59]
	v_cmp_ge_f32_e64 s[58:59], v30, v25
	s_nop 1
	v_addc_co_u32_e64 v46, s[58:59], v46, v47, s[58:59]
	v_cmp_ge_f32_e64 s[58:59], v24, v25
	s_nop 1
	v_cndmask_b32_e64 v47, 0, 1, s[58:59]
	v_cmp_ge_f32_e64 s[58:59], v33, v25
	s_nop 1
	v_addc_co_u32_e64 v46, s[58:59], v46, v47, s[58:59]
	v_cmp_gt_f32_e64 s[58:59], v36, v25
	s_nop 1
	v_cndmask_b32_e64 v47, 0, 1, s[58:59]
	v_cmp_gt_f32_e64 s[58:59], v26, v25
	s_nop 1
	v_addc_co_u32_e64 v46, s[58:59], v46, v47, s[58:59]
	v_cmp_lt_u32_e64 s[58:59], 15, v46
	s_or_b64 s[56:57], s[58:59], s[56:57]
	v_cndmask_b32_e64 v46, v166, 0, s[56:57]
	v_cmp_ge_f32_e64 s[56:57], s33, v33
	s_nop 1
	v_cndmask_b32_e64 v47, 0, 1, s[56:57]
	v_cmp_ge_f32_e64 s[56:57], v2, v33
	s_nop 1
	v_cndmask_b32_e64 v48, 0, 1, s[56:57]
	v_cmp_ge_f32_e64 s[56:57], v3, v33
	s_nop 1
	v_addc_co_u32_e64 v47, s[56:57], v47, v48, s[56:57]
	v_cmp_ge_f32_e64 s[56:57], v4, v33
	s_nop 1
	v_cndmask_b32_e64 v48, 0, 1, s[56:57]
	v_cmp_ge_f32_e64 s[56:57], v5, v33
	s_nop 1
	v_addc_co_u32_e64 v47, s[56:57], v47, v48, s[56:57]
	v_cmp_ge_f32_e64 s[56:57], v6, v33
	s_nop 1
	v_cndmask_b32_e64 v48, 0, 1, s[56:57]
	v_cmp_ge_f32_e64 s[56:57], v1, v33
	s_nop 1
	v_addc_co_u32_e64 v47, s[56:57], v47, v48, s[56:57]
	v_cmp_ge_f32_e64 s[56:57], v8, v33
	s_nop 1
	v_cndmask_b32_e64 v48, 0, 1, s[56:57]
	v_cmp_gt_f32_e64 s[56:57], v27, v33
	s_nop 1
	v_addc_co_u32_e64 v47, s[56:57], v47, v48, s[56:57]
	v_cmp_ge_f32_e64 s[56:57], v0, v33
	s_nop 1
	v_cndmask_b32_e64 v48, 0, 1, s[56:57]
	v_cmp_ge_f32_e64 s[56:57], v12, v33
	s_nop 1
	v_addc_co_u32_e64 v47, s[56:57], v47, v48, s[56:57]
	v_cmp_ge_f32_e64 s[56:57], v7, v33
	s_nop 1
	v_cndmask_b32_e64 v48, 0, 1, s[56:57]
	v_cmp_ge_f32_e64 s[56:57], v13, v33
	s_nop 1
	v_addc_co_u32_e64 v47, s[56:57], v47, v48, s[56:57]
	v_cmp_ge_f32_e64 s[56:57], v9, v33
	s_nop 1
	v_cndmask_b32_e64 v48, 0, 1, s[56:57]
	v_cmp_ge_f32_e64 s[56:57], v14, v33
	s_nop 1
	v_addc_co_u32_e64 v47, s[56:57], v47, v48, s[56:57]
	v_cmp_ge_f32_e64 s[56:57], v10, v33
	s_nop 1
	v_cndmask_b32_e64 v48, 0, 1, s[56:57]
	v_cmp_ge_f32_e64 s[56:57], v15, v33
	s_nop 1
	v_addc_co_u32_e64 v47, s[56:57], v47, v48, s[56:57]
	v_cmp_ge_f32_e64 s[56:57], v11, v33
	s_nop 1
	v_cndmask_b32_e64 v48, 0, 1, s[56:57]
	v_cmp_ge_f32_e64 s[56:57], v20, v33
	s_nop 1
	v_addc_co_u32_e64 v47, s[56:57], v47, v48, s[56:57]
	v_cmp_ge_f32_e64 s[56:57], v16, v33
	s_nop 1
	v_cndmask_b32_e64 v48, 0, 1, s[56:57]
	v_cmp_ge_f32_e64 s[56:57], v21, v33
	s_nop 1
	v_addc_co_u32_e64 v47, s[56:57], v47, v48, s[56:57]
	v_cmp_ge_f32_e64 s[56:57], v17, v33
	s_nop 1
	v_cndmask_b32_e64 v48, 0, 1, s[56:57]
	v_cmp_ge_f32_e64 s[56:57], v22, v33
	s_nop 1
	v_addc_co_u32_e64 v47, s[56:57], v47, v48, s[56:57]
	v_cmp_ge_f32_e64 s[56:57], v18, v33
	s_nop 1
	v_cndmask_b32_e64 v48, 0, 1, s[56:57]
	v_cmp_ge_f32_e64 s[56:57], v23, v33
	s_nop 1
	v_addc_co_u32_e64 v47, s[56:57], v47, v48, s[56:57]
	v_cmp_ge_f32_e64 s[56:57], v19, v33
	s_nop 1
	v_cndmask_b32_e64 v48, 0, 1, s[56:57]
	v_cmp_ge_f32_e64 s[56:57], v30, v33
	s_nop 1
	v_addc_co_u32_e64 v47, s[56:57], v47, v48, s[56:57]
	v_cmp_ge_f32_e64 s[56:57], v24, v33
	s_nop 1
	v_cndmask_b32_e64 v48, 0, 1, s[56:57]
	v_cmp_gt_f32_e64 s[56:57], v25, v33
	s_nop 1
	v_addc_co_u32_e64 v47, s[56:57], v47, v48, s[56:57]
	v_cmp_gt_f32_e64 s[56:57], v36, v33
	s_nop 1
	v_cndmask_b32_e64 v48, 0, 1, s[56:57]
	v_cmp_gt_f32_e64 s[56:57], v26, v33
	s_nop 1
	v_addc_co_u32_e64 v47, s[56:57], v47, v48, s[56:57]
	v_cmp_lt_u32_e64 s[56:57], 15, v47
	s_or_b64 s[54:55], s[56:57], s[54:55]
	v_cndmask_b32_e64 v47, v167, 0, s[54:55]
	v_cmp_ge_f32_e64 s[54:55], s33, v24
	s_nop 1
	v_cndmask_b32_e64 v48, 0, 1, s[54:55]
	v_cmp_ge_f32_e64 s[54:55], v2, v24
	s_nop 1
	v_cndmask_b32_e64 v49, 0, 1, s[54:55]
	v_cmp_ge_f32_e64 s[54:55], v3, v24
	s_nop 1
	v_addc_co_u32_e64 v48, s[54:55], v48, v49, s[54:55]
	v_cmp_ge_f32_e64 s[54:55], v4, v24
	s_nop 1
	v_cndmask_b32_e64 v49, 0, 1, s[54:55]
	v_cmp_ge_f32_e64 s[54:55], v5, v24
	s_nop 1
	v_addc_co_u32_e64 v48, s[54:55], v48, v49, s[54:55]
	v_cmp_ge_f32_e64 s[54:55], v6, v24
	s_nop 1
	v_cndmask_b32_e64 v49, 0, 1, s[54:55]
	v_cmp_ge_f32_e64 s[54:55], v1, v24
	s_nop 1
	v_addc_co_u32_e64 v48, s[54:55], v48, v49, s[54:55]
	v_cmp_ge_f32_e64 s[54:55], v8, v24
	s_nop 1
	v_cndmask_b32_e64 v49, 0, 1, s[54:55]
	v_cmp_gt_f32_e64 s[54:55], v27, v24
	s_nop 1
	v_addc_co_u32_e64 v48, s[54:55], v48, v49, s[54:55]
	v_cmp_ge_f32_e64 s[54:55], v0, v24
	s_nop 1
	v_cndmask_b32_e64 v49, 0, 1, s[54:55]
	v_cmp_ge_f32_e64 s[54:55], v12, v24
	s_nop 1
	v_addc_co_u32_e64 v48, s[54:55], v48, v49, s[54:55]
	v_cmp_ge_f32_e64 s[54:55], v7, v24
	s_nop 1
	v_cndmask_b32_e64 v49, 0, 1, s[54:55]
	v_cmp_ge_f32_e64 s[54:55], v13, v24
	s_nop 1
	v_addc_co_u32_e64 v48, s[54:55], v48, v49, s[54:55]
	v_cmp_ge_f32_e64 s[54:55], v9, v24
	s_nop 1
	v_cndmask_b32_e64 v49, 0, 1, s[54:55]
	v_cmp_ge_f32_e64 s[54:55], v14, v24
	s_nop 1
	v_addc_co_u32_e64 v48, s[54:55], v48, v49, s[54:55]
	v_cmp_ge_f32_e64 s[54:55], v10, v24
	s_nop 1
	v_cndmask_b32_e64 v49, 0, 1, s[54:55]
	v_cmp_ge_f32_e64 s[54:55], v15, v24
	s_nop 1
	v_addc_co_u32_e64 v48, s[54:55], v48, v49, s[54:55]
	v_cmp_ge_f32_e64 s[54:55], v11, v24
	s_nop 1
	v_cndmask_b32_e64 v49, 0, 1, s[54:55]
	v_cmp_ge_f32_e64 s[54:55], v20, v24
	s_nop 1
	v_addc_co_u32_e64 v48, s[54:55], v48, v49, s[54:55]
	v_cmp_ge_f32_e64 s[54:55], v16, v24
	s_nop 1
	v_cndmask_b32_e64 v49, 0, 1, s[54:55]
	v_cmp_ge_f32_e64 s[54:55], v21, v24
	s_nop 1
	v_addc_co_u32_e64 v48, s[54:55], v48, v49, s[54:55]
	v_cmp_ge_f32_e64 s[54:55], v17, v24
	s_nop 1
	v_cndmask_b32_e64 v49, 0, 1, s[54:55]
	v_cmp_ge_f32_e64 s[54:55], v22, v24
	s_nop 1
	v_addc_co_u32_e64 v48, s[54:55], v48, v49, s[54:55]
	v_cmp_ge_f32_e64 s[54:55], v18, v24
	s_nop 1
	v_cndmask_b32_e64 v49, 0, 1, s[54:55]
	v_cmp_ge_f32_e64 s[54:55], v23, v24
	s_nop 1
	v_addc_co_u32_e64 v48, s[54:55], v48, v49, s[54:55]
	v_cmp_ge_f32_e64 s[54:55], v19, v24
	s_nop 1
	v_cndmask_b32_e64 v49, 0, 1, s[54:55]
	v_cmp_ge_f32_e64 s[54:55], v30, v24
	s_nop 1
	v_addc_co_u32_e64 v48, s[54:55], v48, v49, s[54:55]
	v_cmp_gt_f32_e64 s[54:55], v33, v24
	s_nop 1
	v_cndmask_b32_e64 v49, 0, 1, s[54:55]
	v_cmp_gt_f32_e64 s[54:55], v25, v24
	s_nop 1
	v_addc_co_u32_e64 v48, s[54:55], v48, v49, s[54:55]
	v_cmp_gt_f32_e64 s[54:55], v36, v24
	s_nop 1
	v_cndmask_b32_e64 v49, 0, 1, s[54:55]
	v_cmp_gt_f32_e64 s[54:55], v26, v24
	s_nop 1
	v_addc_co_u32_e64 v48, s[54:55], v48, v49, s[54:55]
	v_cmp_lt_u32_e64 s[54:55], 15, v48
	s_or_b64 s[52:53], s[54:55], s[52:53]
	v_cndmask_b32_e64 v48, v168, 0, s[52:53]
	v_cmp_ge_f32_e64 s[52:53], s33, v30
	s_nop 1
	v_cndmask_b32_e64 v49, 0, 1, s[52:53]
	v_cmp_ge_f32_e64 s[52:53], v2, v30
	s_nop 1
	v_cndmask_b32_e64 v50, 0, 1, s[52:53]
	v_cmp_ge_f32_e64 s[52:53], v3, v30
	s_nop 1
	v_addc_co_u32_e64 v49, s[52:53], v49, v50, s[52:53]
	v_cmp_ge_f32_e64 s[52:53], v4, v30
	s_nop 1
	v_cndmask_b32_e64 v50, 0, 1, s[52:53]
	v_cmp_ge_f32_e64 s[52:53], v5, v30
	s_nop 1
	v_addc_co_u32_e64 v49, s[52:53], v49, v50, s[52:53]
	v_cmp_ge_f32_e64 s[52:53], v6, v30
	s_nop 1
	v_cndmask_b32_e64 v50, 0, 1, s[52:53]
	v_cmp_ge_f32_e64 s[52:53], v1, v30
	s_nop 1
	v_addc_co_u32_e64 v49, s[52:53], v49, v50, s[52:53]
	v_cmp_ge_f32_e64 s[52:53], v8, v30
	s_nop 1
	v_cndmask_b32_e64 v50, 0, 1, s[52:53]
	v_cmp_gt_f32_e64 s[52:53], v27, v30
	s_nop 1
	v_addc_co_u32_e64 v49, s[52:53], v49, v50, s[52:53]
	v_cmp_ge_f32_e64 s[52:53], v0, v30
	s_nop 1
	v_cndmask_b32_e64 v50, 0, 1, s[52:53]
	v_cmp_ge_f32_e64 s[52:53], v12, v30
	s_nop 1
	v_addc_co_u32_e64 v49, s[52:53], v49, v50, s[52:53]
	v_cmp_ge_f32_e64 s[52:53], v7, v30
	s_nop 1
	v_cndmask_b32_e64 v50, 0, 1, s[52:53]
	v_cmp_ge_f32_e64 s[52:53], v13, v30
	s_nop 1
	v_addc_co_u32_e64 v49, s[52:53], v49, v50, s[52:53]
	v_cmp_ge_f32_e64 s[52:53], v9, v30
	s_nop 1
	v_cndmask_b32_e64 v50, 0, 1, s[52:53]
	v_cmp_ge_f32_e64 s[52:53], v14, v30
	s_nop 1
	v_addc_co_u32_e64 v49, s[52:53], v49, v50, s[52:53]
	v_cmp_ge_f32_e64 s[52:53], v10, v30
	s_nop 1
	v_cndmask_b32_e64 v50, 0, 1, s[52:53]
	v_cmp_ge_f32_e64 s[52:53], v15, v30
	s_nop 1
	v_addc_co_u32_e64 v49, s[52:53], v49, v50, s[52:53]
	v_cmp_ge_f32_e64 s[52:53], v11, v30
	s_nop 1
	v_cndmask_b32_e64 v50, 0, 1, s[52:53]
	v_cmp_ge_f32_e64 s[52:53], v20, v30
	s_nop 1
	v_addc_co_u32_e64 v49, s[52:53], v49, v50, s[52:53]
	v_cmp_ge_f32_e64 s[52:53], v16, v30
	s_nop 1
	v_cndmask_b32_e64 v50, 0, 1, s[52:53]
	v_cmp_ge_f32_e64 s[52:53], v21, v30
	s_nop 1
	v_addc_co_u32_e64 v49, s[52:53], v49, v50, s[52:53]
	v_cmp_ge_f32_e64 s[52:53], v17, v30
	s_nop 1
	v_cndmask_b32_e64 v50, 0, 1, s[52:53]
	v_cmp_ge_f32_e64 s[52:53], v22, v30
	s_nop 1
	v_addc_co_u32_e64 v49, s[52:53], v49, v50, s[52:53]
	v_cmp_ge_f32_e64 s[52:53], v18, v30
	s_nop 1
	v_cndmask_b32_e64 v50, 0, 1, s[52:53]
	v_cmp_ge_f32_e64 s[52:53], v23, v30
	s_nop 1
	v_addc_co_u32_e64 v49, s[52:53], v49, v50, s[52:53]
	v_cmp_ge_f32_e64 s[52:53], v19, v30
	s_nop 1
	v_cndmask_b32_e64 v50, 0, 1, s[52:53]
	v_cmp_gt_f32_e64 s[52:53], v24, v30
	s_nop 1
	v_addc_co_u32_e64 v49, s[52:53], v49, v50, s[52:53]
	v_cmp_gt_f32_e64 s[52:53], v33, v30
	s_nop 1
	v_cndmask_b32_e64 v50, 0, 1, s[52:53]
	v_cmp_gt_f32_e64 s[52:53], v25, v30
	s_nop 1
	v_addc_co_u32_e64 v49, s[52:53], v49, v50, s[52:53]
	v_cmp_gt_f32_e64 s[52:53], v36, v30
	s_nop 1
	v_cndmask_b32_e64 v50, 0, 1, s[52:53]
	v_cmp_gt_f32_e64 s[52:53], v26, v30
	s_nop 1
	v_addc_co_u32_e64 v49, s[52:53], v49, v50, s[52:53]
	v_cmp_lt_u32_e64 s[52:53], 15, v49
	s_or_b64 s[50:51], s[52:53], s[50:51]
	v_cndmask_b32_e64 v49, v169, 0, s[50:51]
	v_cmp_ge_f32_e64 s[50:51], s33, v19
	s_nop 1
	v_cndmask_b32_e64 v50, 0, 1, s[50:51]
	v_cmp_ge_f32_e64 s[50:51], v2, v19
	s_nop 1
	v_cndmask_b32_e64 v51, 0, 1, s[50:51]
	v_cmp_ge_f32_e64 s[50:51], v3, v19
	s_nop 1
	v_addc_co_u32_e64 v50, s[50:51], v50, v51, s[50:51]
	v_cmp_ge_f32_e64 s[50:51], v4, v19
	s_nop 1
	v_cndmask_b32_e64 v51, 0, 1, s[50:51]
	v_cmp_ge_f32_e64 s[50:51], v5, v19
	s_nop 1
	v_addc_co_u32_e64 v50, s[50:51], v50, v51, s[50:51]
	v_cmp_ge_f32_e64 s[50:51], v6, v19
	s_nop 1
	v_cndmask_b32_e64 v51, 0, 1, s[50:51]
	v_cmp_ge_f32_e64 s[50:51], v1, v19
	s_nop 1
	v_addc_co_u32_e64 v50, s[50:51], v50, v51, s[50:51]
	v_cmp_ge_f32_e64 s[50:51], v8, v19
	s_nop 1
	v_cndmask_b32_e64 v51, 0, 1, s[50:51]
	v_cmp_gt_f32_e64 s[50:51], v27, v19
	s_nop 1
	v_addc_co_u32_e64 v50, s[50:51], v50, v51, s[50:51]
	v_cmp_ge_f32_e64 s[50:51], v0, v19
	s_nop 1
	v_cndmask_b32_e64 v51, 0, 1, s[50:51]
	v_cmp_ge_f32_e64 s[50:51], v12, v19
	s_nop 1
	v_addc_co_u32_e64 v50, s[50:51], v50, v51, s[50:51]
	v_cmp_ge_f32_e64 s[50:51], v7, v19
	s_nop 1
	v_cndmask_b32_e64 v51, 0, 1, s[50:51]
	v_cmp_ge_f32_e64 s[50:51], v13, v19
	s_nop 1
	v_addc_co_u32_e64 v50, s[50:51], v50, v51, s[50:51]
	v_cmp_ge_f32_e64 s[50:51], v9, v19
	s_nop 1
	v_cndmask_b32_e64 v51, 0, 1, s[50:51]
	v_cmp_ge_f32_e64 s[50:51], v14, v19
	s_nop 1
	v_addc_co_u32_e64 v50, s[50:51], v50, v51, s[50:51]
	v_cmp_ge_f32_e64 s[50:51], v10, v19
	s_nop 1
	v_cndmask_b32_e64 v51, 0, 1, s[50:51]
	v_cmp_ge_f32_e64 s[50:51], v15, v19
	s_nop 1
	v_addc_co_u32_e64 v50, s[50:51], v50, v51, s[50:51]
	v_cmp_ge_f32_e64 s[50:51], v11, v19
	s_nop 1
	v_cndmask_b32_e64 v51, 0, 1, s[50:51]
	v_cmp_ge_f32_e64 s[50:51], v20, v19
	s_nop 1
	v_addc_co_u32_e64 v50, s[50:51], v50, v51, s[50:51]
	v_cmp_ge_f32_e64 s[50:51], v16, v19
	s_nop 1
	v_cndmask_b32_e64 v51, 0, 1, s[50:51]
	v_cmp_ge_f32_e64 s[50:51], v21, v19
	s_nop 1
	v_addc_co_u32_e64 v50, s[50:51], v50, v51, s[50:51]
	v_cmp_ge_f32_e64 s[50:51], v17, v19
	s_nop 1
	v_cndmask_b32_e64 v51, 0, 1, s[50:51]
	v_cmp_ge_f32_e64 s[50:51], v22, v19
	s_nop 1
	v_addc_co_u32_e64 v50, s[50:51], v50, v51, s[50:51]
	v_cmp_ge_f32_e64 s[50:51], v18, v19
	s_nop 1
	v_cndmask_b32_e64 v51, 0, 1, s[50:51]
	v_cmp_ge_f32_e64 s[50:51], v23, v19
	s_nop 1
	v_addc_co_u32_e64 v50, s[50:51], v50, v51, s[50:51]
	v_cmp_gt_f32_e64 s[50:51], v30, v19
	s_nop 1
	v_cndmask_b32_e64 v51, 0, 1, s[50:51]
	v_cmp_gt_f32_e64 s[50:51], v24, v19
	s_nop 1
	v_addc_co_u32_e64 v50, s[50:51], v50, v51, s[50:51]
	v_cmp_gt_f32_e64 s[50:51], v33, v19
	s_nop 1
	v_cndmask_b32_e64 v51, 0, 1, s[50:51]
	v_cmp_gt_f32_e64 s[50:51], v25, v19
	s_nop 1
	v_addc_co_u32_e64 v50, s[50:51], v50, v51, s[50:51]
	v_cmp_gt_f32_e64 s[50:51], v36, v19
	s_nop 1
	v_cndmask_b32_e64 v51, 0, 1, s[50:51]
	v_cmp_gt_f32_e64 s[50:51], v26, v19
	s_nop 1
	v_addc_co_u32_e64 v50, s[50:51], v50, v51, s[50:51]
	v_cmp_lt_u32_e64 s[50:51], 15, v50
	s_or_b64 s[48:49], s[50:51], s[48:49]
	v_cndmask_b32_e64 v50, v170, 0, s[48:49]
	v_cmp_ge_f32_e64 s[48:49], s33, v23
	s_nop 1
	v_cndmask_b32_e64 v51, 0, 1, s[48:49]
	v_cmp_ge_f32_e64 s[48:49], v2, v23
	s_nop 1
	v_cndmask_b32_e64 v52, 0, 1, s[48:49]
	v_cmp_ge_f32_e64 s[48:49], v3, v23
	s_nop 1
	v_addc_co_u32_e64 v51, s[48:49], v51, v52, s[48:49]
	v_cmp_ge_f32_e64 s[48:49], v4, v23
	s_nop 1
	v_cndmask_b32_e64 v52, 0, 1, s[48:49]
	v_cmp_ge_f32_e64 s[48:49], v5, v23
	s_nop 1
	v_addc_co_u32_e64 v51, s[48:49], v51, v52, s[48:49]
	v_cmp_ge_f32_e64 s[48:49], v6, v23
	s_nop 1
	v_cndmask_b32_e64 v52, 0, 1, s[48:49]
	v_cmp_ge_f32_e64 s[48:49], v1, v23
	s_nop 1
	v_addc_co_u32_e64 v51, s[48:49], v51, v52, s[48:49]
	v_cmp_ge_f32_e64 s[48:49], v8, v23
	s_nop 1
	v_cndmask_b32_e64 v52, 0, 1, s[48:49]
	v_cmp_gt_f32_e64 s[48:49], v27, v23
	s_nop 1
	v_addc_co_u32_e64 v51, s[48:49], v51, v52, s[48:49]
	v_cmp_ge_f32_e64 s[48:49], v0, v23
	s_nop 1
	v_cndmask_b32_e64 v52, 0, 1, s[48:49]
	v_cmp_ge_f32_e64 s[48:49], v12, v23
	s_nop 1
	v_addc_co_u32_e64 v51, s[48:49], v51, v52, s[48:49]
	v_cmp_ge_f32_e64 s[48:49], v7, v23
	s_nop 1
	v_cndmask_b32_e64 v52, 0, 1, s[48:49]
	v_cmp_ge_f32_e64 s[48:49], v13, v23
	s_nop 1
	v_addc_co_u32_e64 v51, s[48:49], v51, v52, s[48:49]
	v_cmp_ge_f32_e64 s[48:49], v9, v23
	s_nop 1
	v_cndmask_b32_e64 v52, 0, 1, s[48:49]
	v_cmp_ge_f32_e64 s[48:49], v14, v23
	s_nop 1
	v_addc_co_u32_e64 v51, s[48:49], v51, v52, s[48:49]
	v_cmp_ge_f32_e64 s[48:49], v10, v23
	s_nop 1
	v_cndmask_b32_e64 v52, 0, 1, s[48:49]
	v_cmp_ge_f32_e64 s[48:49], v15, v23
	s_nop 1
	v_addc_co_u32_e64 v51, s[48:49], v51, v52, s[48:49]
	v_cmp_ge_f32_e64 s[48:49], v11, v23
	s_nop 1
	v_cndmask_b32_e64 v52, 0, 1, s[48:49]
	v_cmp_ge_f32_e64 s[48:49], v20, v23
	s_nop 1
	v_addc_co_u32_e64 v51, s[48:49], v51, v52, s[48:49]
	v_cmp_ge_f32_e64 s[48:49], v16, v23
	s_nop 1
	v_cndmask_b32_e64 v52, 0, 1, s[48:49]
	v_cmp_ge_f32_e64 s[48:49], v21, v23
	s_nop 1
	v_addc_co_u32_e64 v51, s[48:49], v51, v52, s[48:49]
	v_cmp_ge_f32_e64 s[48:49], v17, v23
	s_nop 1
	v_cndmask_b32_e64 v52, 0, 1, s[48:49]
	v_cmp_ge_f32_e64 s[48:49], v22, v23
	s_nop 1
	v_addc_co_u32_e64 v51, s[48:49], v51, v52, s[48:49]
	v_cmp_ge_f32_e64 s[48:49], v18, v23
	s_nop 1
	v_cndmask_b32_e64 v52, 0, 1, s[48:49]
	v_cmp_gt_f32_e64 s[48:49], v19, v23
	s_nop 1
	v_addc_co_u32_e64 v51, s[48:49], v51, v52, s[48:49]
	v_cmp_gt_f32_e64 s[48:49], v30, v23
	s_nop 1
	v_cndmask_b32_e64 v52, 0, 1, s[48:49]
	v_cmp_gt_f32_e64 s[48:49], v24, v23
	s_nop 1
	v_addc_co_u32_e64 v51, s[48:49], v51, v52, s[48:49]
	v_cmp_gt_f32_e64 s[48:49], v33, v23
	s_nop 1
	v_cndmask_b32_e64 v52, 0, 1, s[48:49]
	v_cmp_gt_f32_e64 s[48:49], v25, v23
	s_nop 1
	v_addc_co_u32_e64 v51, s[48:49], v51, v52, s[48:49]
	v_cmp_gt_f32_e64 s[48:49], v36, v23
	s_nop 1
	v_cndmask_b32_e64 v52, 0, 1, s[48:49]
	v_cmp_gt_f32_e64 s[48:49], v26, v23
	s_nop 1
	v_addc_co_u32_e64 v51, s[48:49], v51, v52, s[48:49]
	v_cmp_lt_u32_e64 s[48:49], 15, v51
	s_or_b64 s[46:47], s[48:49], s[46:47]
	v_cndmask_b32_e64 v51, v171, 0, s[46:47]
	v_cmp_ge_f32_e64 s[46:47], s33, v18
	s_nop 1
	v_cndmask_b32_e64 v52, 0, 1, s[46:47]
	v_cmp_ge_f32_e64 s[46:47], v2, v18
	s_nop 1
	v_cndmask_b32_e64 v53, 0, 1, s[46:47]
	v_cmp_ge_f32_e64 s[46:47], v3, v18
	s_nop 1
	v_addc_co_u32_e64 v52, s[46:47], v52, v53, s[46:47]
	v_cmp_ge_f32_e64 s[46:47], v4, v18
	s_nop 1
	v_cndmask_b32_e64 v53, 0, 1, s[46:47]
	v_cmp_ge_f32_e64 s[46:47], v5, v18
	s_nop 1
	v_addc_co_u32_e64 v52, s[46:47], v52, v53, s[46:47]
	v_cmp_ge_f32_e64 s[46:47], v6, v18
	s_nop 1
	v_cndmask_b32_e64 v53, 0, 1, s[46:47]
	v_cmp_ge_f32_e64 s[46:47], v1, v18
	s_nop 1
	v_addc_co_u32_e64 v52, s[46:47], v52, v53, s[46:47]
	v_cmp_ge_f32_e64 s[46:47], v8, v18
	s_nop 1
	v_cndmask_b32_e64 v53, 0, 1, s[46:47]
	v_cmp_gt_f32_e64 s[46:47], v27, v18
	s_nop 1
	v_addc_co_u32_e64 v52, s[46:47], v52, v53, s[46:47]
	v_cmp_ge_f32_e64 s[46:47], v0, v18
	s_nop 1
	v_cndmask_b32_e64 v53, 0, 1, s[46:47]
	v_cmp_ge_f32_e64 s[46:47], v12, v18
	s_nop 1
	v_addc_co_u32_e64 v52, s[46:47], v52, v53, s[46:47]
	v_cmp_ge_f32_e64 s[46:47], v7, v18
	s_nop 1
	v_cndmask_b32_e64 v53, 0, 1, s[46:47]
	v_cmp_ge_f32_e64 s[46:47], v13, v18
	s_nop 1
	v_addc_co_u32_e64 v52, s[46:47], v52, v53, s[46:47]
	v_cmp_ge_f32_e64 s[46:47], v9, v18
	s_nop 1
	v_cndmask_b32_e64 v53, 0, 1, s[46:47]
	v_cmp_ge_f32_e64 s[46:47], v14, v18
	s_nop 1
	v_addc_co_u32_e64 v52, s[46:47], v52, v53, s[46:47]
	v_cmp_ge_f32_e64 s[46:47], v10, v18
	s_nop 1
	v_cndmask_b32_e64 v53, 0, 1, s[46:47]
	v_cmp_ge_f32_e64 s[46:47], v15, v18
	s_nop 1
	v_addc_co_u32_e64 v52, s[46:47], v52, v53, s[46:47]
	v_cmp_ge_f32_e64 s[46:47], v11, v18
	s_nop 1
	v_cndmask_b32_e64 v53, 0, 1, s[46:47]
	v_cmp_ge_f32_e64 s[46:47], v20, v18
	s_nop 1
	v_addc_co_u32_e64 v52, s[46:47], v52, v53, s[46:47]
	v_cmp_ge_f32_e64 s[46:47], v16, v18
	s_nop 1
	v_cndmask_b32_e64 v53, 0, 1, s[46:47]
	v_cmp_ge_f32_e64 s[46:47], v21, v18
	s_nop 1
	v_addc_co_u32_e64 v52, s[46:47], v52, v53, s[46:47]
	v_cmp_ge_f32_e64 s[46:47], v17, v18
	s_nop 1
	v_cndmask_b32_e64 v53, 0, 1, s[46:47]
	v_cmp_ge_f32_e64 s[46:47], v22, v18
	s_nop 1
	v_addc_co_u32_e64 v52, s[46:47], v52, v53, s[46:47]
	v_cmp_gt_f32_e64 s[46:47], v23, v18
	s_nop 1
	v_cndmask_b32_e64 v53, 0, 1, s[46:47]
	v_cmp_gt_f32_e64 s[46:47], v19, v18
	s_nop 1
	v_addc_co_u32_e64 v52, s[46:47], v52, v53, s[46:47]
	v_cmp_gt_f32_e64 s[46:47], v30, v18
	s_nop 1
	v_cndmask_b32_e64 v53, 0, 1, s[46:47]
	v_cmp_gt_f32_e64 s[46:47], v24, v18
	s_nop 1
	v_addc_co_u32_e64 v52, s[46:47], v52, v53, s[46:47]
	v_cmp_gt_f32_e64 s[46:47], v33, v18
	s_nop 1
	v_cndmask_b32_e64 v53, 0, 1, s[46:47]
	v_cmp_gt_f32_e64 s[46:47], v25, v18
	s_nop 1
	v_addc_co_u32_e64 v52, s[46:47], v52, v53, s[46:47]
	v_cmp_gt_f32_e64 s[46:47], v36, v18
	s_nop 1
	v_cndmask_b32_e64 v53, 0, 1, s[46:47]
	v_cmp_gt_f32_e64 s[46:47], v26, v18
	s_nop 1
	v_addc_co_u32_e64 v52, s[46:47], v52, v53, s[46:47]
	v_cmp_lt_u32_e64 s[46:47], 15, v52
	s_or_b64 s[44:45], s[46:47], s[44:45]
	v_cndmask_b32_e64 v52, v172, 0, s[44:45]
	v_cmp_ge_f32_e64 s[44:45], s33, v22
	s_nop 1
	v_cndmask_b32_e64 v53, 0, 1, s[44:45]
	v_cmp_ge_f32_e64 s[44:45], v2, v22
	s_nop 1
	v_cndmask_b32_e64 v54, 0, 1, s[44:45]
	v_cmp_ge_f32_e64 s[44:45], v3, v22
	s_nop 1
	v_addc_co_u32_e64 v53, s[44:45], v53, v54, s[44:45]
	v_cmp_ge_f32_e64 s[44:45], v4, v22
	s_nop 1
	v_cndmask_b32_e64 v54, 0, 1, s[44:45]
	v_cmp_ge_f32_e64 s[44:45], v5, v22
	s_nop 1
	v_addc_co_u32_e64 v53, s[44:45], v53, v54, s[44:45]
	v_cmp_ge_f32_e64 s[44:45], v6, v22
	s_nop 1
	v_cndmask_b32_e64 v54, 0, 1, s[44:45]
	v_cmp_ge_f32_e64 s[44:45], v1, v22
	s_nop 1
	v_addc_co_u32_e64 v53, s[44:45], v53, v54, s[44:45]
	v_cmp_ge_f32_e64 s[44:45], v8, v22
	s_nop 1
	v_cndmask_b32_e64 v54, 0, 1, s[44:45]
	v_cmp_gt_f32_e64 s[44:45], v27, v22
	s_nop 1
	v_addc_co_u32_e64 v53, s[44:45], v53, v54, s[44:45]
	v_cmp_ge_f32_e64 s[44:45], v0, v22
	s_nop 1
	v_cndmask_b32_e64 v54, 0, 1, s[44:45]
	v_cmp_ge_f32_e64 s[44:45], v12, v22
	s_nop 1
	v_addc_co_u32_e64 v53, s[44:45], v53, v54, s[44:45]
	v_cmp_ge_f32_e64 s[44:45], v7, v22
	s_nop 1
	v_cndmask_b32_e64 v54, 0, 1, s[44:45]
	v_cmp_ge_f32_e64 s[44:45], v13, v22
	s_nop 1
	v_addc_co_u32_e64 v53, s[44:45], v53, v54, s[44:45]
	v_cmp_ge_f32_e64 s[44:45], v9, v22
	s_nop 1
	v_cndmask_b32_e64 v54, 0, 1, s[44:45]
	v_cmp_ge_f32_e64 s[44:45], v14, v22
	s_nop 1
	v_addc_co_u32_e64 v53, s[44:45], v53, v54, s[44:45]
	v_cmp_ge_f32_e64 s[44:45], v10, v22
	s_nop 1
	v_cndmask_b32_e64 v54, 0, 1, s[44:45]
	v_cmp_ge_f32_e64 s[44:45], v15, v22
	s_nop 1
	v_addc_co_u32_e64 v53, s[44:45], v53, v54, s[44:45]
	v_cmp_ge_f32_e64 s[44:45], v11, v22
	s_nop 1
	v_cndmask_b32_e64 v54, 0, 1, s[44:45]
	v_cmp_ge_f32_e64 s[44:45], v20, v22
	s_nop 1
	v_addc_co_u32_e64 v53, s[44:45], v53, v54, s[44:45]
	v_cmp_ge_f32_e64 s[44:45], v16, v22
	s_nop 1
	v_cndmask_b32_e64 v54, 0, 1, s[44:45]
	v_cmp_ge_f32_e64 s[44:45], v21, v22
	s_nop 1
	v_addc_co_u32_e64 v53, s[44:45], v53, v54, s[44:45]
	v_cmp_ge_f32_e64 s[44:45], v17, v22
	s_nop 1
	v_cndmask_b32_e64 v54, 0, 1, s[44:45]
	v_cmp_gt_f32_e64 s[44:45], v18, v22
	s_nop 1
	v_addc_co_u32_e64 v53, s[44:45], v53, v54, s[44:45]
	v_cmp_gt_f32_e64 s[44:45], v23, v22
	s_nop 1
	v_cndmask_b32_e64 v54, 0, 1, s[44:45]
	v_cmp_gt_f32_e64 s[44:45], v19, v22
	s_nop 1
	v_addc_co_u32_e64 v53, s[44:45], v53, v54, s[44:45]
	v_cmp_gt_f32_e64 s[44:45], v30, v22
	s_nop 1
	v_cndmask_b32_e64 v54, 0, 1, s[44:45]
	v_cmp_gt_f32_e64 s[44:45], v24, v22
	s_nop 1
	v_addc_co_u32_e64 v53, s[44:45], v53, v54, s[44:45]
	v_cmp_gt_f32_e64 s[44:45], v33, v22
	s_nop 1
	v_cndmask_b32_e64 v54, 0, 1, s[44:45]
	v_cmp_gt_f32_e64 s[44:45], v25, v22
	s_nop 1
	v_addc_co_u32_e64 v53, s[44:45], v53, v54, s[44:45]
	v_cmp_gt_f32_e64 s[44:45], v36, v22
	s_nop 1
	v_cndmask_b32_e64 v54, 0, 1, s[44:45]
	v_cmp_gt_f32_e64 s[44:45], v26, v22
	s_nop 1
	v_addc_co_u32_e64 v53, s[44:45], v53, v54, s[44:45]
	v_cmp_lt_u32_e64 s[44:45], 15, v53
	s_or_b64 s[42:43], s[44:45], s[42:43]
	v_cndmask_b32_e64 v53, v173, 0, s[42:43]
	v_cmp_ge_f32_e64 s[42:43], s33, v17
	s_nop 1
	v_cndmask_b32_e64 v54, 0, 1, s[42:43]
	v_cmp_ge_f32_e64 s[42:43], v2, v17
	s_nop 1
	v_cndmask_b32_e64 v55, 0, 1, s[42:43]
	v_cmp_ge_f32_e64 s[42:43], v3, v17
	s_nop 1
	v_addc_co_u32_e64 v54, s[42:43], v54, v55, s[42:43]
	v_cmp_ge_f32_e64 s[42:43], v4, v17
	s_nop 1
	v_cndmask_b32_e64 v55, 0, 1, s[42:43]
	v_cmp_ge_f32_e64 s[42:43], v5, v17
	s_nop 1
	v_addc_co_u32_e64 v54, s[42:43], v54, v55, s[42:43]
	v_cmp_ge_f32_e64 s[42:43], v6, v17
	s_nop 1
	v_cndmask_b32_e64 v55, 0, 1, s[42:43]
	v_cmp_ge_f32_e64 s[42:43], v1, v17
	s_nop 1
	v_addc_co_u32_e64 v54, s[42:43], v54, v55, s[42:43]
	v_cmp_ge_f32_e64 s[42:43], v8, v17
	s_nop 1
	v_cndmask_b32_e64 v55, 0, 1, s[42:43]
	v_cmp_gt_f32_e64 s[42:43], v27, v17
	s_nop 1
	v_addc_co_u32_e64 v54, s[42:43], v54, v55, s[42:43]
	v_cmp_ge_f32_e64 s[42:43], v0, v17
	s_nop 1
	v_cndmask_b32_e64 v55, 0, 1, s[42:43]
	v_cmp_ge_f32_e64 s[42:43], v12, v17
	s_nop 1
	v_addc_co_u32_e64 v54, s[42:43], v54, v55, s[42:43]
	v_cmp_ge_f32_e64 s[42:43], v7, v17
	s_nop 1
	v_cndmask_b32_e64 v55, 0, 1, s[42:43]
	v_cmp_ge_f32_e64 s[42:43], v13, v17
	s_nop 1
	v_addc_co_u32_e64 v54, s[42:43], v54, v55, s[42:43]
	v_cmp_ge_f32_e64 s[42:43], v9, v17
	s_nop 1
	v_cndmask_b32_e64 v55, 0, 1, s[42:43]
	v_cmp_ge_f32_e64 s[42:43], v14, v17
	s_nop 1
	v_addc_co_u32_e64 v54, s[42:43], v54, v55, s[42:43]
	v_cmp_ge_f32_e64 s[42:43], v10, v17
	s_nop 1
	v_cndmask_b32_e64 v55, 0, 1, s[42:43]
	v_cmp_ge_f32_e64 s[42:43], v15, v17
	s_nop 1
	v_addc_co_u32_e64 v54, s[42:43], v54, v55, s[42:43]
	v_cmp_ge_f32_e64 s[42:43], v11, v17
	s_nop 1
	v_cndmask_b32_e64 v55, 0, 1, s[42:43]
	v_cmp_ge_f32_e64 s[42:43], v20, v17
	s_nop 1
	v_addc_co_u32_e64 v54, s[42:43], v54, v55, s[42:43]
	v_cmp_ge_f32_e64 s[42:43], v16, v17
	s_nop 1
	v_cndmask_b32_e64 v55, 0, 1, s[42:43]
	v_cmp_ge_f32_e64 s[42:43], v21, v17
	s_nop 1
	v_addc_co_u32_e64 v54, s[42:43], v54, v55, s[42:43]
	v_cmp_gt_f32_e64 s[42:43], v22, v17
	s_nop 1
	v_cndmask_b32_e64 v55, 0, 1, s[42:43]
	v_cmp_gt_f32_e64 s[42:43], v18, v17
	s_nop 1
	v_addc_co_u32_e64 v54, s[42:43], v54, v55, s[42:43]
	v_cmp_gt_f32_e64 s[42:43], v23, v17
	s_nop 1
	v_cndmask_b32_e64 v55, 0, 1, s[42:43]
	v_cmp_gt_f32_e64 s[42:43], v19, v17
	s_nop 1
	v_addc_co_u32_e64 v54, s[42:43], v54, v55, s[42:43]
	v_cmp_gt_f32_e64 s[42:43], v30, v17
	s_nop 1
	v_cndmask_b32_e64 v55, 0, 1, s[42:43]
	v_cmp_gt_f32_e64 s[42:43], v24, v17
	s_nop 1
	v_addc_co_u32_e64 v54, s[42:43], v54, v55, s[42:43]
	v_cmp_gt_f32_e64 s[42:43], v33, v17
	s_nop 1
	v_cndmask_b32_e64 v55, 0, 1, s[42:43]
	v_cmp_gt_f32_e64 s[42:43], v25, v17
	s_nop 1
	v_addc_co_u32_e64 v54, s[42:43], v54, v55, s[42:43]
	v_cmp_gt_f32_e64 s[42:43], v36, v17
	s_nop 1
	v_cndmask_b32_e64 v55, 0, 1, s[42:43]
	v_cmp_gt_f32_e64 s[42:43], v26, v17
	s_nop 1
	v_addc_co_u32_e64 v54, s[42:43], v54, v55, s[42:43]
	v_cmp_lt_u32_e64 s[42:43], 15, v54
	s_or_b64 s[40:41], s[42:43], s[40:41]
	v_cndmask_b32_e64 v54, v174, 0, s[40:41]
	v_cmp_ge_f32_e64 s[40:41], s33, v21
	s_nop 1
	v_cndmask_b32_e64 v55, 0, 1, s[40:41]
	v_cmp_ge_f32_e64 s[40:41], v2, v21
	s_nop 1
	v_cndmask_b32_e64 v56, 0, 1, s[40:41]
	v_cmp_ge_f32_e64 s[40:41], v3, v21
	s_nop 1
	v_addc_co_u32_e64 v55, s[40:41], v55, v56, s[40:41]
	v_cmp_ge_f32_e64 s[40:41], v4, v21
	s_nop 1
	v_cndmask_b32_e64 v56, 0, 1, s[40:41]
	v_cmp_ge_f32_e64 s[40:41], v5, v21
	s_nop 1
	v_addc_co_u32_e64 v55, s[40:41], v55, v56, s[40:41]
	v_cmp_ge_f32_e64 s[40:41], v6, v21
	s_nop 1
	v_cndmask_b32_e64 v56, 0, 1, s[40:41]
	v_cmp_ge_f32_e64 s[40:41], v1, v21
	s_nop 1
	v_addc_co_u32_e64 v55, s[40:41], v55, v56, s[40:41]
	v_cmp_ge_f32_e64 s[40:41], v8, v21
	s_nop 1
	v_cndmask_b32_e64 v56, 0, 1, s[40:41]
	v_cmp_gt_f32_e64 s[40:41], v27, v21
	s_nop 1
	v_addc_co_u32_e64 v55, s[40:41], v55, v56, s[40:41]
	v_cmp_ge_f32_e64 s[40:41], v0, v21
	s_nop 1
	v_cndmask_b32_e64 v56, 0, 1, s[40:41]
	v_cmp_ge_f32_e64 s[40:41], v12, v21
	s_nop 1
	v_addc_co_u32_e64 v55, s[40:41], v55, v56, s[40:41]
	v_cmp_ge_f32_e64 s[40:41], v7, v21
	s_nop 1
	v_cndmask_b32_e64 v56, 0, 1, s[40:41]
	v_cmp_ge_f32_e64 s[40:41], v13, v21
	s_nop 1
	v_addc_co_u32_e64 v55, s[40:41], v55, v56, s[40:41]
	v_cmp_ge_f32_e64 s[40:41], v9, v21
	s_nop 1
	v_cndmask_b32_e64 v56, 0, 1, s[40:41]
	v_cmp_ge_f32_e64 s[40:41], v14, v21
	s_nop 1
	v_addc_co_u32_e64 v55, s[40:41], v55, v56, s[40:41]
	v_cmp_ge_f32_e64 s[40:41], v10, v21
	s_nop 1
	v_cndmask_b32_e64 v56, 0, 1, s[40:41]
	v_cmp_ge_f32_e64 s[40:41], v15, v21
	s_nop 1
	v_addc_co_u32_e64 v55, s[40:41], v55, v56, s[40:41]
	v_cmp_ge_f32_e64 s[40:41], v11, v21
	s_nop 1
	v_cndmask_b32_e64 v56, 0, 1, s[40:41]
	v_cmp_ge_f32_e64 s[40:41], v20, v21
	s_nop 1
	v_addc_co_u32_e64 v55, s[40:41], v55, v56, s[40:41]
	v_cmp_ge_f32_e64 s[40:41], v16, v21
	s_nop 1
	v_cndmask_b32_e64 v56, 0, 1, s[40:41]
	v_cmp_gt_f32_e64 s[40:41], v17, v21
	s_nop 1
	v_addc_co_u32_e64 v55, s[40:41], v55, v56, s[40:41]
	v_cmp_gt_f32_e64 s[40:41], v22, v21
	s_nop 1
	v_cndmask_b32_e64 v56, 0, 1, s[40:41]
	v_cmp_gt_f32_e64 s[40:41], v18, v21
	s_nop 1
	v_addc_co_u32_e64 v55, s[40:41], v55, v56, s[40:41]
	v_cmp_gt_f32_e64 s[40:41], v23, v21
	s_nop 1
	v_cndmask_b32_e64 v56, 0, 1, s[40:41]
	v_cmp_gt_f32_e64 s[40:41], v19, v21
	s_nop 1
	v_addc_co_u32_e64 v55, s[40:41], v55, v56, s[40:41]
	v_cmp_gt_f32_e64 s[40:41], v30, v21
	s_nop 1
	v_cndmask_b32_e64 v56, 0, 1, s[40:41]
	v_cmp_gt_f32_e64 s[40:41], v24, v21
	s_nop 1
	v_addc_co_u32_e64 v55, s[40:41], v55, v56, s[40:41]
	v_cmp_gt_f32_e64 s[40:41], v33, v21
	s_nop 1
	v_cndmask_b32_e64 v56, 0, 1, s[40:41]
	v_cmp_gt_f32_e64 s[40:41], v25, v21
	s_nop 1
	v_addc_co_u32_e64 v55, s[40:41], v55, v56, s[40:41]
	v_cmp_gt_f32_e64 s[40:41], v36, v21
	s_nop 1
	v_cndmask_b32_e64 v56, 0, 1, s[40:41]
	v_cmp_gt_f32_e64 s[40:41], v26, v21
	s_nop 1
	v_addc_co_u32_e64 v55, s[40:41], v55, v56, s[40:41]
	v_cmp_lt_u32_e64 s[40:41], 15, v55
	s_or_b64 s[38:39], s[40:41], s[38:39]
	v_cndmask_b32_e64 v55, v175, 0, s[38:39]
	v_cmp_ge_f32_e64 s[38:39], s33, v16
	s_nop 1
	v_cndmask_b32_e64 v56, 0, 1, s[38:39]
	v_cmp_ge_f32_e64 s[38:39], v2, v16
	s_nop 1
	v_cndmask_b32_e64 v57, 0, 1, s[38:39]
	v_cmp_ge_f32_e64 s[38:39], v3, v16
	s_nop 1
	v_addc_co_u32_e64 v56, s[38:39], v56, v57, s[38:39]
	v_cmp_ge_f32_e64 s[38:39], v4, v16
	s_nop 1
	v_cndmask_b32_e64 v57, 0, 1, s[38:39]
	v_cmp_ge_f32_e64 s[38:39], v5, v16
	s_nop 1
	v_addc_co_u32_e64 v56, s[38:39], v56, v57, s[38:39]
	v_cmp_ge_f32_e64 s[38:39], v6, v16
	s_nop 1
	v_cndmask_b32_e64 v57, 0, 1, s[38:39]
	v_cmp_ge_f32_e64 s[38:39], v1, v16
	s_nop 1
	v_addc_co_u32_e64 v56, s[38:39], v56, v57, s[38:39]
	v_cmp_ge_f32_e64 s[38:39], v8, v16
	s_nop 1
	v_cndmask_b32_e64 v57, 0, 1, s[38:39]
	v_cmp_gt_f32_e64 s[38:39], v27, v16
	s_nop 1
	v_addc_co_u32_e64 v56, s[38:39], v56, v57, s[38:39]
	v_cmp_ge_f32_e64 s[38:39], v0, v16
	s_nop 1
	v_cndmask_b32_e64 v57, 0, 1, s[38:39]
	v_cmp_ge_f32_e64 s[38:39], v12, v16
	s_nop 1
	v_addc_co_u32_e64 v56, s[38:39], v56, v57, s[38:39]
	v_cmp_ge_f32_e64 s[38:39], v7, v16
	s_nop 1
	v_cndmask_b32_e64 v57, 0, 1, s[38:39]
	v_cmp_ge_f32_e64 s[38:39], v13, v16
	s_nop 1
	v_addc_co_u32_e64 v56, s[38:39], v56, v57, s[38:39]
	v_cmp_ge_f32_e64 s[38:39], v9, v16
	s_nop 1
	v_cndmask_b32_e64 v57, 0, 1, s[38:39]
	v_cmp_ge_f32_e64 s[38:39], v14, v16
	s_nop 1
	v_addc_co_u32_e64 v56, s[38:39], v56, v57, s[38:39]
	v_cmp_ge_f32_e64 s[38:39], v10, v16
	s_nop 1
	v_cndmask_b32_e64 v57, 0, 1, s[38:39]
	v_cmp_ge_f32_e64 s[38:39], v15, v16
	s_nop 1
	v_addc_co_u32_e64 v56, s[38:39], v56, v57, s[38:39]
	v_cmp_ge_f32_e64 s[38:39], v11, v16
	s_nop 1
	v_cndmask_b32_e64 v57, 0, 1, s[38:39]
	v_cmp_ge_f32_e64 s[38:39], v20, v16
	s_nop 1
	v_addc_co_u32_e64 v56, s[38:39], v56, v57, s[38:39]
	v_cmp_gt_f32_e64 s[38:39], v21, v16
	s_nop 1
	v_cndmask_b32_e64 v57, 0, 1, s[38:39]
	v_cmp_gt_f32_e64 s[38:39], v17, v16
	s_nop 1
	v_addc_co_u32_e64 v56, s[38:39], v56, v57, s[38:39]
	v_cmp_gt_f32_e64 s[38:39], v22, v16
	s_nop 1
	v_cndmask_b32_e64 v57, 0, 1, s[38:39]
	v_cmp_gt_f32_e64 s[38:39], v18, v16
	s_nop 1
	v_addc_co_u32_e64 v56, s[38:39], v56, v57, s[38:39]
	v_cmp_gt_f32_e64 s[38:39], v23, v16
	s_nop 1
	v_cndmask_b32_e64 v57, 0, 1, s[38:39]
	v_cmp_gt_f32_e64 s[38:39], v19, v16
	s_nop 1
	v_addc_co_u32_e64 v56, s[38:39], v56, v57, s[38:39]
	v_cmp_gt_f32_e64 s[38:39], v30, v16
	s_nop 1
	v_cndmask_b32_e64 v57, 0, 1, s[38:39]
	v_cmp_gt_f32_e64 s[38:39], v24, v16
	s_nop 1
	v_addc_co_u32_e64 v56, s[38:39], v56, v57, s[38:39]
	v_cmp_gt_f32_e64 s[38:39], v33, v16
	s_nop 1
	v_cndmask_b32_e64 v57, 0, 1, s[38:39]
	v_cmp_gt_f32_e64 s[38:39], v25, v16
	s_nop 1
	v_addc_co_u32_e64 v56, s[38:39], v56, v57, s[38:39]
	v_cmp_gt_f32_e64 s[38:39], v36, v16
	s_nop 1
	v_cndmask_b32_e64 v57, 0, 1, s[38:39]
	v_cmp_gt_f32_e64 s[38:39], v26, v16
	s_nop 1
	v_addc_co_u32_e64 v56, s[38:39], v56, v57, s[38:39]
	v_cmp_lt_u32_e64 s[38:39], 15, v56
	s_or_b64 s[36:37], s[38:39], s[36:37]
	v_cndmask_b32_e64 v56, v176, 0, s[36:37]
	v_cmp_ge_f32_e64 s[36:37], s33, v20
	s_nop 1
	v_cndmask_b32_e64 v57, 0, 1, s[36:37]
	v_cmp_ge_f32_e64 s[36:37], v2, v20
	s_nop 1
	v_cndmask_b32_e64 v58, 0, 1, s[36:37]
	v_cmp_ge_f32_e64 s[36:37], v3, v20
	s_nop 1
	v_addc_co_u32_e64 v57, s[36:37], v57, v58, s[36:37]
	v_cmp_ge_f32_e64 s[36:37], v4, v20
	s_nop 1
	v_cndmask_b32_e64 v58, 0, 1, s[36:37]
	v_cmp_ge_f32_e64 s[36:37], v5, v20
	s_nop 1
	v_addc_co_u32_e64 v57, s[36:37], v57, v58, s[36:37]
	v_cmp_ge_f32_e64 s[36:37], v6, v20
	s_nop 1
	v_cndmask_b32_e64 v58, 0, 1, s[36:37]
	v_cmp_ge_f32_e64 s[36:37], v1, v20
	s_nop 1
	v_addc_co_u32_e64 v57, s[36:37], v57, v58, s[36:37]
	v_cmp_ge_f32_e64 s[36:37], v8, v20
	s_nop 1
	v_cndmask_b32_e64 v58, 0, 1, s[36:37]
	v_cmp_gt_f32_e64 s[36:37], v27, v20
	s_nop 1
	v_addc_co_u32_e64 v57, s[36:37], v57, v58, s[36:37]
	v_cmp_ge_f32_e64 s[36:37], v0, v20
	s_nop 1
	v_cndmask_b32_e64 v58, 0, 1, s[36:37]
	v_cmp_ge_f32_e64 s[36:37], v12, v20
	s_nop 1
	v_addc_co_u32_e64 v57, s[36:37], v57, v58, s[36:37]
	v_cmp_ge_f32_e64 s[36:37], v7, v20
	s_nop 1
	v_cndmask_b32_e64 v58, 0, 1, s[36:37]
	v_cmp_ge_f32_e64 s[36:37], v13, v20
	s_nop 1
	v_addc_co_u32_e64 v57, s[36:37], v57, v58, s[36:37]
	v_cmp_ge_f32_e64 s[36:37], v9, v20
	s_nop 1
	v_cndmask_b32_e64 v58, 0, 1, s[36:37]
	v_cmp_ge_f32_e64 s[36:37], v14, v20
	s_nop 1
	v_addc_co_u32_e64 v57, s[36:37], v57, v58, s[36:37]
	v_cmp_ge_f32_e64 s[36:37], v10, v20
	s_nop 1
	v_cndmask_b32_e64 v58, 0, 1, s[36:37]
	v_cmp_ge_f32_e64 s[36:37], v15, v20
	s_nop 1
	v_addc_co_u32_e64 v57, s[36:37], v57, v58, s[36:37]
	v_cmp_ge_f32_e64 s[36:37], v11, v20
	s_nop 1
	v_cndmask_b32_e64 v58, 0, 1, s[36:37]
	v_cmp_gt_f32_e64 s[36:37], v16, v20
	s_nop 1
	v_addc_co_u32_e64 v57, s[36:37], v57, v58, s[36:37]
	v_cmp_gt_f32_e64 s[36:37], v21, v20
	s_nop 1
	v_cndmask_b32_e64 v58, 0, 1, s[36:37]
	v_cmp_gt_f32_e64 s[36:37], v17, v20
	s_nop 1
	v_addc_co_u32_e64 v57, s[36:37], v57, v58, s[36:37]
	v_cmp_gt_f32_e64 s[36:37], v22, v20
	s_nop 1
	v_cndmask_b32_e64 v58, 0, 1, s[36:37]
	v_cmp_gt_f32_e64 s[36:37], v18, v20
	s_nop 1
	v_addc_co_u32_e64 v57, s[36:37], v57, v58, s[36:37]
	v_cmp_gt_f32_e64 s[36:37], v23, v20
	s_nop 1
	v_cndmask_b32_e64 v58, 0, 1, s[36:37]
	v_cmp_gt_f32_e64 s[36:37], v19, v20
	s_nop 1
	v_addc_co_u32_e64 v57, s[36:37], v57, v58, s[36:37]
	v_cmp_gt_f32_e64 s[36:37], v30, v20
	s_nop 1
	v_cndmask_b32_e64 v58, 0, 1, s[36:37]
	v_cmp_gt_f32_e64 s[36:37], v24, v20
	s_nop 1
	v_addc_co_u32_e64 v57, s[36:37], v57, v58, s[36:37]
	v_cmp_gt_f32_e64 s[36:37], v33, v20
	s_nop 1
	v_cndmask_b32_e64 v58, 0, 1, s[36:37]
	v_cmp_gt_f32_e64 s[36:37], v25, v20
	s_nop 1
	v_addc_co_u32_e64 v57, s[36:37], v57, v58, s[36:37]
	v_cmp_gt_f32_e64 s[36:37], v36, v20
	s_nop 1
	v_cndmask_b32_e64 v58, 0, 1, s[36:37]
	v_cmp_gt_f32_e64 s[36:37], v26, v20
	s_nop 1
	v_addc_co_u32_e64 v57, s[36:37], v57, v58, s[36:37]
	v_cmp_lt_u32_e64 s[36:37], 15, v57
	s_or_b64 s[34:35], s[36:37], s[34:35]
	v_cndmask_b32_e64 v57, v177, 0, s[34:35]
	v_cmp_ge_f32_e64 s[34:35], s33, v11
	s_nop 1
	v_cndmask_b32_e64 v58, 0, 1, s[34:35]
	v_cmp_ge_f32_e64 s[34:35], v2, v11
	s_nop 1
	v_cndmask_b32_e64 v59, 0, 1, s[34:35]
	v_cmp_ge_f32_e64 s[34:35], v3, v11
	s_nop 1
	v_addc_co_u32_e64 v58, s[34:35], v58, v59, s[34:35]
	v_cmp_ge_f32_e64 s[34:35], v4, v11
	s_nop 1
	v_cndmask_b32_e64 v59, 0, 1, s[34:35]
	v_cmp_ge_f32_e64 s[34:35], v5, v11
	s_nop 1
	v_addc_co_u32_e64 v58, s[34:35], v58, v59, s[34:35]
	v_cmp_ge_f32_e64 s[34:35], v6, v11
	s_nop 1
	v_cndmask_b32_e64 v59, 0, 1, s[34:35]
	v_cmp_ge_f32_e64 s[34:35], v1, v11
	s_nop 1
	v_addc_co_u32_e64 v58, s[34:35], v58, v59, s[34:35]
	v_cmp_ge_f32_e64 s[34:35], v8, v11
	s_nop 1
	v_cndmask_b32_e64 v59, 0, 1, s[34:35]
	v_cmp_gt_f32_e64 s[34:35], v27, v11
	s_nop 1
	v_addc_co_u32_e64 v58, s[34:35], v58, v59, s[34:35]
	v_cmp_ge_f32_e64 s[34:35], v0, v11
	s_nop 1
	v_cndmask_b32_e64 v59, 0, 1, s[34:35]
	v_cmp_ge_f32_e64 s[34:35], v12, v11
	s_nop 1
	v_addc_co_u32_e64 v58, s[34:35], v58, v59, s[34:35]
	v_cmp_ge_f32_e64 s[34:35], v7, v11
	s_nop 1
	v_cndmask_b32_e64 v59, 0, 1, s[34:35]
	v_cmp_ge_f32_e64 s[34:35], v13, v11
	s_nop 1
	v_addc_co_u32_e64 v58, s[34:35], v58, v59, s[34:35]
	v_cmp_ge_f32_e64 s[34:35], v9, v11
	s_nop 1
	v_cndmask_b32_e64 v59, 0, 1, s[34:35]
	v_cmp_ge_f32_e64 s[34:35], v14, v11
	s_nop 1
	v_addc_co_u32_e64 v58, s[34:35], v58, v59, s[34:35]
	v_cmp_ge_f32_e64 s[34:35], v10, v11
	s_nop 1
	v_cndmask_b32_e64 v59, 0, 1, s[34:35]
	v_cmp_ge_f32_e64 s[34:35], v15, v11
	s_nop 1
	v_addc_co_u32_e64 v58, s[34:35], v58, v59, s[34:35]
	v_cmp_gt_f32_e64 s[34:35], v20, v11
	s_nop 1
	v_cndmask_b32_e64 v59, 0, 1, s[34:35]
	v_cmp_gt_f32_e64 s[34:35], v16, v11
	s_nop 1
	v_addc_co_u32_e64 v58, s[34:35], v58, v59, s[34:35]
	v_cmp_gt_f32_e64 s[34:35], v21, v11
	s_nop 1
	v_cndmask_b32_e64 v59, 0, 1, s[34:35]
	v_cmp_gt_f32_e64 s[34:35], v17, v11
	s_nop 1
	v_addc_co_u32_e64 v58, s[34:35], v58, v59, s[34:35]
	v_cmp_gt_f32_e64 s[34:35], v22, v11
	s_nop 1
	v_cndmask_b32_e64 v59, 0, 1, s[34:35]
	v_cmp_gt_f32_e64 s[34:35], v18, v11
	s_nop 1
	v_addc_co_u32_e64 v58, s[34:35], v58, v59, s[34:35]
	v_cmp_gt_f32_e64 s[34:35], v23, v11
	s_nop 1
	v_cndmask_b32_e64 v59, 0, 1, s[34:35]
	v_cmp_gt_f32_e64 s[34:35], v19, v11
	s_nop 1
	v_addc_co_u32_e64 v58, s[34:35], v58, v59, s[34:35]
	v_cmp_gt_f32_e64 s[34:35], v30, v11
	s_nop 1
	v_cndmask_b32_e64 v59, 0, 1, s[34:35]
	v_cmp_gt_f32_e64 s[34:35], v24, v11
	s_nop 1
	v_addc_co_u32_e64 v58, s[34:35], v58, v59, s[34:35]
	v_cmp_gt_f32_e64 s[34:35], v33, v11
	s_nop 1
	v_cndmask_b32_e64 v59, 0, 1, s[34:35]
	v_cmp_gt_f32_e64 s[34:35], v25, v11
	s_nop 1
	v_addc_co_u32_e64 v58, s[34:35], v58, v59, s[34:35]
	v_cmp_gt_f32_e64 s[34:35], v36, v11
	s_nop 1
	v_cndmask_b32_e64 v59, 0, 1, s[34:35]
	v_cmp_gt_f32_e64 s[34:35], v26, v11
	s_nop 1
	v_addc_co_u32_e64 v58, s[34:35], v58, v59, s[34:35]
	v_cmp_lt_u32_e64 s[34:35], 15, v58
	s_or_b64 s[30:31], s[34:35], s[30:31]
	v_cndmask_b32_e64 v58, v178, 0, s[30:31]
	v_cmp_ge_f32_e64 s[30:31], s33, v15
	s_nop 1
	v_cndmask_b32_e64 v59, 0, 1, s[30:31]
	v_cmp_ge_f32_e64 s[30:31], v2, v15
	s_nop 1
	v_cndmask_b32_e64 v60, 0, 1, s[30:31]
	v_cmp_ge_f32_e64 s[30:31], v3, v15
	s_nop 1
	v_addc_co_u32_e64 v59, s[30:31], v59, v60, s[30:31]
	v_cmp_ge_f32_e64 s[30:31], v4, v15
	s_nop 1
	v_cndmask_b32_e64 v60, 0, 1, s[30:31]
	v_cmp_ge_f32_e64 s[30:31], v5, v15
	s_nop 1
	v_addc_co_u32_e64 v59, s[30:31], v59, v60, s[30:31]
	v_cmp_ge_f32_e64 s[30:31], v6, v15
	s_nop 1
	v_cndmask_b32_e64 v60, 0, 1, s[30:31]
	v_cmp_ge_f32_e64 s[30:31], v1, v15
	s_nop 1
	v_addc_co_u32_e64 v59, s[30:31], v59, v60, s[30:31]
	v_cmp_ge_f32_e64 s[30:31], v8, v15
	s_nop 1
	v_cndmask_b32_e64 v60, 0, 1, s[30:31]
	v_cmp_gt_f32_e64 s[30:31], v27, v15
	s_nop 1
	v_addc_co_u32_e64 v59, s[30:31], v59, v60, s[30:31]
	v_cmp_ge_f32_e64 s[30:31], v0, v15
	s_nop 1
	v_cndmask_b32_e64 v60, 0, 1, s[30:31]
	v_cmp_ge_f32_e64 s[30:31], v12, v15
	s_nop 1
	v_addc_co_u32_e64 v59, s[30:31], v59, v60, s[30:31]
	v_cmp_ge_f32_e64 s[30:31], v7, v15
	s_nop 1
	v_cndmask_b32_e64 v60, 0, 1, s[30:31]
	v_cmp_ge_f32_e64 s[30:31], v13, v15
	s_nop 1
	v_addc_co_u32_e64 v59, s[30:31], v59, v60, s[30:31]
	v_cmp_ge_f32_e64 s[30:31], v9, v15
	s_nop 1
	v_cndmask_b32_e64 v60, 0, 1, s[30:31]
	v_cmp_ge_f32_e64 s[30:31], v14, v15
	s_nop 1
	v_addc_co_u32_e64 v59, s[30:31], v59, v60, s[30:31]
	v_cmp_ge_f32_e64 s[30:31], v10, v15
	s_nop 1
	v_cndmask_b32_e64 v60, 0, 1, s[30:31]
	v_cmp_gt_f32_e64 s[30:31], v11, v15
	s_nop 1
	v_addc_co_u32_e64 v59, s[30:31], v59, v60, s[30:31]
	v_cmp_gt_f32_e64 s[30:31], v20, v15
	s_nop 1
	v_cndmask_b32_e64 v60, 0, 1, s[30:31]
	v_cmp_gt_f32_e64 s[30:31], v16, v15
	s_nop 1
	v_addc_co_u32_e64 v59, s[30:31], v59, v60, s[30:31]
	v_cmp_gt_f32_e64 s[30:31], v21, v15
	s_nop 1
	v_cndmask_b32_e64 v60, 0, 1, s[30:31]
	v_cmp_gt_f32_e64 s[30:31], v17, v15
	s_nop 1
	v_addc_co_u32_e64 v59, s[30:31], v59, v60, s[30:31]
	v_cmp_gt_f32_e64 s[30:31], v22, v15
	s_nop 1
	v_cndmask_b32_e64 v60, 0, 1, s[30:31]
	v_cmp_gt_f32_e64 s[30:31], v18, v15
	s_nop 1
	v_addc_co_u32_e64 v59, s[30:31], v59, v60, s[30:31]
	v_cmp_gt_f32_e64 s[30:31], v23, v15
	s_nop 1
	v_cndmask_b32_e64 v60, 0, 1, s[30:31]
	v_cmp_gt_f32_e64 s[30:31], v19, v15
	s_nop 1
	v_addc_co_u32_e64 v59, s[30:31], v59, v60, s[30:31]
	v_cmp_gt_f32_e64 s[30:31], v30, v15
	s_nop 1
	v_cndmask_b32_e64 v60, 0, 1, s[30:31]
	v_cmp_gt_f32_e64 s[30:31], v24, v15
	s_nop 1
	v_addc_co_u32_e64 v59, s[30:31], v59, v60, s[30:31]
	v_cmp_gt_f32_e64 s[30:31], v33, v15
	s_nop 1
	v_cndmask_b32_e64 v60, 0, 1, s[30:31]
	v_cmp_gt_f32_e64 s[30:31], v25, v15
	s_nop 1
	v_addc_co_u32_e64 v59, s[30:31], v59, v60, s[30:31]
	v_cmp_gt_f32_e64 s[30:31], v36, v15
	s_nop 1
	v_cndmask_b32_e64 v60, 0, 1, s[30:31]
	v_cmp_gt_f32_e64 s[30:31], v26, v15
	s_nop 1
	v_addc_co_u32_e64 v59, s[30:31], v59, v60, s[30:31]
	v_cmp_lt_u32_e64 s[30:31], 15, v59
	s_or_b64 s[28:29], s[30:31], s[28:29]
	v_cndmask_b32_e64 v59, v179, 0, s[28:29]
	v_cmp_ge_f32_e64 s[28:29], s33, v10
	s_nop 1
	v_cndmask_b32_e64 v60, 0, 1, s[28:29]
	v_cmp_ge_f32_e64 s[28:29], v2, v10
	s_nop 1
	v_cndmask_b32_e64 v61, 0, 1, s[28:29]
	v_cmp_ge_f32_e64 s[28:29], v3, v10
	s_nop 1
	v_addc_co_u32_e64 v60, s[28:29], v60, v61, s[28:29]
	v_cmp_ge_f32_e64 s[28:29], v4, v10
	s_nop 1
	v_cndmask_b32_e64 v61, 0, 1, s[28:29]
	v_cmp_ge_f32_e64 s[28:29], v5, v10
	s_nop 1
	v_addc_co_u32_e64 v60, s[28:29], v60, v61, s[28:29]
	v_cmp_ge_f32_e64 s[28:29], v6, v10
	s_nop 1
	v_cndmask_b32_e64 v61, 0, 1, s[28:29]
	v_cmp_ge_f32_e64 s[28:29], v1, v10
	s_nop 1
	v_addc_co_u32_e64 v60, s[28:29], v60, v61, s[28:29]
	v_cmp_ge_f32_e64 s[28:29], v8, v10
	s_nop 1
	v_cndmask_b32_e64 v61, 0, 1, s[28:29]
	v_cmp_gt_f32_e64 s[28:29], v27, v10
	s_nop 1
	v_addc_co_u32_e64 v60, s[28:29], v60, v61, s[28:29]
	v_cmp_ge_f32_e64 s[28:29], v0, v10
	s_nop 1
	v_cndmask_b32_e64 v61, 0, 1, s[28:29]
	v_cmp_ge_f32_e64 s[28:29], v12, v10
	s_nop 1
	v_addc_co_u32_e64 v60, s[28:29], v60, v61, s[28:29]
	v_cmp_ge_f32_e64 s[28:29], v7, v10
	s_nop 1
	v_cndmask_b32_e64 v61, 0, 1, s[28:29]
	v_cmp_ge_f32_e64 s[28:29], v13, v10
	s_nop 1
	v_addc_co_u32_e64 v60, s[28:29], v60, v61, s[28:29]
	v_cmp_ge_f32_e64 s[28:29], v9, v10
	s_nop 1
	v_cndmask_b32_e64 v61, 0, 1, s[28:29]
	v_cmp_ge_f32_e64 s[28:29], v14, v10
	s_nop 1
	v_addc_co_u32_e64 v60, s[28:29], v60, v61, s[28:29]
	v_cmp_gt_f32_e64 s[28:29], v15, v10
	s_nop 1
	v_cndmask_b32_e64 v61, 0, 1, s[28:29]
	v_cmp_gt_f32_e64 s[28:29], v11, v10
	s_nop 1
	v_addc_co_u32_e64 v60, s[28:29], v60, v61, s[28:29]
	v_cmp_gt_f32_e64 s[28:29], v20, v10
	s_nop 1
	v_cndmask_b32_e64 v61, 0, 1, s[28:29]
	v_cmp_gt_f32_e64 s[28:29], v16, v10
	s_nop 1
	v_addc_co_u32_e64 v60, s[28:29], v60, v61, s[28:29]
	v_cmp_gt_f32_e64 s[28:29], v21, v10
	s_nop 1
	v_cndmask_b32_e64 v61, 0, 1, s[28:29]
	v_cmp_gt_f32_e64 s[28:29], v17, v10
	s_nop 1
	v_addc_co_u32_e64 v60, s[28:29], v60, v61, s[28:29]
	v_cmp_gt_f32_e64 s[28:29], v22, v10
	s_nop 1
	v_cndmask_b32_e64 v61, 0, 1, s[28:29]
	v_cmp_gt_f32_e64 s[28:29], v18, v10
	s_nop 1
	v_addc_co_u32_e64 v60, s[28:29], v60, v61, s[28:29]
	v_cmp_gt_f32_e64 s[28:29], v23, v10
	s_nop 1
	v_cndmask_b32_e64 v61, 0, 1, s[28:29]
	v_cmp_gt_f32_e64 s[28:29], v19, v10
	s_nop 1
	v_addc_co_u32_e64 v60, s[28:29], v60, v61, s[28:29]
	v_cmp_gt_f32_e64 s[28:29], v30, v10
	s_nop 1
	v_cndmask_b32_e64 v61, 0, 1, s[28:29]
	v_cmp_gt_f32_e64 s[28:29], v24, v10
	s_nop 1
	v_addc_co_u32_e64 v60, s[28:29], v60, v61, s[28:29]
	v_cmp_gt_f32_e64 s[28:29], v33, v10
	s_nop 1
	v_cndmask_b32_e64 v61, 0, 1, s[28:29]
	v_cmp_gt_f32_e64 s[28:29], v25, v10
	s_nop 1
	v_addc_co_u32_e64 v60, s[28:29], v60, v61, s[28:29]
	v_cmp_gt_f32_e64 s[28:29], v36, v10
	s_nop 1
	v_cndmask_b32_e64 v61, 0, 1, s[28:29]
	v_cmp_gt_f32_e64 s[28:29], v26, v10
	s_nop 1
	v_addc_co_u32_e64 v60, s[28:29], v60, v61, s[28:29]
	v_cmp_lt_u32_e64 s[28:29], 15, v60
	s_or_b64 s[26:27], s[28:29], s[26:27]
	v_cndmask_b32_e64 v60, v180, 0, s[26:27]
	v_cmp_ge_f32_e64 s[26:27], s33, v14
	s_nop 1
	v_cndmask_b32_e64 v61, 0, 1, s[26:27]
	v_cmp_ge_f32_e64 s[26:27], v2, v14
	s_nop 1
	v_cndmask_b32_e64 v62, 0, 1, s[26:27]
	v_cmp_ge_f32_e64 s[26:27], v3, v14
	s_nop 1
	v_addc_co_u32_e64 v61, s[26:27], v61, v62, s[26:27]
	v_cmp_ge_f32_e64 s[26:27], v4, v14
	s_nop 1
	v_cndmask_b32_e64 v62, 0, 1, s[26:27]
	v_cmp_ge_f32_e64 s[26:27], v5, v14
	s_nop 1
	v_addc_co_u32_e64 v61, s[26:27], v61, v62, s[26:27]
	v_cmp_ge_f32_e64 s[26:27], v6, v14
	s_nop 1
	v_cndmask_b32_e64 v62, 0, 1, s[26:27]
	v_cmp_ge_f32_e64 s[26:27], v1, v14
	s_nop 1
	v_addc_co_u32_e64 v61, s[26:27], v61, v62, s[26:27]
	v_cmp_ge_f32_e64 s[26:27], v8, v14
	s_nop 1
	v_cndmask_b32_e64 v62, 0, 1, s[26:27]
	v_cmp_gt_f32_e64 s[26:27], v27, v14
	s_nop 1
	v_addc_co_u32_e64 v61, s[26:27], v61, v62, s[26:27]
	v_cmp_ge_f32_e64 s[26:27], v0, v14
	s_nop 1
	v_cndmask_b32_e64 v62, 0, 1, s[26:27]
	v_cmp_ge_f32_e64 s[26:27], v12, v14
	s_nop 1
	v_addc_co_u32_e64 v61, s[26:27], v61, v62, s[26:27]
	v_cmp_ge_f32_e64 s[26:27], v7, v14
	s_nop 1
	v_cndmask_b32_e64 v62, 0, 1, s[26:27]
	v_cmp_ge_f32_e64 s[26:27], v13, v14
	s_nop 1
	v_addc_co_u32_e64 v61, s[26:27], v61, v62, s[26:27]
	v_cmp_ge_f32_e64 s[26:27], v9, v14
	s_nop 1
	v_cndmask_b32_e64 v62, 0, 1, s[26:27]
	v_cmp_gt_f32_e64 s[26:27], v10, v14
	s_nop 1
	v_addc_co_u32_e64 v61, s[26:27], v61, v62, s[26:27]
	v_cmp_gt_f32_e64 s[26:27], v15, v14
	s_nop 1
	v_cndmask_b32_e64 v62, 0, 1, s[26:27]
	v_cmp_gt_f32_e64 s[26:27], v11, v14
	s_nop 1
	v_addc_co_u32_e64 v61, s[26:27], v61, v62, s[26:27]
	v_cmp_gt_f32_e64 s[26:27], v20, v14
	s_nop 1
	v_cndmask_b32_e64 v62, 0, 1, s[26:27]
	v_cmp_gt_f32_e64 s[26:27], v16, v14
	s_nop 1
	v_addc_co_u32_e64 v61, s[26:27], v61, v62, s[26:27]
	v_cmp_gt_f32_e64 s[26:27], v21, v14
	s_nop 1
	v_cndmask_b32_e64 v62, 0, 1, s[26:27]
	v_cmp_gt_f32_e64 s[26:27], v17, v14
	s_nop 1
	v_addc_co_u32_e64 v61, s[26:27], v61, v62, s[26:27]
	v_cmp_gt_f32_e64 s[26:27], v22, v14
	s_nop 1
	v_cndmask_b32_e64 v62, 0, 1, s[26:27]
	v_cmp_gt_f32_e64 s[26:27], v18, v14
	s_nop 1
	v_addc_co_u32_e64 v61, s[26:27], v61, v62, s[26:27]
	v_cmp_gt_f32_e64 s[26:27], v23, v14
	s_nop 1
	v_cndmask_b32_e64 v62, 0, 1, s[26:27]
	v_cmp_gt_f32_e64 s[26:27], v19, v14
	s_nop 1
	v_addc_co_u32_e64 v61, s[26:27], v61, v62, s[26:27]
	v_cmp_gt_f32_e64 s[26:27], v30, v14
	s_nop 1
	v_cndmask_b32_e64 v62, 0, 1, s[26:27]
	v_cmp_gt_f32_e64 s[26:27], v24, v14
	s_nop 1
	v_addc_co_u32_e64 v61, s[26:27], v61, v62, s[26:27]
	v_cmp_gt_f32_e64 s[26:27], v33, v14
	s_nop 1
	v_cndmask_b32_e64 v62, 0, 1, s[26:27]
	v_cmp_gt_f32_e64 s[26:27], v25, v14
	s_nop 1
	v_addc_co_u32_e64 v61, s[26:27], v61, v62, s[26:27]
	v_cmp_gt_f32_e64 s[26:27], v36, v14
	s_nop 1
	v_cndmask_b32_e64 v62, 0, 1, s[26:27]
	v_cmp_gt_f32_e64 s[26:27], v26, v14
	s_nop 1
	v_addc_co_u32_e64 v61, s[26:27], v61, v62, s[26:27]
	v_cmp_lt_u32_e64 s[26:27], 15, v61
	s_or_b64 s[24:25], s[26:27], s[24:25]
	v_cndmask_b32_e64 v61, v181, 0, s[24:25]
	v_cmp_ge_f32_e64 s[24:25], s33, v9
	s_nop 1
	v_cndmask_b32_e64 v62, 0, 1, s[24:25]
	v_cmp_ge_f32_e64 s[24:25], v2, v9
	s_nop 1
	v_cndmask_b32_e64 v63, 0, 1, s[24:25]
	v_cmp_ge_f32_e64 s[24:25], v3, v9
	s_nop 1
	v_addc_co_u32_e64 v62, s[24:25], v62, v63, s[24:25]
	v_cmp_ge_f32_e64 s[24:25], v4, v9
	s_nop 1
	v_cndmask_b32_e64 v63, 0, 1, s[24:25]
	v_cmp_ge_f32_e64 s[24:25], v5, v9
	s_nop 1
	v_addc_co_u32_e64 v62, s[24:25], v62, v63, s[24:25]
	v_cmp_ge_f32_e64 s[24:25], v6, v9
	s_nop 1
	v_cndmask_b32_e64 v63, 0, 1, s[24:25]
	v_cmp_ge_f32_e64 s[24:25], v1, v9
	s_nop 1
	v_addc_co_u32_e64 v62, s[24:25], v62, v63, s[24:25]
	v_cmp_ge_f32_e64 s[24:25], v8, v9
	s_nop 1
	v_cndmask_b32_e64 v63, 0, 1, s[24:25]
	v_cmp_gt_f32_e64 s[24:25], v27, v9
	s_nop 1
	v_addc_co_u32_e64 v62, s[24:25], v62, v63, s[24:25]
	v_cmp_ge_f32_e64 s[24:25], v0, v9
	s_nop 1
	v_cndmask_b32_e64 v63, 0, 1, s[24:25]
	v_cmp_ge_f32_e64 s[24:25], v12, v9
	s_nop 1
	v_addc_co_u32_e64 v62, s[24:25], v62, v63, s[24:25]
	v_cmp_ge_f32_e64 s[24:25], v7, v9
	s_nop 1
	v_cndmask_b32_e64 v63, 0, 1, s[24:25]
	v_cmp_ge_f32_e64 s[24:25], v13, v9
	s_nop 1
	v_addc_co_u32_e64 v62, s[24:25], v62, v63, s[24:25]
	v_cmp_gt_f32_e64 s[24:25], v14, v9
	s_nop 1
	v_cndmask_b32_e64 v63, 0, 1, s[24:25]
	v_cmp_gt_f32_e64 s[24:25], v10, v9
	s_nop 1
	v_addc_co_u32_e64 v62, s[24:25], v62, v63, s[24:25]
	v_cmp_gt_f32_e64 s[24:25], v15, v9
	s_nop 1
	v_cndmask_b32_e64 v63, 0, 1, s[24:25]
	v_cmp_gt_f32_e64 s[24:25], v11, v9
	s_nop 1
	v_addc_co_u32_e64 v62, s[24:25], v62, v63, s[24:25]
	v_cmp_gt_f32_e64 s[24:25], v20, v9
	s_nop 1
	v_cndmask_b32_e64 v63, 0, 1, s[24:25]
	v_cmp_gt_f32_e64 s[24:25], v16, v9
	s_nop 1
	v_addc_co_u32_e64 v62, s[24:25], v62, v63, s[24:25]
	v_cmp_gt_f32_e64 s[24:25], v21, v9
	s_nop 1
	v_cndmask_b32_e64 v63, 0, 1, s[24:25]
	v_cmp_gt_f32_e64 s[24:25], v17, v9
	s_nop 1
	v_addc_co_u32_e64 v62, s[24:25], v62, v63, s[24:25]
	v_cmp_gt_f32_e64 s[24:25], v22, v9
	s_nop 1
	v_cndmask_b32_e64 v63, 0, 1, s[24:25]
	v_cmp_gt_f32_e64 s[24:25], v18, v9
	s_nop 1
	v_addc_co_u32_e64 v62, s[24:25], v62, v63, s[24:25]
	v_cmp_gt_f32_e64 s[24:25], v23, v9
	s_nop 1
	v_cndmask_b32_e64 v63, 0, 1, s[24:25]
	v_cmp_gt_f32_e64 s[24:25], v19, v9
	s_nop 1
	v_addc_co_u32_e64 v62, s[24:25], v62, v63, s[24:25]
	v_cmp_gt_f32_e64 s[24:25], v30, v9
	s_nop 1
	v_cndmask_b32_e64 v63, 0, 1, s[24:25]
	v_cmp_gt_f32_e64 s[24:25], v24, v9
	s_nop 1
	v_addc_co_u32_e64 v62, s[24:25], v62, v63, s[24:25]
	v_cmp_gt_f32_e64 s[24:25], v33, v9
	s_nop 1
	v_cndmask_b32_e64 v63, 0, 1, s[24:25]
	v_cmp_gt_f32_e64 s[24:25], v25, v9
	s_nop 1
	v_addc_co_u32_e64 v62, s[24:25], v62, v63, s[24:25]
	v_cmp_gt_f32_e64 s[24:25], v36, v9
	s_nop 1
	v_cndmask_b32_e64 v63, 0, 1, s[24:25]
	v_cmp_gt_f32_e64 s[24:25], v26, v9
	s_nop 1
	v_addc_co_u32_e64 v62, s[24:25], v62, v63, s[24:25]
	v_cmp_lt_u32_e64 s[24:25], 15, v62
	s_or_b64 s[22:23], s[24:25], s[22:23]
	v_cndmask_b32_e64 v62, v182, 0, s[22:23]
	v_cmp_ge_f32_e64 s[22:23], s33, v13
	s_nop 1
	v_cndmask_b32_e64 v63, 0, 1, s[22:23]
	v_cmp_ge_f32_e64 s[22:23], v2, v13
	s_nop 1
	v_cndmask_b32_e64 v64, 0, 1, s[22:23]
	v_cmp_ge_f32_e64 s[22:23], v3, v13
	s_nop 1
	v_addc_co_u32_e64 v63, s[22:23], v63, v64, s[22:23]
	v_cmp_ge_f32_e64 s[22:23], v4, v13
	s_nop 1
	v_cndmask_b32_e64 v64, 0, 1, s[22:23]
	v_cmp_ge_f32_e64 s[22:23], v5, v13
	s_nop 1
	v_addc_co_u32_e64 v63, s[22:23], v63, v64, s[22:23]
	v_cmp_ge_f32_e64 s[22:23], v6, v13
	s_nop 1
	v_cndmask_b32_e64 v64, 0, 1, s[22:23]
	v_cmp_ge_f32_e64 s[22:23], v1, v13
	s_nop 1
	v_addc_co_u32_e64 v63, s[22:23], v63, v64, s[22:23]
	v_cmp_ge_f32_e64 s[22:23], v8, v13
	s_nop 1
	v_cndmask_b32_e64 v64, 0, 1, s[22:23]
	v_cmp_gt_f32_e64 s[22:23], v27, v13
	s_nop 1
	v_addc_co_u32_e64 v63, s[22:23], v63, v64, s[22:23]
	v_cmp_ge_f32_e64 s[22:23], v0, v13
	s_nop 1
	v_cndmask_b32_e64 v64, 0, 1, s[22:23]
	v_cmp_ge_f32_e64 s[22:23], v12, v13
	s_nop 1
	v_addc_co_u32_e64 v63, s[22:23], v63, v64, s[22:23]
	v_cmp_ge_f32_e64 s[22:23], v7, v13
	s_nop 1
	v_cndmask_b32_e64 v64, 0, 1, s[22:23]
	v_cmp_gt_f32_e64 s[22:23], v9, v13
	s_nop 1
	v_addc_co_u32_e64 v63, s[22:23], v63, v64, s[22:23]
	v_cmp_gt_f32_e64 s[22:23], v14, v13
	s_nop 1
	v_cndmask_b32_e64 v64, 0, 1, s[22:23]
	v_cmp_gt_f32_e64 s[22:23], v10, v13
	s_nop 1
	v_addc_co_u32_e64 v63, s[22:23], v63, v64, s[22:23]
	v_cmp_gt_f32_e64 s[22:23], v15, v13
	s_nop 1
	v_cndmask_b32_e64 v64, 0, 1, s[22:23]
	v_cmp_gt_f32_e64 s[22:23], v11, v13
	s_nop 1
	v_addc_co_u32_e64 v63, s[22:23], v63, v64, s[22:23]
	v_cmp_gt_f32_e64 s[22:23], v20, v13
	s_nop 1
	v_cndmask_b32_e64 v64, 0, 1, s[22:23]
	v_cmp_gt_f32_e64 s[22:23], v16, v13
	s_nop 1
	v_addc_co_u32_e64 v63, s[22:23], v63, v64, s[22:23]
	v_cmp_gt_f32_e64 s[22:23], v21, v13
	s_nop 1
	v_cndmask_b32_e64 v64, 0, 1, s[22:23]
	v_cmp_gt_f32_e64 s[22:23], v17, v13
	s_nop 1
	v_addc_co_u32_e64 v63, s[22:23], v63, v64, s[22:23]
	v_cmp_gt_f32_e64 s[22:23], v22, v13
	s_nop 1
	v_cndmask_b32_e64 v64, 0, 1, s[22:23]
	v_cmp_gt_f32_e64 s[22:23], v18, v13
	s_nop 1
	v_addc_co_u32_e64 v63, s[22:23], v63, v64, s[22:23]
	v_cmp_gt_f32_e64 s[22:23], v23, v13
	s_nop 1
	v_cndmask_b32_e64 v64, 0, 1, s[22:23]
	v_cmp_gt_f32_e64 s[22:23], v19, v13
	s_nop 1
	v_addc_co_u32_e64 v63, s[22:23], v63, v64, s[22:23]
	v_cmp_gt_f32_e64 s[22:23], v30, v13
	s_nop 1
	v_cndmask_b32_e64 v64, 0, 1, s[22:23]
	v_cmp_gt_f32_e64 s[22:23], v24, v13
	s_nop 1
	v_addc_co_u32_e64 v63, s[22:23], v63, v64, s[22:23]
	v_cmp_gt_f32_e64 s[22:23], v33, v13
	s_nop 1
	v_cndmask_b32_e64 v64, 0, 1, s[22:23]
	v_cmp_gt_f32_e64 s[22:23], v25, v13
	s_nop 1
	v_addc_co_u32_e64 v63, s[22:23], v63, v64, s[22:23]
	v_cmp_gt_f32_e64 s[22:23], v36, v13
	s_nop 1
	v_cndmask_b32_e64 v64, 0, 1, s[22:23]
	v_cmp_gt_f32_e64 s[22:23], v26, v13
	s_nop 1
	v_addc_co_u32_e64 v63, s[22:23], v63, v64, s[22:23]
	v_cmp_lt_u32_e64 s[22:23], 15, v63
	s_or_b64 s[20:21], s[22:23], s[20:21]
	v_cndmask_b32_e64 v63, v183, 0, s[20:21]
	v_cmp_ge_f32_e64 s[20:21], s33, v7
	s_nop 1
	v_cndmask_b32_e64 v64, 0, 1, s[20:21]
	v_cmp_ge_f32_e64 s[20:21], v2, v7
	s_nop 1
	v_cndmask_b32_e64 v65, 0, 1, s[20:21]
	v_cmp_ge_f32_e64 s[20:21], v3, v7
	s_nop 1
	v_addc_co_u32_e64 v64, s[20:21], v64, v65, s[20:21]
	v_cmp_ge_f32_e64 s[20:21], v4, v7
	s_nop 1
	v_cndmask_b32_e64 v65, 0, 1, s[20:21]
	v_cmp_ge_f32_e64 s[20:21], v5, v7
	s_nop 1
	v_addc_co_u32_e64 v64, s[20:21], v64, v65, s[20:21]
	v_cmp_ge_f32_e64 s[20:21], v6, v7
	s_nop 1
	v_cndmask_b32_e64 v65, 0, 1, s[20:21]
	v_cmp_ge_f32_e64 s[20:21], v1, v7
	s_nop 1
	v_addc_co_u32_e64 v64, s[20:21], v64, v65, s[20:21]
	v_cmp_ge_f32_e64 s[20:21], v8, v7
	s_nop 1
	v_cndmask_b32_e64 v65, 0, 1, s[20:21]
	v_cmp_gt_f32_e64 s[20:21], v27, v7
	s_nop 1
	v_addc_co_u32_e64 v64, s[20:21], v64, v65, s[20:21]
	v_cmp_ge_f32_e64 s[20:21], v0, v7
	s_nop 1
	v_cndmask_b32_e64 v65, 0, 1, s[20:21]
	v_cmp_ge_f32_e64 s[20:21], v12, v7
	s_nop 1
	v_addc_co_u32_e64 v64, s[20:21], v64, v65, s[20:21]
	v_cmp_gt_f32_e64 s[20:21], v13, v7
	s_nop 1
	v_cndmask_b32_e64 v65, 0, 1, s[20:21]
	v_cmp_gt_f32_e64 s[20:21], v9, v7
	s_nop 1
	v_addc_co_u32_e64 v64, s[20:21], v64, v65, s[20:21]
	v_cmp_gt_f32_e64 s[20:21], v14, v7
	s_nop 1
	v_cndmask_b32_e64 v65, 0, 1, s[20:21]
	v_cmp_gt_f32_e64 s[20:21], v10, v7
	s_nop 1
	v_addc_co_u32_e64 v64, s[20:21], v64, v65, s[20:21]
	v_cmp_gt_f32_e64 s[20:21], v15, v7
	s_nop 1
	v_cndmask_b32_e64 v65, 0, 1, s[20:21]
	v_cmp_gt_f32_e64 s[20:21], v11, v7
	s_nop 1
	v_addc_co_u32_e64 v64, s[20:21], v64, v65, s[20:21]
	v_cmp_gt_f32_e64 s[20:21], v20, v7
	s_nop 1
	v_cndmask_b32_e64 v65, 0, 1, s[20:21]
	v_cmp_gt_f32_e64 s[20:21], v16, v7
	s_nop 1
	v_addc_co_u32_e64 v64, s[20:21], v64, v65, s[20:21]
	v_cmp_gt_f32_e64 s[20:21], v21, v7
	s_nop 1
	v_cndmask_b32_e64 v65, 0, 1, s[20:21]
	v_cmp_gt_f32_e64 s[20:21], v17, v7
	s_nop 1
	v_addc_co_u32_e64 v64, s[20:21], v64, v65, s[20:21]
	v_cmp_gt_f32_e64 s[20:21], v22, v7
	s_nop 1
	v_cndmask_b32_e64 v65, 0, 1, s[20:21]
	v_cmp_gt_f32_e64 s[20:21], v18, v7
	s_nop 1
	v_addc_co_u32_e64 v64, s[20:21], v64, v65, s[20:21]
	v_cmp_gt_f32_e64 s[20:21], v23, v7
	s_nop 1
	v_cndmask_b32_e64 v65, 0, 1, s[20:21]
	v_cmp_gt_f32_e64 s[20:21], v19, v7
	s_nop 1
	v_addc_co_u32_e64 v64, s[20:21], v64, v65, s[20:21]
	v_cmp_gt_f32_e64 s[20:21], v30, v7
	s_nop 1
	v_cndmask_b32_e64 v65, 0, 1, s[20:21]
	v_cmp_gt_f32_e64 s[20:21], v24, v7
	s_nop 1
	v_addc_co_u32_e64 v64, s[20:21], v64, v65, s[20:21]
	v_cmp_gt_f32_e64 s[20:21], v33, v7
	s_nop 1
	v_cndmask_b32_e64 v65, 0, 1, s[20:21]
	v_cmp_gt_f32_e64 s[20:21], v25, v7
	s_nop 1
	v_addc_co_u32_e64 v64, s[20:21], v64, v65, s[20:21]
	v_cmp_gt_f32_e64 s[20:21], v36, v7
	s_nop 1
	v_cndmask_b32_e64 v65, 0, 1, s[20:21]
	v_cmp_gt_f32_e64 s[20:21], v26, v7
	s_nop 1
	v_addc_co_u32_e64 v64, s[20:21], v64, v65, s[20:21]
	v_cmp_lt_u32_e64 s[20:21], 15, v64
	s_or_b64 s[18:19], s[20:21], s[18:19]
	v_cndmask_b32_e64 v64, v184, 0, s[18:19]
	v_cmp_ge_f32_e64 s[18:19], s33, v12
	s_nop 1
	v_cndmask_b32_e64 v65, 0, 1, s[18:19]
	v_cmp_ge_f32_e64 s[18:19], v2, v12
	s_nop 1
	v_cndmask_b32_e64 v66, 0, 1, s[18:19]
	v_cmp_ge_f32_e64 s[18:19], v3, v12
	s_nop 1
	v_addc_co_u32_e64 v65, s[18:19], v65, v66, s[18:19]
	v_cmp_ge_f32_e64 s[18:19], v4, v12
	s_nop 1
	v_cndmask_b32_e64 v66, 0, 1, s[18:19]
	v_cmp_ge_f32_e64 s[18:19], v5, v12
	s_nop 1
	v_addc_co_u32_e64 v65, s[18:19], v65, v66, s[18:19]
	v_cmp_ge_f32_e64 s[18:19], v6, v12
	s_nop 1
	v_cndmask_b32_e64 v66, 0, 1, s[18:19]
	v_cmp_ge_f32_e64 s[18:19], v1, v12
	s_nop 1
	v_addc_co_u32_e64 v65, s[18:19], v65, v66, s[18:19]
	v_cmp_ge_f32_e64 s[18:19], v8, v12
	s_nop 1
	v_cndmask_b32_e64 v66, 0, 1, s[18:19]
	v_cmp_gt_f32_e64 s[18:19], v27, v12
	s_nop 1
	v_addc_co_u32_e64 v65, s[18:19], v65, v66, s[18:19]
	v_cmp_ge_f32_e64 s[18:19], v0, v12
	s_nop 1
	v_cndmask_b32_e64 v66, 0, 1, s[18:19]
	v_cmp_gt_f32_e64 s[18:19], v7, v12
	s_nop 1
	v_addc_co_u32_e64 v65, s[18:19], v65, v66, s[18:19]
	v_cmp_gt_f32_e64 s[18:19], v13, v12
	s_nop 1
	v_cndmask_b32_e64 v66, 0, 1, s[18:19]
	v_cmp_gt_f32_e64 s[18:19], v9, v12
	s_nop 1
	v_addc_co_u32_e64 v65, s[18:19], v65, v66, s[18:19]
	v_cmp_gt_f32_e64 s[18:19], v14, v12
	s_nop 1
	v_cndmask_b32_e64 v66, 0, 1, s[18:19]
	v_cmp_gt_f32_e64 s[18:19], v10, v12
	s_nop 1
	v_addc_co_u32_e64 v65, s[18:19], v65, v66, s[18:19]
	v_cmp_gt_f32_e64 s[18:19], v15, v12
	s_nop 1
	v_cndmask_b32_e64 v66, 0, 1, s[18:19]
	v_cmp_gt_f32_e64 s[18:19], v11, v12
	s_nop 1
	v_addc_co_u32_e64 v65, s[18:19], v65, v66, s[18:19]
	v_cmp_gt_f32_e64 s[18:19], v20, v12
	s_nop 1
	v_cndmask_b32_e64 v66, 0, 1, s[18:19]
	v_cmp_gt_f32_e64 s[18:19], v16, v12
	s_nop 1
	v_addc_co_u32_e64 v65, s[18:19], v65, v66, s[18:19]
	v_cmp_gt_f32_e64 s[18:19], v21, v12
	s_nop 1
	v_cndmask_b32_e64 v66, 0, 1, s[18:19]
	v_cmp_gt_f32_e64 s[18:19], v17, v12
	s_nop 1
	v_addc_co_u32_e64 v65, s[18:19], v65, v66, s[18:19]
	v_cmp_gt_f32_e64 s[18:19], v22, v12
	s_nop 1
	v_cndmask_b32_e64 v66, 0, 1, s[18:19]
	v_cmp_gt_f32_e64 s[18:19], v18, v12
	s_nop 1
	v_addc_co_u32_e64 v65, s[18:19], v65, v66, s[18:19]
	v_cmp_gt_f32_e64 s[18:19], v23, v12
	s_nop 1
	v_cndmask_b32_e64 v66, 0, 1, s[18:19]
	v_cmp_gt_f32_e64 s[18:19], v19, v12
	s_nop 1
	v_addc_co_u32_e64 v65, s[18:19], v65, v66, s[18:19]
	v_cmp_gt_f32_e64 s[18:19], v30, v12
	s_nop 1
	v_cndmask_b32_e64 v66, 0, 1, s[18:19]
	v_cmp_gt_f32_e64 s[18:19], v24, v12
	s_nop 1
	v_addc_co_u32_e64 v65, s[18:19], v65, v66, s[18:19]
	v_cmp_gt_f32_e64 s[18:19], v33, v12
	s_nop 1
	v_cndmask_b32_e64 v66, 0, 1, s[18:19]
	v_cmp_gt_f32_e64 s[18:19], v25, v12
	s_nop 1
	v_addc_co_u32_e64 v65, s[18:19], v65, v66, s[18:19]
	v_cmp_gt_f32_e64 s[18:19], v36, v12
	s_nop 1
	v_cndmask_b32_e64 v66, 0, 1, s[18:19]
	v_cmp_gt_f32_e64 s[18:19], v26, v12
	s_nop 1
	v_addc_co_u32_e64 v65, s[18:19], v65, v66, s[18:19]
	v_cmp_lt_u32_e64 s[18:19], 15, v65
	s_or_b64 s[16:17], s[18:19], s[16:17]
	v_cndmask_b32_e64 v65, v185, 0, s[16:17]
	v_cmp_ge_f32_e64 s[16:17], s33, v0
	s_nop 1
	v_cndmask_b32_e64 v66, 0, 1, s[16:17]
	v_cmp_ge_f32_e64 s[16:17], v2, v0
	s_nop 1
	v_cndmask_b32_e64 v67, 0, 1, s[16:17]
	v_cmp_ge_f32_e64 s[16:17], v3, v0
	s_nop 1
	v_addc_co_u32_e64 v66, s[16:17], v66, v67, s[16:17]
	v_cmp_ge_f32_e64 s[16:17], v4, v0
	s_nop 1
	v_cndmask_b32_e64 v67, 0, 1, s[16:17]
	v_cmp_ge_f32_e64 s[16:17], v5, v0
	s_nop 1
	v_addc_co_u32_e64 v66, s[16:17], v66, v67, s[16:17]
	v_cmp_ge_f32_e64 s[16:17], v6, v0
	s_nop 1
	v_cndmask_b32_e64 v67, 0, 1, s[16:17]
	v_cmp_ge_f32_e64 s[16:17], v1, v0
	s_nop 1
	v_addc_co_u32_e64 v66, s[16:17], v66, v67, s[16:17]
	v_cmp_ge_f32_e64 s[16:17], v8, v0
	s_nop 1
	v_cndmask_b32_e64 v67, 0, 1, s[16:17]
	v_cmp_gt_f32_e64 s[16:17], v27, v0
	s_nop 1
	v_addc_co_u32_e64 v66, s[16:17], v66, v67, s[16:17]
	v_cmp_gt_f32_e64 s[16:17], v12, v0
	s_nop 1
	v_cndmask_b32_e64 v67, 0, 1, s[16:17]
	v_cmp_gt_f32_e64 s[16:17], v7, v0
	s_nop 1
	v_addc_co_u32_e64 v66, s[16:17], v66, v67, s[16:17]
	v_cmp_gt_f32_e64 s[16:17], v13, v0
	s_nop 1
	v_cndmask_b32_e64 v67, 0, 1, s[16:17]
	v_cmp_gt_f32_e64 s[16:17], v9, v0
	s_nop 1
	v_addc_co_u32_e64 v66, s[16:17], v66, v67, s[16:17]
	v_cmp_gt_f32_e64 s[16:17], v14, v0
	s_nop 1
	v_cndmask_b32_e64 v67, 0, 1, s[16:17]
	v_cmp_gt_f32_e64 s[16:17], v10, v0
	s_nop 1
	v_addc_co_u32_e64 v66, s[16:17], v66, v67, s[16:17]
	v_cmp_gt_f32_e64 s[16:17], v15, v0
	s_nop 1
	v_cndmask_b32_e64 v67, 0, 1, s[16:17]
	v_cmp_gt_f32_e64 s[16:17], v11, v0
	s_nop 1
	v_addc_co_u32_e64 v66, s[16:17], v66, v67, s[16:17]
	v_cmp_gt_f32_e64 s[16:17], v20, v0
	s_nop 1
	v_cndmask_b32_e64 v67, 0, 1, s[16:17]
	v_cmp_gt_f32_e64 s[16:17], v16, v0
	s_nop 1
	v_addc_co_u32_e64 v66, s[16:17], v66, v67, s[16:17]
	v_cmp_gt_f32_e64 s[16:17], v21, v0
	s_nop 1
	v_cndmask_b32_e64 v67, 0, 1, s[16:17]
	v_cmp_gt_f32_e64 s[16:17], v17, v0
	s_nop 1
	v_addc_co_u32_e64 v66, s[16:17], v66, v67, s[16:17]
	v_cmp_gt_f32_e64 s[16:17], v22, v0
	s_nop 1
	v_cndmask_b32_e64 v67, 0, 1, s[16:17]
	v_cmp_gt_f32_e64 s[16:17], v18, v0
	s_nop 1
	v_addc_co_u32_e64 v66, s[16:17], v66, v67, s[16:17]
	v_cmp_gt_f32_e64 s[16:17], v23, v0
	s_nop 1
	v_cndmask_b32_e64 v67, 0, 1, s[16:17]
	v_cmp_gt_f32_e64 s[16:17], v19, v0
	s_nop 1
	v_addc_co_u32_e64 v66, s[16:17], v66, v67, s[16:17]
	v_cmp_gt_f32_e64 s[16:17], v30, v0
	s_nop 1
	v_cndmask_b32_e64 v67, 0, 1, s[16:17]
	v_cmp_gt_f32_e64 s[16:17], v24, v0
	s_nop 1
	v_addc_co_u32_e64 v66, s[16:17], v66, v67, s[16:17]
	v_cmp_gt_f32_e64 s[16:17], v33, v0
	s_nop 1
	v_cndmask_b32_e64 v67, 0, 1, s[16:17]
	v_cmp_gt_f32_e64 s[16:17], v25, v0
	s_nop 1
	v_addc_co_u32_e64 v66, s[16:17], v66, v67, s[16:17]
	v_cmp_gt_f32_e64 s[16:17], v36, v0
	s_nop 1
	v_cndmask_b32_e64 v67, 0, 1, s[16:17]
	v_cmp_gt_f32_e64 s[16:17], v26, v0
	s_nop 1
	v_addc_co_u32_e64 v66, s[16:17], v66, v67, s[16:17]
	v_cmp_lt_u32_e64 s[16:17], 15, v66
	s_or_b64 s[14:15], s[16:17], s[14:15]
	v_cndmask_b32_e64 v66, v186, 0, s[14:15]
	v_cmp_ge_f32_e64 s[14:15], s33, v8
	s_nop 1
	v_cndmask_b32_e64 v67, 0, 1, s[14:15]
	v_cmp_ge_f32_e64 s[14:15], v2, v8
	s_nop 1
	v_cndmask_b32_e64 v68, 0, 1, s[14:15]
	v_cmp_ge_f32_e64 s[14:15], v3, v8
	s_nop 1
	v_addc_co_u32_e64 v67, s[14:15], v67, v68, s[14:15]
	v_cmp_ge_f32_e64 s[14:15], v4, v8
	s_nop 1
	v_cndmask_b32_e64 v68, 0, 1, s[14:15]
	v_cmp_ge_f32_e64 s[14:15], v5, v8
	s_nop 1
	v_addc_co_u32_e64 v67, s[14:15], v67, v68, s[14:15]
	v_cmp_ge_f32_e64 s[14:15], v6, v8
	s_nop 1
	v_cndmask_b32_e64 v68, 0, 1, s[14:15]
	v_cmp_ge_f32_e64 s[14:15], v1, v8
	s_nop 1
	v_addc_co_u32_e64 v67, s[14:15], v67, v68, s[14:15]
	v_cmp_gt_f32_e64 s[14:15], v27, v8
	s_nop 1
	v_cndmask_b32_e64 v68, 0, 1, s[14:15]
	v_cmp_gt_f32_e64 s[14:15], v0, v8
	s_nop 1
	v_addc_co_u32_e64 v67, s[14:15], v67, v68, s[14:15]
	v_cmp_gt_f32_e64 s[14:15], v12, v8
	s_nop 1
	v_cndmask_b32_e64 v68, 0, 1, s[14:15]
	v_cmp_gt_f32_e64 s[14:15], v7, v8
	s_nop 1
	v_addc_co_u32_e64 v67, s[14:15], v67, v68, s[14:15]
	v_cmp_gt_f32_e64 s[14:15], v13, v8
	s_nop 1
	v_cndmask_b32_e64 v68, 0, 1, s[14:15]
	v_cmp_gt_f32_e64 s[14:15], v9, v8
	s_nop 1
	v_addc_co_u32_e64 v67, s[14:15], v67, v68, s[14:15]
	v_cmp_gt_f32_e64 s[14:15], v14, v8
	s_nop 1
	v_cndmask_b32_e64 v68, 0, 1, s[14:15]
	v_cmp_gt_f32_e64 s[14:15], v10, v8
	s_nop 1
	v_addc_co_u32_e64 v67, s[14:15], v67, v68, s[14:15]
	v_cmp_gt_f32_e64 s[14:15], v15, v8
	s_nop 1
	v_cndmask_b32_e64 v68, 0, 1, s[14:15]
	v_cmp_gt_f32_e64 s[14:15], v11, v8
	s_nop 1
	v_addc_co_u32_e64 v67, s[14:15], v67, v68, s[14:15]
	v_cmp_gt_f32_e64 s[14:15], v20, v8
	s_nop 1
	v_cndmask_b32_e64 v68, 0, 1, s[14:15]
	v_cmp_gt_f32_e64 s[14:15], v16, v8
	s_nop 1
	v_addc_co_u32_e64 v67, s[14:15], v67, v68, s[14:15]
	v_cmp_gt_f32_e64 s[14:15], v21, v8
	s_nop 1
	v_cndmask_b32_e64 v68, 0, 1, s[14:15]
	v_cmp_gt_f32_e64 s[14:15], v17, v8
	s_nop 1
	v_addc_co_u32_e64 v67, s[14:15], v67, v68, s[14:15]
	v_cmp_gt_f32_e64 s[14:15], v22, v8
	s_nop 1
	v_cndmask_b32_e64 v68, 0, 1, s[14:15]
	v_cmp_gt_f32_e64 s[14:15], v18, v8
	s_nop 1
	v_addc_co_u32_e64 v67, s[14:15], v67, v68, s[14:15]
	v_cmp_gt_f32_e64 s[14:15], v23, v8
	s_nop 1
	v_cndmask_b32_e64 v68, 0, 1, s[14:15]
	v_cmp_gt_f32_e64 s[14:15], v19, v8
	s_nop 1
	v_addc_co_u32_e64 v67, s[14:15], v67, v68, s[14:15]
	v_cmp_gt_f32_e64 s[14:15], v30, v8
	s_nop 1
	v_cndmask_b32_e64 v68, 0, 1, s[14:15]
	v_cmp_gt_f32_e64 s[14:15], v24, v8
	s_nop 1
	v_addc_co_u32_e64 v67, s[14:15], v67, v68, s[14:15]
	v_cmp_gt_f32_e64 s[14:15], v33, v8
	s_nop 1
	v_cndmask_b32_e64 v68, 0, 1, s[14:15]
	v_cmp_gt_f32_e64 s[14:15], v25, v8
	s_nop 1
	v_addc_co_u32_e64 v67, s[14:15], v67, v68, s[14:15]
	v_cmp_gt_f32_e64 s[14:15], v36, v8
	s_nop 1
	v_cndmask_b32_e64 v68, 0, 1, s[14:15]
	v_cmp_gt_f32_e64 s[14:15], v26, v8
	s_nop 1
	v_addc_co_u32_e64 v67, s[14:15], v67, v68, s[14:15]
	v_cmp_lt_u32_e64 s[14:15], 15, v67
	s_or_b64 s[12:13], s[14:15], s[12:13]
	v_cndmask_b32_e64 v67, v187, 0, s[12:13]
	v_cmp_gt_f32_e64 s[12:13], v3, v2
	s_nop 1
	v_cndmask_b32_e64 v68, 0, 1, s[12:13]
	v_cmp_ge_f32_e64 s[12:13], s33, v2
	s_nop 1
	v_cndmask_b32_e64 v69, 0, 1, s[12:13]
	v_cmp_gt_f32_e64 s[12:13], v4, v2
	s_nop 1
	v_addc_co_u32_e64 v68, s[12:13], v68, v69, s[12:13]
	v_cmp_gt_f32_e64 s[12:13], v5, v2
	s_nop 1
	v_cndmask_b32_e64 v69, 0, 1, s[12:13]
	v_cmp_gt_f32_e64 s[12:13], v6, v2
	s_nop 1
	v_addc_co_u32_e64 v68, s[12:13], v68, v69, s[12:13]
	v_cmp_gt_f32_e64 s[12:13], v1, v2
	s_nop 1
	v_cndmask_b32_e64 v69, 0, 1, s[12:13]
	v_cmp_gt_f32_e64 s[12:13], v8, v2
	s_nop 1
	v_addc_co_u32_e64 v68, s[12:13], v68, v69, s[12:13]
	v_cmp_gt_f32_e64 s[12:13], v0, v2
	s_nop 1
	v_cndmask_b32_e64 v69, 0, 1, s[12:13]
	v_cmp_gt_f32_e64 s[12:13], v12, v2
	s_nop 1
	v_addc_co_u32_e64 v68, s[12:13], v68, v69, s[12:13]
	v_cmp_gt_f32_e64 s[12:13], v7, v2
	s_nop 1
	v_cndmask_b32_e64 v69, 0, 1, s[12:13]
	v_cmp_gt_f32_e64 s[12:13], v13, v2
	s_nop 1
	v_addc_co_u32_e64 v68, s[12:13], v68, v69, s[12:13]
	v_cmp_gt_f32_e64 s[12:13], v9, v2
	s_nop 1
	v_cndmask_b32_e64 v69, 0, 1, s[12:13]
	v_cmp_gt_f32_e64 s[12:13], v14, v2
	s_nop 1
	v_addc_co_u32_e64 v68, s[12:13], v68, v69, s[12:13]
	v_cmp_gt_f32_e64 s[12:13], v10, v2
	s_nop 1
	v_cndmask_b32_e64 v69, 0, 1, s[12:13]
	v_cmp_gt_f32_e64 s[12:13], v15, v2
	s_nop 1
	v_addc_co_u32_e64 v68, s[12:13], v68, v69, s[12:13]
	v_cmp_gt_f32_e64 s[12:13], v11, v2
	s_nop 1
	v_cndmask_b32_e64 v69, 0, 1, s[12:13]
	v_cmp_gt_f32_e64 s[12:13], v20, v2
	s_nop 1
	v_addc_co_u32_e64 v68, s[12:13], v68, v69, s[12:13]
	v_cmp_gt_f32_e64 s[12:13], v16, v2
	s_nop 1
	v_cndmask_b32_e64 v69, 0, 1, s[12:13]
	v_cmp_gt_f32_e64 s[12:13], v21, v2
	s_nop 1
	v_addc_co_u32_e64 v68, s[12:13], v68, v69, s[12:13]
	v_cmp_gt_f32_e64 s[12:13], v17, v2
	s_nop 1
	v_cndmask_b32_e64 v69, 0, 1, s[12:13]
	v_cmp_gt_f32_e64 s[12:13], v22, v2
	s_nop 1
	v_addc_co_u32_e64 v68, s[12:13], v68, v69, s[12:13]
	v_cmp_gt_f32_e64 s[12:13], v18, v2
	s_nop 1
	v_cndmask_b32_e64 v69, 0, 1, s[12:13]
	v_cmp_gt_f32_e64 s[12:13], v23, v2
	s_nop 1
	v_addc_co_u32_e64 v68, s[12:13], v68, v69, s[12:13]
	v_cmp_gt_f32_e64 s[12:13], v19, v2
	s_nop 1
	v_cndmask_b32_e64 v69, 0, 1, s[12:13]
	v_cmp_gt_f32_e64 s[12:13], v30, v2
	s_nop 1
	v_addc_co_u32_e64 v68, s[12:13], v68, v69, s[12:13]
	v_cmp_gt_f32_e64 s[12:13], v24, v2
	s_nop 1
	v_cndmask_b32_e64 v69, 0, 1, s[12:13]
	v_cmp_gt_f32_e64 s[12:13], v33, v2
	s_nop 1
	v_addc_co_u32_e64 v68, s[12:13], v68, v69, s[12:13]
	v_cmp_gt_f32_e64 s[12:13], v25, v2
	s_nop 1
	v_cndmask_b32_e64 v69, 0, 1, s[12:13]
	v_cmp_gt_f32_e64 s[12:13], v36, v2
	s_nop 1
	v_addc_co_u32_e64 v68, s[12:13], v68, v69, s[12:13]
	v_cmp_gt_f32_e64 s[12:13], v26, v2
	s_nop 1
	v_cndmask_b32_e64 v69, 0, 1, s[12:13]
	v_cmp_gt_f32_e64 s[12:13], v27, v2
	s_nop 1
	v_addc_co_u32_e64 v68, s[12:13], v68, v69, s[12:13]
	v_cmp_lt_u32_e64 s[12:13], 15, v68
	s_or_b64 s[10:11], s[12:13], s[10:11]
	v_cndmask_b32_e64 v68, 2, 0, s[10:11]
	v_cmp_lt_f32_e64 s[10:11], s33, v3
	s_nop 1
	v_cndmask_b32_e64 v69, 0, 1, s[10:11]
	v_cmp_lt_f32_e64 s[10:11], s33, v2
	s_nop 1
	v_cndmask_b32_e64 v70, 0, 1, s[10:11]
	v_cmp_lt_f32_e64 s[10:11], s33, v4
	s_nop 1
	v_addc_co_u32_e64 v69, s[10:11], v69, v70, s[10:11]
	v_cmp_lt_f32_e64 s[10:11], s33, v5
	s_nop 1
	v_cndmask_b32_e64 v70, 0, 1, s[10:11]
	v_cmp_lt_f32_e64 s[10:11], s33, v6
	s_nop 1
	v_addc_co_u32_e64 v69, s[10:11], v69, v70, s[10:11]
	v_cmp_lt_f32_e64 s[10:11], s33, v1
	s_nop 1
	v_cndmask_b32_e64 v70, 0, 1, s[10:11]
	v_cmp_lt_f32_e64 s[10:11], s33, v8
	s_nop 1
	v_addc_co_u32_e64 v69, s[10:11], v69, v70, s[10:11]
	v_cmp_lt_f32_e64 s[10:11], s33, v0
	s_nop 1
	v_cndmask_b32_e64 v70, 0, 1, s[10:11]
	v_cmp_lt_f32_e64 s[10:11], s33, v12
	s_nop 1
	v_addc_co_u32_e64 v69, s[10:11], v69, v70, s[10:11]
	v_cmp_lt_f32_e64 s[10:11], s33, v7
	s_nop 1
	v_cndmask_b32_e64 v70, 0, 1, s[10:11]
	v_cmp_lt_f32_e64 s[10:11], s33, v13
	s_nop 1
	v_addc_co_u32_e64 v69, s[10:11], v69, v70, s[10:11]
	v_cmp_lt_f32_e64 s[10:11], s33, v9
	s_nop 1
	v_cndmask_b32_e64 v70, 0, 1, s[10:11]
	v_cmp_lt_f32_e64 s[10:11], s33, v14
	s_nop 1
	v_addc_co_u32_e64 v69, s[10:11], v69, v70, s[10:11]
	v_cmp_lt_f32_e64 s[10:11], s33, v10
	s_nop 1
	v_cndmask_b32_e64 v70, 0, 1, s[10:11]
	v_cmp_lt_f32_e64 s[10:11], s33, v15
	s_nop 1
	v_addc_co_u32_e64 v69, s[10:11], v69, v70, s[10:11]
	v_cmp_lt_f32_e64 s[10:11], s33, v11
	s_nop 1
	v_cndmask_b32_e64 v70, 0, 1, s[10:11]
	v_cmp_lt_f32_e64 s[10:11], s33, v20
	s_nop 1
	v_addc_co_u32_e64 v69, s[10:11], v69, v70, s[10:11]
	v_cmp_lt_f32_e64 s[10:11], s33, v16
	s_nop 1
	v_cndmask_b32_e64 v70, 0, 1, s[10:11]
	v_cmp_lt_f32_e64 s[10:11], s33, v21
	s_nop 1
	v_addc_co_u32_e64 v69, s[10:11], v69, v70, s[10:11]
	v_cmp_lt_f32_e64 s[10:11], s33, v17
	s_nop 1
	v_cndmask_b32_e64 v70, 0, 1, s[10:11]
	v_cmp_lt_f32_e64 s[10:11], s33, v22
	s_nop 1
	v_addc_co_u32_e64 v69, s[10:11], v69, v70, s[10:11]
	v_cmp_lt_f32_e64 s[10:11], s33, v18
	s_nop 1
	v_cndmask_b32_e64 v70, 0, 1, s[10:11]
	v_cmp_lt_f32_e64 s[10:11], s33, v23
	s_nop 1
	v_addc_co_u32_e64 v69, s[10:11], v69, v70, s[10:11]
	v_cmp_lt_f32_e64 s[10:11], s33, v19
	s_nop 1
	v_cndmask_b32_e64 v70, 0, 1, s[10:11]
	v_cmp_lt_f32_e64 s[10:11], s33, v30
	s_nop 1
	v_addc_co_u32_e64 v69, s[10:11], v69, v70, s[10:11]
	v_cmp_lt_f32_e64 s[10:11], s33, v24
	s_nop 1
	v_cndmask_b32_e64 v70, 0, 1, s[10:11]
	v_cmp_lt_f32_e64 s[10:11], s33, v33
	s_nop 1
	v_addc_co_u32_e64 v69, s[10:11], v69, v70, s[10:11]
	v_cmp_lt_f32_e64 s[10:11], s33, v25
	s_nop 1
	v_cndmask_b32_e64 v70, 0, 1, s[10:11]
	v_cmp_lt_f32_e64 s[10:11], s33, v36
	s_nop 1
	v_addc_co_u32_e64 v69, s[10:11], v69, v70, s[10:11]
	v_cmp_lt_f32_e64 s[10:11], s33, v26
	s_nop 1
	v_cndmask_b32_e64 v70, 0, 1, s[10:11]
	v_cmp_lt_f32_e64 s[10:11], s33, v27
	s_nop 1
	v_addc_co_u32_e64 v69, s[10:11], v69, v70, s[10:11]
	v_cmp_gt_u32_e64 s[10:11], 16, v69
	s_nop 1
	v_cndmask_b32_e64 v69, 0, 1, s[10:11]
	v_cmp_ge_f32_e64 s[10:11], s33, v3
	v_or_b32_e32 v68, v68, v69
	s_nop 0
	v_cndmask_b32_e64 v69, 0, 1, s[10:11]
	v_cmp_ge_f32_e64 s[10:11], v2, v3
	s_nop 1
	v_cndmask_b32_e64 v70, 0, 1, s[10:11]
	v_cmp_gt_f32_e64 s[10:11], v4, v3
	s_nop 1
	v_addc_co_u32_e64 v69, s[10:11], v69, v70, s[10:11]
	v_cmp_gt_f32_e64 s[10:11], v5, v3
	s_nop 1
	v_cndmask_b32_e64 v70, 0, 1, s[10:11]
	v_cmp_gt_f32_e64 s[10:11], v6, v3
	s_nop 1
	v_addc_co_u32_e64 v69, s[10:11], v69, v70, s[10:11]
	v_cmp_gt_f32_e64 s[10:11], v1, v3
	s_nop 1
	v_cndmask_b32_e64 v70, 0, 1, s[10:11]
	v_cmp_gt_f32_e64 s[10:11], v8, v3
	s_nop 1
	v_addc_co_u32_e64 v69, s[10:11], v69, v70, s[10:11]
	v_cmp_gt_f32_e64 s[10:11], v0, v3
	s_nop 1
	v_cndmask_b32_e64 v70, 0, 1, s[10:11]
	v_cmp_gt_f32_e64 s[10:11], v12, v3
	s_nop 1
	v_addc_co_u32_e64 v69, s[10:11], v69, v70, s[10:11]
	v_cmp_gt_f32_e64 s[10:11], v7, v3
	s_nop 1
	v_cndmask_b32_e64 v70, 0, 1, s[10:11]
	v_cmp_gt_f32_e64 s[10:11], v13, v3
	s_nop 1
	v_addc_co_u32_e64 v69, s[10:11], v69, v70, s[10:11]
	v_cmp_gt_f32_e64 s[10:11], v9, v3
	s_nop 1
	v_cndmask_b32_e64 v70, 0, 1, s[10:11]
	v_cmp_gt_f32_e64 s[10:11], v14, v3
	s_nop 1
	v_addc_co_u32_e64 v69, s[10:11], v69, v70, s[10:11]
	v_cmp_gt_f32_e64 s[10:11], v10, v3
	s_nop 1
	v_cndmask_b32_e64 v70, 0, 1, s[10:11]
	v_cmp_gt_f32_e64 s[10:11], v15, v3
	s_nop 1
	v_addc_co_u32_e64 v69, s[10:11], v69, v70, s[10:11]
	v_cmp_gt_f32_e64 s[10:11], v11, v3
	s_nop 1
	v_cndmask_b32_e64 v70, 0, 1, s[10:11]
	v_cmp_gt_f32_e64 s[10:11], v20, v3
	s_nop 1
	v_addc_co_u32_e64 v69, s[10:11], v69, v70, s[10:11]
	v_cmp_gt_f32_e64 s[10:11], v16, v3
	s_nop 1
	v_cndmask_b32_e64 v70, 0, 1, s[10:11]
	v_cmp_gt_f32_e64 s[10:11], v21, v3
	s_nop 1
	v_addc_co_u32_e64 v69, s[10:11], v69, v70, s[10:11]
	v_cmp_gt_f32_e64 s[10:11], v17, v3
	s_nop 1
	v_cndmask_b32_e64 v70, 0, 1, s[10:11]
	v_cmp_gt_f32_e64 s[10:11], v22, v3
	s_nop 1
	v_addc_co_u32_e64 v69, s[10:11], v69, v70, s[10:11]
	v_cmp_gt_f32_e64 s[10:11], v18, v3
	s_nop 1
	v_cndmask_b32_e64 v70, 0, 1, s[10:11]
	v_cmp_gt_f32_e64 s[10:11], v23, v3
	s_nop 1
	v_addc_co_u32_e64 v69, s[10:11], v69, v70, s[10:11]
	v_cmp_gt_f32_e64 s[10:11], v19, v3
	s_nop 1
	v_cndmask_b32_e64 v70, 0, 1, s[10:11]
	v_cmp_gt_f32_e64 s[10:11], v30, v3
	s_nop 1
	v_addc_co_u32_e64 v69, s[10:11], v69, v70, s[10:11]
	v_cmp_gt_f32_e64 s[10:11], v24, v3
	s_nop 1
	v_cndmask_b32_e64 v70, 0, 1, s[10:11]
	v_cmp_gt_f32_e64 s[10:11], v33, v3
	s_nop 1
	v_addc_co_u32_e64 v69, s[10:11], v69, v70, s[10:11]
	v_cmp_gt_f32_e64 s[10:11], v25, v3
	s_nop 1
	v_cndmask_b32_e64 v70, 0, 1, s[10:11]
	v_cmp_gt_f32_e64 s[10:11], v36, v3
	s_nop 1
	v_addc_co_u32_e64 v69, s[10:11], v69, v70, s[10:11]
	v_cmp_gt_f32_e64 s[10:11], v26, v3
	s_nop 1
	v_cndmask_b32_e64 v70, 0, 1, s[10:11]
	v_cmp_gt_f32_e64 s[10:11], v27, v3
	s_nop 1
	v_addc_co_u32_e64 v69, s[10:11], v69, v70, s[10:11]
	v_cmp_lt_u32_e64 s[10:11], 15, v69
	s_or_b64 s[6:7], s[10:11], s[6:7]
	v_cndmask_b32_e64 v69, 4, 0, s[6:7]
	v_cmp_ge_f32_e64 s[6:7], s33, v4
	s_nop 1
	v_cndmask_b32_e64 v70, 0, 1, s[6:7]
	v_cmp_ge_f32_e64 s[6:7], v2, v4
	s_nop 1
	v_cndmask_b32_e64 v71, 0, 1, s[6:7]
	v_cmp_ge_f32_e64 s[6:7], v3, v4
	s_nop 1
	v_addc_co_u32_e64 v70, s[6:7], v70, v71, s[6:7]
	v_cmp_gt_f32_e64 s[6:7], v5, v4
	s_nop 1
	v_cndmask_b32_e64 v71, 0, 1, s[6:7]
	v_cmp_gt_f32_e64 s[6:7], v6, v4
	s_nop 1
	v_addc_co_u32_e64 v70, s[6:7], v70, v71, s[6:7]
	v_cmp_gt_f32_e64 s[6:7], v1, v4
	s_nop 1
	v_cndmask_b32_e64 v71, 0, 1, s[6:7]
	v_cmp_gt_f32_e64 s[6:7], v8, v4
	s_nop 1
	v_addc_co_u32_e64 v70, s[6:7], v70, v71, s[6:7]
	v_cmp_gt_f32_e64 s[6:7], v0, v4
	s_nop 1
	v_cndmask_b32_e64 v71, 0, 1, s[6:7]
	v_cmp_gt_f32_e64 s[6:7], v12, v4
	s_nop 1
	v_addc_co_u32_e64 v70, s[6:7], v70, v71, s[6:7]
	v_cmp_gt_f32_e64 s[6:7], v7, v4
	s_nop 1
	v_cndmask_b32_e64 v71, 0, 1, s[6:7]
	v_cmp_gt_f32_e64 s[6:7], v13, v4
	s_nop 1
	v_addc_co_u32_e64 v70, s[6:7], v70, v71, s[6:7]
	v_cmp_gt_f32_e64 s[6:7], v9, v4
	s_nop 1
	v_cndmask_b32_e64 v71, 0, 1, s[6:7]
	v_cmp_gt_f32_e64 s[6:7], v14, v4
	s_nop 1
	v_addc_co_u32_e64 v70, s[6:7], v70, v71, s[6:7]
	v_cmp_gt_f32_e64 s[6:7], v10, v4
	s_nop 1
	v_cndmask_b32_e64 v71, 0, 1, s[6:7]
	v_cmp_gt_f32_e64 s[6:7], v15, v4
	s_nop 1
	v_addc_co_u32_e64 v70, s[6:7], v70, v71, s[6:7]
	v_cmp_gt_f32_e64 s[6:7], v11, v4
	s_nop 1
	v_cndmask_b32_e64 v71, 0, 1, s[6:7]
	v_cmp_gt_f32_e64 s[6:7], v20, v4
	s_nop 1
	v_addc_co_u32_e64 v70, s[6:7], v70, v71, s[6:7]
	v_cmp_gt_f32_e64 s[6:7], v16, v4
	s_nop 1
	v_cndmask_b32_e64 v71, 0, 1, s[6:7]
	v_cmp_gt_f32_e64 s[6:7], v21, v4
	s_nop 1
	v_addc_co_u32_e64 v70, s[6:7], v70, v71, s[6:7]
	v_cmp_gt_f32_e64 s[6:7], v17, v4
	s_nop 1
	v_cndmask_b32_e64 v71, 0, 1, s[6:7]
	v_cmp_gt_f32_e64 s[6:7], v22, v4
	s_nop 1
	v_addc_co_u32_e64 v70, s[6:7], v70, v71, s[6:7]
	v_cmp_gt_f32_e64 s[6:7], v18, v4
	s_nop 1
	v_cndmask_b32_e64 v71, 0, 1, s[6:7]
	v_cmp_gt_f32_e64 s[6:7], v23, v4
	s_nop 1
	v_addc_co_u32_e64 v70, s[6:7], v70, v71, s[6:7]
	v_cmp_gt_f32_e64 s[6:7], v19, v4
	s_nop 1
	v_cndmask_b32_e64 v71, 0, 1, s[6:7]
	v_cmp_gt_f32_e64 s[6:7], v30, v4
	s_nop 1
	v_addc_co_u32_e64 v70, s[6:7], v70, v71, s[6:7]
	v_cmp_gt_f32_e64 s[6:7], v24, v4
	s_nop 1
	v_cndmask_b32_e64 v71, 0, 1, s[6:7]
	v_cmp_gt_f32_e64 s[6:7], v33, v4
	s_nop 1
	v_addc_co_u32_e64 v70, s[6:7], v70, v71, s[6:7]
	v_cmp_gt_f32_e64 s[6:7], v25, v4
	s_nop 1
	v_cndmask_b32_e64 v71, 0, 1, s[6:7]
	v_cmp_gt_f32_e64 s[6:7], v36, v4
	s_nop 1
	v_addc_co_u32_e64 v70, s[6:7], v70, v71, s[6:7]
	v_cmp_gt_f32_e64 s[6:7], v26, v4
	s_nop 1
	v_cndmask_b32_e64 v71, 0, 1, s[6:7]
	v_cmp_gt_f32_e64 s[6:7], v27, v4
	s_nop 1
	v_addc_co_u32_e64 v70, s[6:7], v70, v71, s[6:7]
	v_cmp_lt_u32_e64 s[6:7], 15, v70
	s_or_b64 s[4:5], s[6:7], s[4:5]
	v_cndmask_b32_e64 v70, 8, 0, s[4:5]
	v_cmp_ge_f32_e64 s[4:5], s33, v5
	v_or3_b32 v68, v68, v69, v70
	s_nop 0
	v_cndmask_b32_e64 v69, 0, 1, s[4:5]
	v_cmp_ge_f32_e64 s[4:5], v2, v5
	s_nop 1
	v_cndmask_b32_e64 v70, 0, 1, s[4:5]
	v_cmp_ge_f32_e64 s[4:5], v3, v5
	s_nop 1
	v_addc_co_u32_e64 v69, s[4:5], v69, v70, s[4:5]
	v_cmp_ge_f32_e64 s[4:5], v4, v5
	s_nop 1
	v_cndmask_b32_e64 v70, 0, 1, s[4:5]
	v_cmp_gt_f32_e64 s[4:5], v6, v5
	s_nop 1
	v_addc_co_u32_e64 v69, s[4:5], v69, v70, s[4:5]
	v_cmp_gt_f32_e64 s[4:5], v1, v5
	s_nop 1
	v_cndmask_b32_e64 v70, 0, 1, s[4:5]
	v_cmp_gt_f32_e64 s[4:5], v8, v5
	s_nop 1
	v_addc_co_u32_e64 v69, s[4:5], v69, v70, s[4:5]
	v_cmp_gt_f32_e64 s[4:5], v0, v5
	s_nop 1
	v_cndmask_b32_e64 v70, 0, 1, s[4:5]
	v_cmp_gt_f32_e64 s[4:5], v12, v5
	s_nop 1
	v_addc_co_u32_e64 v69, s[4:5], v69, v70, s[4:5]
	v_cmp_gt_f32_e64 s[4:5], v7, v5
	s_nop 1
	v_cndmask_b32_e64 v70, 0, 1, s[4:5]
	v_cmp_gt_f32_e64 s[4:5], v13, v5
	s_nop 1
	v_addc_co_u32_e64 v69, s[4:5], v69, v70, s[4:5]
	v_cmp_gt_f32_e64 s[4:5], v9, v5
	s_nop 1
	v_cndmask_b32_e64 v70, 0, 1, s[4:5]
	v_cmp_gt_f32_e64 s[4:5], v14, v5
	s_nop 1
	v_addc_co_u32_e64 v69, s[4:5], v69, v70, s[4:5]
	v_cmp_gt_f32_e64 s[4:5], v10, v5
	s_nop 1
	v_cndmask_b32_e64 v70, 0, 1, s[4:5]
	v_cmp_gt_f32_e64 s[4:5], v15, v5
	s_nop 1
	v_addc_co_u32_e64 v69, s[4:5], v69, v70, s[4:5]
	v_cmp_gt_f32_e64 s[4:5], v11, v5
	s_nop 1
	v_cndmask_b32_e64 v70, 0, 1, s[4:5]
	v_cmp_gt_f32_e64 s[4:5], v20, v5
	s_nop 1
	v_addc_co_u32_e64 v69, s[4:5], v69, v70, s[4:5]
	v_cmp_gt_f32_e64 s[4:5], v16, v5
	s_nop 1
	v_cndmask_b32_e64 v70, 0, 1, s[4:5]
	v_cmp_gt_f32_e64 s[4:5], v21, v5
	s_nop 1
	v_addc_co_u32_e64 v69, s[4:5], v69, v70, s[4:5]
	v_cmp_gt_f32_e64 s[4:5], v17, v5
	s_nop 1
	v_cndmask_b32_e64 v70, 0, 1, s[4:5]
	v_cmp_gt_f32_e64 s[4:5], v22, v5
	s_nop 1
	v_addc_co_u32_e64 v69, s[4:5], v69, v70, s[4:5]
	v_cmp_gt_f32_e64 s[4:5], v18, v5
	s_nop 1
	v_cndmask_b32_e64 v70, 0, 1, s[4:5]
	v_cmp_gt_f32_e64 s[4:5], v23, v5
	s_nop 1
	v_addc_co_u32_e64 v69, s[4:5], v69, v70, s[4:5]
	v_cmp_gt_f32_e64 s[4:5], v19, v5
	s_nop 1
	v_cndmask_b32_e64 v70, 0, 1, s[4:5]
	v_cmp_gt_f32_e64 s[4:5], v30, v5
	s_nop 1
	v_addc_co_u32_e64 v69, s[4:5], v69, v70, s[4:5]
	v_cmp_gt_f32_e64 s[4:5], v24, v5
	s_nop 1
	v_cndmask_b32_e64 v70, 0, 1, s[4:5]
	v_cmp_gt_f32_e64 s[4:5], v33, v5
	s_nop 1
	v_addc_co_u32_e64 v69, s[4:5], v69, v70, s[4:5]
	v_cmp_gt_f32_e64 s[4:5], v25, v5
	s_nop 1
	v_cndmask_b32_e64 v70, 0, 1, s[4:5]
	v_cmp_gt_f32_e64 s[4:5], v36, v5
	s_nop 1
	v_addc_co_u32_e64 v69, s[4:5], v69, v70, s[4:5]
	v_cmp_gt_f32_e64 s[4:5], v26, v5
	s_nop 1
	v_cndmask_b32_e64 v70, 0, 1, s[4:5]
	v_cmp_gt_f32_e64 s[4:5], v27, v5
	s_nop 1
	v_addc_co_u32_e64 v69, s[4:5], v69, v70, s[4:5]
	v_cmp_lt_u32_e64 s[4:5], 15, v69
	s_or_b64 s[2:3], s[4:5], s[2:3]
	v_cndmask_b32_e64 v69, 16, 0, s[2:3]
	v_cmp_ge_f32_e64 s[2:3], s33, v6
	s_nop 1
	v_cndmask_b32_e64 v70, 0, 1, s[2:3]
	v_cmp_ge_f32_e64 s[2:3], v2, v6
	s_nop 1
	v_cndmask_b32_e64 v71, 0, 1, s[2:3]
	v_cmp_ge_f32_e64 s[2:3], v3, v6
	s_nop 1
	v_addc_co_u32_e64 v70, s[2:3], v70, v71, s[2:3]
	v_cmp_ge_f32_e64 s[2:3], v4, v6
	s_nop 1
	v_cndmask_b32_e64 v71, 0, 1, s[2:3]
	v_cmp_ge_f32_e64 s[2:3], v5, v6
	s_nop 1
	v_addc_co_u32_e64 v70, s[2:3], v70, v71, s[2:3]
	v_cmp_gt_f32_e64 s[2:3], v1, v6
	s_nop 1
	v_cndmask_b32_e64 v71, 0, 1, s[2:3]
	v_cmp_gt_f32_e64 s[2:3], v8, v6
	s_nop 1
	v_addc_co_u32_e64 v70, s[2:3], v70, v71, s[2:3]
	v_cmp_gt_f32_e64 s[2:3], v0, v6
	s_nop 1
	v_cndmask_b32_e64 v71, 0, 1, s[2:3]
	v_cmp_gt_f32_e64 s[2:3], v12, v6
	s_nop 1
	v_addc_co_u32_e64 v70, s[2:3], v70, v71, s[2:3]
	v_cmp_gt_f32_e64 s[2:3], v7, v6
	s_nop 1
	v_cndmask_b32_e64 v71, 0, 1, s[2:3]
	v_cmp_gt_f32_e64 s[2:3], v13, v6
	s_nop 1
	v_addc_co_u32_e64 v70, s[2:3], v70, v71, s[2:3]
	v_cmp_gt_f32_e64 s[2:3], v9, v6
	s_nop 1
	v_cndmask_b32_e64 v71, 0, 1, s[2:3]
	v_cmp_gt_f32_e64 s[2:3], v14, v6
	s_nop 1
	v_addc_co_u32_e64 v70, s[2:3], v70, v71, s[2:3]
	v_cmp_gt_f32_e64 s[2:3], v10, v6
	s_nop 1
	v_cndmask_b32_e64 v71, 0, 1, s[2:3]
	v_cmp_gt_f32_e64 s[2:3], v15, v6
	s_nop 1
	v_addc_co_u32_e64 v70, s[2:3], v70, v71, s[2:3]
	v_cmp_gt_f32_e64 s[2:3], v11, v6
	s_nop 1
	v_cndmask_b32_e64 v71, 0, 1, s[2:3]
	v_cmp_gt_f32_e64 s[2:3], v20, v6
	s_nop 1
	v_addc_co_u32_e64 v70, s[2:3], v70, v71, s[2:3]
	v_cmp_gt_f32_e64 s[2:3], v16, v6
	s_nop 1
	v_cndmask_b32_e64 v71, 0, 1, s[2:3]
	v_cmp_gt_f32_e64 s[2:3], v21, v6
	s_nop 1
	v_addc_co_u32_e64 v70, s[2:3], v70, v71, s[2:3]
	v_cmp_gt_f32_e64 s[2:3], v17, v6
	s_nop 1
	v_cndmask_b32_e64 v71, 0, 1, s[2:3]
	v_cmp_gt_f32_e64 s[2:3], v22, v6
	s_nop 1
	v_addc_co_u32_e64 v70, s[2:3], v70, v71, s[2:3]
	v_cmp_gt_f32_e64 s[2:3], v18, v6
	s_nop 1
	v_cndmask_b32_e64 v71, 0, 1, s[2:3]
	v_cmp_gt_f32_e64 s[2:3], v23, v6
	s_nop 1
	v_addc_co_u32_e64 v70, s[2:3], v70, v71, s[2:3]
	v_cmp_gt_f32_e64 s[2:3], v19, v6
	s_nop 1
	v_cndmask_b32_e64 v71, 0, 1, s[2:3]
	v_cmp_gt_f32_e64 s[2:3], v30, v6
	s_nop 1
	v_addc_co_u32_e64 v70, s[2:3], v70, v71, s[2:3]
	v_cmp_gt_f32_e64 s[2:3], v24, v6
	s_nop 1
	v_cndmask_b32_e64 v71, 0, 1, s[2:3]
	v_cmp_gt_f32_e64 s[2:3], v33, v6
	s_nop 1
	v_addc_co_u32_e64 v70, s[2:3], v70, v71, s[2:3]
	v_cmp_gt_f32_e64 s[2:3], v25, v6
	s_nop 1
	v_cndmask_b32_e64 v71, 0, 1, s[2:3]
	v_cmp_gt_f32_e64 s[2:3], v36, v6
	s_nop 1
	v_addc_co_u32_e64 v70, s[2:3], v70, v71, s[2:3]
	v_cmp_gt_f32_e64 s[2:3], v26, v6
	s_nop 1
	v_cndmask_b32_e64 v71, 0, 1, s[2:3]
	v_cmp_gt_f32_e64 s[2:3], v27, v6
	s_nop 1
	v_addc_co_u32_e64 v70, s[2:3], v70, v71, s[2:3]
	v_cmp_lt_u32_e64 s[2:3], 15, v70
	s_or_b64 s[0:1], s[2:3], s[0:1]
	v_cndmask_b32_e64 v70, 32, 0, s[0:1]
	v_cmp_ge_f32_e64 s[0:1], s33, v1
	v_or3_b32 v68, v68, v69, v70
	v_readlane_b32 s2, v253, 61
	v_cndmask_b32_e64 v69, 0, 1, s[0:1]
	v_cmp_ge_f32_e64 s[0:1], v2, v1
	s_nop 1
	v_cndmask_b32_e64 v2, 0, 1, s[0:1]
	v_cmp_ge_f32_e64 s[0:1], v3, v1
	s_nop 1
	v_addc_co_u32_e64 v2, s[0:1], v69, v2, s[0:1]
	v_cmp_ge_f32_e64 s[0:1], v4, v1
	s_nop 1
	v_cndmask_b32_e64 v3, 0, 1, s[0:1]
	v_cmp_ge_f32_e64 s[0:1], v5, v1
	s_nop 1
	v_addc_co_u32_e64 v2, s[0:1], v2, v3, s[0:1]
	v_cmp_ge_f32_e64 s[0:1], v6, v1
	s_nop 1
	v_cndmask_b32_e64 v3, 0, 1, s[0:1]
	v_cmp_gt_f32_e64 s[0:1], v8, v1
	s_nop 1
	v_addc_co_u32_e64 v2, s[0:1], v2, v3, s[0:1]
	v_cmp_gt_f32_e64 s[0:1], v0, v1
	s_nop 1
	v_cndmask_b32_e64 v3, 0, 1, s[0:1]
	v_cmp_gt_f32_e64 s[0:1], v12, v1
	s_nop 1
	v_addc_co_u32_e64 v2, s[0:1], v2, v3, s[0:1]
	v_cmp_gt_f32_e64 s[0:1], v7, v1
	s_nop 1
	v_cndmask_b32_e64 v3, 0, 1, s[0:1]
	v_cmp_gt_f32_e64 s[0:1], v13, v1
	s_nop 1
	v_addc_co_u32_e64 v2, s[0:1], v2, v3, s[0:1]
	v_cmp_gt_f32_e64 s[0:1], v9, v1
	s_nop 1
	v_cndmask_b32_e64 v3, 0, 1, s[0:1]
	v_cmp_gt_f32_e64 s[0:1], v14, v1
	s_nop 1
	v_addc_co_u32_e64 v2, s[0:1], v2, v3, s[0:1]
	v_cmp_gt_f32_e64 s[0:1], v10, v1
	s_nop 1
	v_cndmask_b32_e64 v3, 0, 1, s[0:1]
	v_cmp_gt_f32_e64 s[0:1], v15, v1
	s_nop 1
	v_addc_co_u32_e64 v2, s[0:1], v2, v3, s[0:1]
	v_cmp_gt_f32_e64 s[0:1], v11, v1
	s_nop 1
	v_cndmask_b32_e64 v3, 0, 1, s[0:1]
	v_cmp_gt_f32_e64 s[0:1], v20, v1
	s_nop 1
	v_addc_co_u32_e64 v2, s[0:1], v2, v3, s[0:1]
	v_cmp_gt_f32_e64 s[0:1], v16, v1
	s_nop 1
	v_cndmask_b32_e64 v3, 0, 1, s[0:1]
	v_cmp_gt_f32_e64 s[0:1], v21, v1
	s_nop 1
	v_addc_co_u32_e64 v2, s[0:1], v2, v3, s[0:1]
	v_cmp_gt_f32_e64 s[0:1], v17, v1
	s_nop 1
	v_cndmask_b32_e64 v3, 0, 1, s[0:1]
	v_cmp_gt_f32_e64 s[0:1], v22, v1
	s_nop 1
	v_addc_co_u32_e64 v2, s[0:1], v2, v3, s[0:1]
	v_cmp_gt_f32_e64 s[0:1], v18, v1
	s_nop 1
	v_cndmask_b32_e64 v3, 0, 1, s[0:1]
	v_cmp_gt_f32_e64 s[0:1], v23, v1
	s_nop 1
	v_addc_co_u32_e64 v2, s[0:1], v2, v3, s[0:1]
	v_cmp_gt_f32_e64 s[0:1], v19, v1
	s_nop 1
	v_cndmask_b32_e64 v3, 0, 1, s[0:1]
	v_cmp_gt_f32_e64 s[0:1], v30, v1
	s_nop 1
	v_addc_co_u32_e64 v2, s[0:1], v2, v3, s[0:1]
	v_cmp_gt_f32_e64 s[0:1], v24, v1
	s_nop 1
	v_cndmask_b32_e64 v3, 0, 1, s[0:1]
	v_cmp_gt_f32_e64 s[0:1], v33, v1
	s_nop 1
	v_addc_co_u32_e64 v2, s[0:1], v2, v3, s[0:1]
	v_cmp_gt_f32_e64 s[0:1], v25, v1
	s_nop 1
	v_cndmask_b32_e64 v3, 0, 1, s[0:1]
	v_cmp_gt_f32_e64 s[0:1], v36, v1
	s_nop 1
	v_addc_co_u32_e64 v2, s[0:1], v2, v3, s[0:1]
	v_cmp_gt_f32_e64 s[0:1], v26, v1
	s_nop 1
	v_cndmask_b32_e64 v3, 0, 1, s[0:1]
	v_cmp_gt_f32_e64 s[0:1], v27, v1
	s_nop 1
	v_addc_co_u32_e64 v1, s[0:1], v2, v3, s[0:1]
	v_cmp_lt_u32_e64 s[0:1], 15, v1
	s_or_b64 s[0:1], s[0:1], vcc
	v_cmp_ge_f32_e32 vcc, v0, v27
	v_cndmask_b32_e64 v1, 64, 0, s[0:1]
	v_or3_b32 v1, v68, v1, v67
	v_addc_co_u32_e32 v0, vcc, v42, v43, vcc
	v_cmp_ge_f32_e32 vcc, v7, v27
	v_or3_b32 v1, v66, v1, v65
	v_or3_b32 v1, v64, v1, v63
	v_addc_co_u32_e32 v0, vcc, v0, v41, vcc
	v_cmp_ge_f32_e32 vcc, v9, v27
	v_or3_b32 v1, v62, v1, v61
	v_or3_b32 v1, v60, v1, v59
	v_addc_co_u32_e32 v0, vcc, v0, v40, vcc
	v_cmp_ge_f32_e32 vcc, v10, v27
	v_or3_b32 v1, v58, v1, v57
	v_or3_b32 v1, v56, v1, v55
	v_addc_co_u32_e32 v0, vcc, v0, v39, vcc
	v_cmp_ge_f32_e32 vcc, v11, v27
	v_or3_b32 v1, v54, v1, v53
	v_or3_b32 v1, v52, v1, v51
	v_addc_co_u32_e32 v0, vcc, v0, v38, vcc
	v_cmp_ge_f32_e32 vcc, v16, v27
	v_or3_b32 v1, v50, v1, v49
	v_or3_b32 v1, v48, v1, v47
	v_addc_co_u32_e32 v0, vcc, v0, v37, vcc
	v_cmp_ge_f32_e32 vcc, v17, v27
	v_or3_b32 v1, v46, v1, v45
	s_nop 0
	v_addc_co_u32_e32 v0, vcc, v0, v35, vcc
	v_cmp_ge_f32_e32 vcc, v18, v27
	s_nop 1
	v_addc_co_u32_e32 v0, vcc, v0, v34, vcc
	v_cmp_ge_f32_e32 vcc, v19, v27
	s_nop 1
	v_addc_co_u32_e32 v0, vcc, v0, v32, vcc
	v_cmp_ge_f32_e32 vcc, v24, v27
	s_nop 1
	v_addc_co_u32_e32 v0, vcc, v0, v31, vcc
	v_cmp_ge_f32_e32 vcc, v25, v27
	s_nop 1
	v_addc_co_u32_e32 v0, vcc, v0, v29, vcc
	v_cmp_ge_f32_e32 vcc, v26, v27
	s_nop 1
	v_addc_co_u32_e32 v0, vcc, v0, v28, vcc
	v_cmp_lt_u32_e32 vcc, 15, v0
	s_or_b64 s[0:1], vcc, s[8:9]
	v_cndmask_b32_e64 v0, v188, 0, s[0:1]
	v_readlane_b32 s0, v254, 11
	v_readlane_b32 s1, v254, 12
	s_lshl_b64 s[0:1], s[0:1], 13
	s_add_u32 s0, s2, s0
	v_readlane_b32 s2, v253, 62
	s_addc_u32 s1, s2, s1
	v_or3_b32 v2, v44, v1, v0
	v_lshl_add_u64 v[0:1], v[100:101], 2, s[0:1]
	global_store_dword v[0:1], v2, off
	s_branch .LBB0_941

.LBB0_971:
	v_max_f32_e32 v0, v96, v80
	v_max_f32_e32 v5, v97, v81
	v_max3_f32 v0, v204, v0, v5
	v_max_f32_e32 v5, v98, v82
	v_max_f32_e32 v6, v99, v83
	v_max3_f32 v0, v0, v5, v6
	v_max_f32_e32 v5, v100, v84
	v_max_f32_e32 v6, v101, v85
	v_max3_f32 v0, v0, v5, v6
	v_max_f32_e32 v5, v102, v86
	v_max_f32_e32 v6, v103, v87
	v_max3_f32 v0, v0, v5, v6
	v_max_f32_e32 v5, v104, v88
	v_max_f32_e32 v6, v105, v89
	v_max3_f32 v0, v0, v5, v6
	v_max_f32_e32 v5, v106, v90
	v_max_f32_e32 v6, v107, v91
	v_max3_f32 v0, v0, v5, v6
	v_max_f32_e32 v5, v108, v92
	v_max_f32_e32 v6, v109, v93
	v_max3_f32 v0, v0, v5, v6
	v_max_f32_e32 v5, v110, v94
	v_max_f32_e32 v6, v95, v95
	v_max_f32_e32 v7, v111, v111
	v_max_f32_e32 v6, v7, v6
	v_max3_f32 v0, v0, v5, v6
	v_mov_b32_e32 v5, v0
	s_nop 1
	v_permlane32_swap_b32_e32 v0, v5
	v_max_f32_e32 v5, v5, v5
	v_max_f32_e32 v0, v0, v0
	v_max_f32_e32 v5, v0, v5
	v_add_f32_e32 v0, 0x41000000, v204
	v_cmp_gt_f32_e32 vcc, v5, v0
	s_cbranch_vccz .LBB0_973
	v_sub_f32_e32 v0, v204, v5
	v_exp_f32_e32 v0, v0
	v_mov_b32_e32 v204, v5
	v_mul_f32_e32 v177, v177, v0
	v_pk_mul_f32 v[78:79], v[78:79], v[0:1] op_sel_hi:[1,0]
	v_pk_mul_f32 v[76:77], v[76:77], v[0:1] op_sel_hi:[1,0]
	v_pk_mul_f32 v[74:75], v[74:75], v[0:1] op_sel_hi:[1,0]
	v_pk_mul_f32 v[72:73], v[72:73], v[0:1] op_sel_hi:[1,0]
	v_pk_mul_f32 v[70:71], v[70:71], v[0:1] op_sel_hi:[1,0]
	v_pk_mul_f32 v[68:69], v[68:69], v[0:1] op_sel_hi:[1,0]
	v_pk_mul_f32 v[66:67], v[66:67], v[0:1] op_sel_hi:[1,0]
	v_pk_mul_f32 v[64:65], v[64:65], v[0:1] op_sel_hi:[1,0]
	v_pk_mul_f32 v[62:63], v[62:63], v[0:1] op_sel_hi:[1,0]
	v_pk_mul_f32 v[60:61], v[60:61], v[0:1] op_sel_hi:[1,0]
	v_pk_mul_f32 v[58:59], v[58:59], v[0:1] op_sel_hi:[1,0]
	v_pk_mul_f32 v[56:57], v[56:57], v[0:1] op_sel_hi:[1,0]
	v_pk_mul_f32 v[54:55], v[54:55], v[0:1] op_sel_hi:[1,0]
	v_pk_mul_f32 v[52:53], v[52:53], v[0:1] op_sel_hi:[1,0]
	v_pk_mul_f32 v[50:51], v[50:51], v[0:1] op_sel_hi:[1,0]
	v_pk_mul_f32 v[48:49], v[48:49], v[0:1] op_sel_hi:[1,0]
	v_pk_mul_f32 v[46:47], v[46:47], v[0:1] op_sel_hi:[1,0]
	v_pk_mul_f32 v[44:45], v[44:45], v[0:1] op_sel_hi:[1,0]
	v_pk_mul_f32 v[42:43], v[42:43], v[0:1] op_sel_hi:[1,0]
	v_pk_mul_f32 v[40:41], v[40:41], v[0:1] op_sel_hi:[1,0]
	v_pk_mul_f32 v[38:39], v[38:39], v[0:1] op_sel_hi:[1,0]
	v_pk_mul_f32 v[36:37], v[36:37], v[0:1] op_sel_hi:[1,0]
	v_pk_mul_f32 v[34:35], v[34:35], v[0:1] op_sel_hi:[1,0]
	v_pk_mul_f32 v[32:33], v[32:33], v[0:1] op_sel_hi:[1,0]
	v_pk_mul_f32 v[30:31], v[30:31], v[0:1] op_sel_hi:[1,0]
	v_pk_mul_f32 v[28:29], v[28:29], v[0:1] op_sel_hi:[1,0]
	v_pk_mul_f32 v[26:27], v[26:27], v[0:1] op_sel_hi:[1,0]
	v_pk_mul_f32 v[24:25], v[24:25], v[0:1] op_sel_hi:[1,0]
	v_pk_mul_f32 v[22:23], v[22:23], v[0:1] op_sel_hi:[1,0]
	v_pk_mul_f32 v[20:21], v[20:21], v[0:1] op_sel_hi:[1,0]
	v_pk_mul_f32 v[18:19], v[18:19], v[0:1] op_sel_hi:[1,0]
	v_pk_mul_f32 v[16:17], v[16:17], v[0:1] op_sel_hi:[1,0]
	s_branch .LBB0_974

.LBB0_981:
	v_max_f32_e32 v0, v96, v80
	v_max_f32_e32 v3, v97, v81
	v_max3_f32 v0, v204, v0, v3
	v_max_f32_e32 v3, v98, v82
	v_max_f32_e32 v4, v99, v83
	v_max3_f32 v0, v0, v3, v4
	v_max_f32_e32 v3, v100, v84
	v_max_f32_e32 v4, v101, v85
	v_max3_f32 v0, v0, v3, v4
	v_max_f32_e32 v3, v102, v86
	v_max_f32_e32 v4, v103, v87
	v_max3_f32 v0, v0, v3, v4
	v_max_f32_e32 v3, v104, v88
	v_max_f32_e32 v4, v105, v89
	v_max3_f32 v0, v0, v3, v4
	v_max_f32_e32 v3, v106, v90
	v_max_f32_e32 v4, v107, v91
	v_max3_f32 v0, v0, v3, v4
	v_max_f32_e32 v3, v108, v92
	v_max_f32_e32 v4, v109, v93
	v_max3_f32 v0, v0, v3, v4
	v_max_f32_e32 v3, v110, v94
	v_max_f32_e32 v4, v95, v95
	v_max_f32_e32 v5, v111, v111
	v_max_f32_e32 v4, v5, v4
	v_max3_f32 v0, v0, v3, v4
	v_mov_b32_e32 v3, v0
	s_nop 1
	v_permlane32_swap_b32_e32 v0, v3
	v_max_f32_e32 v3, v3, v3
	v_max_f32_e32 v0, v0, v0
	v_max_f32_e32 v3, v0, v3
	v_add_f32_e32 v0, 0x41000000, v204
	v_cmp_gt_f32_e32 vcc, v3, v0
	s_cbranch_vccz .LBB0_983
	v_sub_f32_e32 v0, v204, v3
	v_exp_f32_e32 v0, v0
	v_mov_b32_e32 v204, v3
	v_mul_f32_e32 v177, v177, v0
	v_pk_mul_f32 v[78:79], v[78:79], v[0:1] op_sel_hi:[1,0]
	v_pk_mul_f32 v[76:77], v[76:77], v[0:1] op_sel_hi:[1,0]
	v_pk_mul_f32 v[74:75], v[74:75], v[0:1] op_sel_hi:[1,0]
	v_pk_mul_f32 v[72:73], v[72:73], v[0:1] op_sel_hi:[1,0]
	v_pk_mul_f32 v[70:71], v[70:71], v[0:1] op_sel_hi:[1,0]
	v_pk_mul_f32 v[68:69], v[68:69], v[0:1] op_sel_hi:[1,0]
	v_pk_mul_f32 v[66:67], v[66:67], v[0:1] op_sel_hi:[1,0]
	v_pk_mul_f32 v[64:65], v[64:65], v[0:1] op_sel_hi:[1,0]
	v_pk_mul_f32 v[62:63], v[62:63], v[0:1] op_sel_hi:[1,0]
	v_pk_mul_f32 v[60:61], v[60:61], v[0:1] op_sel_hi:[1,0]
	v_pk_mul_f32 v[58:59], v[58:59], v[0:1] op_sel_hi:[1,0]
	v_pk_mul_f32 v[56:57], v[56:57], v[0:1] op_sel_hi:[1,0]
	v_pk_mul_f32 v[54:55], v[54:55], v[0:1] op_sel_hi:[1,0]
	v_pk_mul_f32 v[52:53], v[52:53], v[0:1] op_sel_hi:[1,0]
	v_pk_mul_f32 v[50:51], v[50:51], v[0:1] op_sel_hi:[1,0]
	v_pk_mul_f32 v[48:49], v[48:49], v[0:1] op_sel_hi:[1,0]
	v_pk_mul_f32 v[46:47], v[46:47], v[0:1] op_sel_hi:[1,0]
	v_pk_mul_f32 v[44:45], v[44:45], v[0:1] op_sel_hi:[1,0]
	v_pk_mul_f32 v[42:43], v[42:43], v[0:1] op_sel_hi:[1,0]
	v_pk_mul_f32 v[40:41], v[40:41], v[0:1] op_sel_hi:[1,0]
	v_pk_mul_f32 v[38:39], v[38:39], v[0:1] op_sel_hi:[1,0]
	v_pk_mul_f32 v[36:37], v[36:37], v[0:1] op_sel_hi:[1,0]
	v_pk_mul_f32 v[34:35], v[34:35], v[0:1] op_sel_hi:[1,0]
	v_pk_mul_f32 v[32:33], v[32:33], v[0:1] op_sel_hi:[1,0]
	v_pk_mul_f32 v[30:31], v[30:31], v[0:1] op_sel_hi:[1,0]
	v_pk_mul_f32 v[28:29], v[28:29], v[0:1] op_sel_hi:[1,0]
	v_pk_mul_f32 v[26:27], v[26:27], v[0:1] op_sel_hi:[1,0]
	v_pk_mul_f32 v[24:25], v[24:25], v[0:1] op_sel_hi:[1,0]
	v_pk_mul_f32 v[22:23], v[22:23], v[0:1] op_sel_hi:[1,0]
	v_pk_mul_f32 v[20:21], v[20:21], v[0:1] op_sel_hi:[1,0]
	v_pk_mul_f32 v[18:19], v[18:19], v[0:1] op_sel_hi:[1,0]
	v_pk_mul_f32 v[16:17], v[16:17], v[0:1] op_sel_hi:[1,0]
	s_branch .LBB0_984
